# A1: gd solve readlane chain software-pipelined over 4 SGPRs, hazard nops dropped (bit-identical)
# baseline (speedup 1.0000x reference)
; __device__ __forceinline__ void gd_prep_item(CArgs* a, LAS unsigned char* lds, int l, int item) {
;     ...
;         float nrow[64];
; #pragma unroll
;         for (int t = 1; t < 64; ++t) nrow[t] = NM[t * 64 + lane];
; #pragma unroll
;         for (int t = 1; t < 64; ++t) { float s0 = 0.f, s1 = 0.f;
; #pragma unroll
;             for (int sI = 0; sI < t; ++sI) { const float cf = __builtin_bit_cast(float, __builtin_amdgcn_readlane(__builtin_bit_cast(int, nrow[t]), sI)); if (sI & 1) s1 += cf * x[sI]; else s0 += cf * x[sI]; }
;             x[t] -= s0 + s1; }
.LBB0_989:
	s_or_b64 exec, exec, s[10:11]
	v_lshl_add_u32 v124, v44, 2, v116
	ds_read2st64_b32 v[126:127], v124 offset0:1 offset1:2
	ds_read2st64_b32 v[128:129], v124 offset0:3 offset1:4
	ds_read2st64_b32 v[130:131], v124 offset0:5 offset1:6
	ds_read2st64_b32 v[132:133], v124 offset0:7 offset1:8
	ds_read2st64_b32 v[134:135], v124 offset0:9 offset1:10
	ds_read2st64_b32 v[118:119], v124 offset0:11 offset1:12
	ds_read2st64_b32 v[116:117], v124 offset0:13 offset1:14
	ds_read2st64_b32 v[114:115], v124 offset0:15 offset1:16
	ds_read2st64_b32 v[112:113], v124 offset0:17 offset1:18
	ds_read2st64_b32 v[110:111], v124 offset0:19 offset1:20
	ds_read2st64_b32 v[108:109], v124 offset0:21 offset1:22
	ds_read2st64_b32 v[106:107], v124 offset0:23 offset1:24
	ds_read2st64_b32 v[104:105], v124 offset0:25 offset1:26
	ds_read2st64_b32 v[102:103], v124 offset0:27 offset1:28
	ds_read2st64_b32 v[100:101], v124 offset0:29 offset1:30
	ds_read2st64_b32 v[98:99], v124 offset0:31 offset1:32
	ds_read2st64_b32 v[96:97], v124 offset0:33 offset1:34
	ds_read2st64_b32 v[94:95], v124 offset0:35 offset1:36
	ds_read2st64_b32 v[92:93], v124 offset0:37 offset1:38
	ds_read2st64_b32 v[90:91], v124 offset0:39 offset1:40
	ds_read2st64_b32 v[88:89], v124 offset0:41 offset1:42
	ds_read2st64_b32 v[86:87], v124 offset0:43 offset1:44
	ds_read2st64_b32 v[84:85], v124 offset0:45 offset1:46
	ds_read2st64_b32 v[82:83], v124 offset0:47 offset1:48
	ds_read2st64_b32 v[68:69], v124 offset0:49 offset1:50
	ds_read2st64_b32 v[58:59], v124 offset0:51 offset1:52
	ds_read2st64_b32 v[50:51], v124 offset0:53 offset1:54
	ds_read2st64_b32 v[44:45], v124 offset0:55 offset1:56
	ds_read2st64_b32 v[38:39], v124 offset0:57 offset1:58
	ds_read2st64_b32 v[32:33], v124 offset0:59 offset1:60
	s_waitcnt lgkmcnt(14)
	ds_read2st64_b32 v[28:29], v124 offset0:61 offset1:62
	ds_read_b32 v125, v124 offset:16128
	v_readlane_b32 s10, v126, 0
	v_readlane_b32 s11, v127, 0
	v_readlane_b32 s100, v127, 1
	v_readlane_b32 s101, v128, 0
	v_fma_f32 v124, v5, s10, 0
	v_readlane_b32 s10, v128, 1
	v_sub_f32_e32 v4, v4, v124
	v_fma_f32 v124, v5, s11, 0
	v_readlane_b32 s11, v128, 2
	v_fma_f32 v126, v4, s100, 0
	v_readlane_b32 s100, v129, 0
	v_add_f32_e32 v124, v124, v126
	v_sub_f32_e32 v124, v70, v124
	v_fma_f32 v70, v5, s101, 0
	v_readlane_b32 s101, v129, 1
	v_fma_f32 v126, v4, s10, 0
	v_readlane_b32 s10, v129, 2
	v_fmac_f32_e32 v70, s11, v124
	v_readlane_b32 s11, v129, 3
	v_add_f32_e32 v70, v126, v70
	v_sub_f32_e32 v71, v71, v70
	v_fma_f32 v70, v5, s100, 0
	v_readlane_b32 s100, v130, 0
	v_fma_f32 v126, v4, s101, 0
	v_readlane_b32 s101, v130, 1
	v_fmac_f32_e32 v70, s10, v124
	v_readlane_b32 s10, v130, 2
	v_fmac_f32_e32 v126, s11, v71
	v_readlane_b32 s11, v130, 3
	v_add_f32_e32 v70, v70, v126
	v_sub_f32_e32 v70, v74, v70
	v_fma_f32 v74, v5, s100, 0
	v_readlane_b32 s100, v130, 4
	v_fma_f32 v126, v4, s101, 0
	v_readlane_b32 s101, v131, 0
	v_fmac_f32_e32 v74, s10, v124
	v_readlane_b32 s10, v131, 1
	v_fmac_f32_e32 v126, s11, v71
	v_readlane_b32 s11, v131, 2
	v_fmac_f32_e32 v74, s100, v70
	v_readlane_b32 s100, v131, 3
	v_add_f32_e32 v74, v126, v74
	v_sub_f32_e32 v74, v75, v74
	v_fma_f32 v75, v5, s101, 0
	v_readlane_b32 s101, v131, 4
	v_fma_f32 v126, v4, s10, 0
	v_readlane_b32 s10, v131, 5
	v_fmac_f32_e32 v75, s11, v124
	v_readlane_b32 s11, v132, 0
	v_fmac_f32_e32 v126, s100, v71
	v_readlane_b32 s100, v132, 1
	v_fmac_f32_e32 v75, s101, v70
	v_readlane_b32 s101, v132, 2
	v_fmac_f32_e32 v126, s10, v74
	v_readlane_b32 s10, v132, 3
	v_add_f32_e32 v75, v75, v126
	v_sub_f32_e32 v75, v80, v75
	v_fma_f32 v80, v5, s11, 0
	v_readlane_b32 s11, v132, 4
	v_fma_f32 v126, v4, s100, 0
	v_readlane_b32 s100, v132, 5
	v_fmac_f32_e32 v80, s101, v124
	v_readlane_b32 s101, v132, 6
	v_fmac_f32_e32 v126, s10, v71
	v_readlane_b32 s10, v133, 0
	v_fmac_f32_e32 v80, s11, v70
	v_readlane_b32 s11, v133, 1
	v_fmac_f32_e32 v126, s100, v74
	v_readlane_b32 s100, v133, 2
	v_fmac_f32_e32 v80, s101, v75
	v_readlane_b32 s101, v133, 3
	v_add_f32_e32 v80, v126, v80
	v_sub_f32_e32 v80, v81, v80
	v_fma_f32 v81, v5, s10, 0
	v_readlane_b32 s10, v133, 4
	v_fma_f32 v126, v4, s11, 0
	v_readlane_b32 s11, v133, 5
	v_fmac_f32_e32 v81, s100, v124
	v_readlane_b32 s100, v133, 6
	v_fmac_f32_e32 v126, s101, v71
	v_readlane_b32 s101, v133, 7
	v_fmac_f32_e32 v81, s10, v70
	v_readlane_b32 s10, v134, 0
	v_fmac_f32_e32 v126, s11, v74
	v_readlane_b32 s11, v134, 1
	v_fmac_f32_e32 v81, s100, v75
	v_readlane_b32 s100, v134, 2
	v_fmac_f32_e32 v126, s101, v80
	v_readlane_b32 s101, v134, 3
	v_add_f32_e32 v81, v81, v126
	v_sub_f32_e32 v78, v78, v81
	v_fma_f32 v81, v5, s10, 0
	v_readlane_b32 s10, v134, 4
	v_fma_f32 v126, v4, s11, 0
	v_readlane_b32 s11, v134, 5
	v_fmac_f32_e32 v81, s100, v124
	v_readlane_b32 s100, v134, 6
	v_fmac_f32_e32 v126, s101, v71
	v_readlane_b32 s101, v134, 7
	v_fmac_f32_e32 v81, s10, v70
	v_readlane_b32 s10, v134, 8
	v_fmac_f32_e32 v126, s11, v74
	v_readlane_b32 s11, v135, 0
	v_fmac_f32_e32 v81, s100, v75
	v_readlane_b32 s100, v135, 1
	v_fmac_f32_e32 v126, s101, v80
	v_readlane_b32 s101, v135, 2
	v_fmac_f32_e32 v81, s10, v78
	v_readlane_b32 s10, v135, 3
	v_add_f32_e32 v81, v126, v81
	v_sub_f32_e32 v79, v79, v81
	v_fma_f32 v81, v5, s11, 0
	v_readlane_b32 s11, v135, 4
	v_fma_f32 v126, v4, s100, 0
	v_readlane_b32 s100, v135, 5
	v_fmac_f32_e32 v81, s101, v124
	v_readlane_b32 s101, v135, 6
	v_fmac_f32_e32 v126, s10, v71
	v_readlane_b32 s10, v135, 7
	v_fmac_f32_e32 v81, s11, v70
	v_readlane_b32 s11, v135, 8
	v_fmac_f32_e32 v126, s100, v74
	v_readlane_b32 s100, v135, 9
	v_fmac_f32_e32 v81, s101, v75
	v_readlane_b32 s101, v118, 0
	v_fmac_f32_e32 v126, s10, v80
	v_readlane_b32 s10, v118, 1
; __device__ __forceinline__ void gd_prep_item(CArgs* a, LAS unsigned char* lds, int l, int item) {
;     ...
;         for (int t = 1; t < 64; ++t) { float s0 = 0.f, s1 = 0.f;
; #pragma unroll
;             for (int sI = 0; sI < t; ++sI) { const float cf = __builtin_bit_cast(float, __builtin_amdgcn_readlane(__builtin_bit_cast(int, nrow[t]), sI)); if (sI & 1) s1 += cf * x[sI]; else s0 += cf * x[sI]; }
;             x[t] -= s0 + s1; }
	v_fmac_f32_e32 v81, s11, v78
	v_readlane_b32 s11, v118, 2
	v_fmac_f32_e32 v126, s100, v79
	v_readlane_b32 s100, v118, 3
	v_add_f32_e32 v81, v81, v126
	v_sub_f32_e32 v76, v76, v81
	v_fma_f32 v81, v5, s101, 0
	v_readlane_b32 s101, v118, 4
	v_fma_f32 v126, v4, s10, 0
	v_readlane_b32 s10, v118, 5
	v_fmac_f32_e32 v81, s11, v124
	v_readlane_b32 s11, v118, 6
	v_fmac_f32_e32 v126, s100, v71
	v_readlane_b32 s100, v118, 7
	v_fmac_f32_e32 v81, s101, v70
	v_readlane_b32 s101, v118, 8
	v_fmac_f32_e32 v126, s10, v74
	v_readlane_b32 s10, v118, 9
	v_fmac_f32_e32 v81, s11, v75
	v_readlane_b32 s11, v118, 10
	v_fmac_f32_e32 v126, s100, v80
	v_readlane_b32 s100, v119, 0
	v_fmac_f32_e32 v81, s101, v78
	v_readlane_b32 s101, v119, 1
	v_fmac_f32_e32 v126, s10, v79
	v_readlane_b32 s10, v119, 2
	v_fmac_f32_e32 v81, s11, v76
	v_readlane_b32 s11, v119, 3
	v_add_f32_e32 v81, v126, v81
	v_sub_f32_e32 v77, v77, v81
	v_fma_f32 v81, v5, s100, 0
	v_readlane_b32 s100, v119, 4
	v_fma_f32 v118, v4, s101, 0
	v_readlane_b32 s101, v119, 5
	v_fmac_f32_e32 v81, s10, v124
	v_readlane_b32 s10, v119, 6
	v_fmac_f32_e32 v118, s11, v71
	v_readlane_b32 s11, v119, 7
	v_fmac_f32_e32 v81, s100, v70
	v_readlane_b32 s100, v119, 8
	v_fmac_f32_e32 v118, s101, v74
	v_readlane_b32 s101, v119, 9
	v_fmac_f32_e32 v81, s10, v75
	v_readlane_b32 s10, v119, 10
	v_fmac_f32_e32 v118, s11, v80
	v_readlane_b32 s11, v119, 11
	v_fmac_f32_e32 v81, s100, v78
	v_readlane_b32 s100, v116, 0
	v_fmac_f32_e32 v118, s101, v79
	v_readlane_b32 s101, v116, 1
	v_fmac_f32_e32 v81, s10, v76
	v_readlane_b32 s10, v116, 2
	v_fmac_f32_e32 v118, s11, v77
	v_readlane_b32 s11, v116, 3
	v_add_f32_e32 v81, v81, v118
	v_sub_f32_e32 v72, v72, v81
	v_fma_f32 v81, v5, s100, 0
	v_readlane_b32 s100, v116, 4
	v_fma_f32 v118, v4, s101, 0
	v_readlane_b32 s101, v116, 5
	v_fmac_f32_e32 v81, s10, v124
	v_readlane_b32 s10, v116, 6
	v_fmac_f32_e32 v118, s11, v71
	v_readlane_b32 s11, v116, 7
	v_fmac_f32_e32 v81, s100, v70
	v_readlane_b32 s100, v116, 8
	v_fmac_f32_e32 v118, s101, v74
	v_readlane_b32 s101, v116, 9
	v_fmac_f32_e32 v81, s10, v75
	v_readlane_b32 s10, v116, 10
	v_fmac_f32_e32 v118, s11, v80
	v_readlane_b32 s11, v116, 11
	v_fmac_f32_e32 v81, s100, v78
	v_readlane_b32 s100, v116, 12
	v_fmac_f32_e32 v118, s101, v79
	v_readlane_b32 s101, v117, 0
	v_fmac_f32_e32 v81, s10, v76
	v_readlane_b32 s10, v117, 1
	v_fmac_f32_e32 v118, s11, v77
	v_readlane_b32 s11, v117, 2
	v_fmac_f32_e32 v81, s100, v72
	v_readlane_b32 s100, v117, 3
	v_add_f32_e32 v81, v118, v81
	v_sub_f32_e32 v73, v73, v81
	v_fma_f32 v81, v5, s101, 0
	v_readlane_b32 s101, v117, 4
	v_fma_f32 v116, v4, s10, 0
	v_readlane_b32 s10, v117, 5
	v_fmac_f32_e32 v81, s11, v124
	v_readlane_b32 s11, v117, 6
	v_fmac_f32_e32 v116, s100, v71
	v_readlane_b32 s100, v117, 7
	v_fmac_f32_e32 v81, s101, v70
	v_readlane_b32 s101, v117, 8
	v_fmac_f32_e32 v116, s10, v74
	v_readlane_b32 s10, v117, 9
	v_fmac_f32_e32 v81, s11, v75
	v_readlane_b32 s11, v117, 10
	v_fmac_f32_e32 v116, s100, v80
	v_readlane_b32 s100, v117, 11
	v_fmac_f32_e32 v81, s101, v78
	v_readlane_b32 s101, v117, 12
	v_fmac_f32_e32 v116, s10, v79
	v_readlane_b32 s10, v117, 13
	v_fmac_f32_e32 v81, s11, v76
	v_readlane_b32 s11, v114, 0
	v_fmac_f32_e32 v116, s100, v77
	v_readlane_b32 s100, v114, 1
	v_fmac_f32_e32 v81, s101, v72
	v_readlane_b32 s101, v114, 2
	v_fmac_f32_e32 v116, s10, v73
	v_readlane_b32 s10, v114, 3
	v_add_f32_e32 v81, v81, v116
	v_sub_f32_e32 v66, v66, v81
	v_fma_f32 v81, v5, s11, 0
	v_readlane_b32 s11, v114, 4
	v_fma_f32 v116, v4, s100, 0
	v_readlane_b32 s100, v114, 5
	v_fmac_f32_e32 v81, s101, v124
	v_readlane_b32 s101, v114, 6
	v_fmac_f32_e32 v116, s10, v71
	v_readlane_b32 s10, v114, 7
	v_fmac_f32_e32 v81, s11, v70
	v_readlane_b32 s11, v114, 8
	v_fmac_f32_e32 v116, s100, v74
	v_readlane_b32 s100, v114, 9
	v_fmac_f32_e32 v81, s101, v75
	v_readlane_b32 s101, v114, 10
	v_fmac_f32_e32 v116, s10, v80
	v_readlane_b32 s10, v114, 11
	v_fmac_f32_e32 v81, s11, v78
	v_readlane_b32 s11, v114, 12
	v_fmac_f32_e32 v116, s100, v79
	v_readlane_b32 s100, v114, 13
	v_fmac_f32_e32 v81, s101, v76
	v_readlane_b32 s101, v114, 14
	v_fmac_f32_e32 v116, s10, v77
	v_readlane_b32 s10, v115, 0
	v_fmac_f32_e32 v81, s11, v72
	v_readlane_b32 s11, v115, 1
	v_fmac_f32_e32 v116, s100, v73
	v_readlane_b32 s100, v115, 2
	v_fmac_f32_e32 v81, s101, v66
	v_readlane_b32 s101, v115, 3
	v_add_f32_e32 v81, v116, v81
	v_sub_f32_e32 v67, v67, v81
	v_fma_f32 v81, v5, s10, 0
	v_readlane_b32 s10, v115, 4
	v_fma_f32 v114, v4, s11, 0
	v_readlane_b32 s11, v115, 5
	v_fmac_f32_e32 v81, s100, v124
	v_readlane_b32 s100, v115, 6
	v_fmac_f32_e32 v114, s101, v71
	v_readlane_b32 s101, v115, 7
	v_fmac_f32_e32 v81, s10, v70
	v_readlane_b32 s10, v115, 8
	v_fmac_f32_e32 v114, s11, v74
	v_readlane_b32 s11, v115, 9
	v_fmac_f32_e32 v81, s100, v75
	v_readlane_b32 s100, v115, 10
	v_fmac_f32_e32 v114, s101, v80
	v_readlane_b32 s101, v115, 11
	v_fmac_f32_e32 v81, s10, v78
	v_readlane_b32 s10, v115, 12
	v_fmac_f32_e32 v114, s11, v79
	v_readlane_b32 s11, v115, 13
	v_fmac_f32_e32 v81, s100, v76
	v_readlane_b32 s100, v115, 14
	v_fmac_f32_e32 v114, s101, v77
	v_readlane_b32 s101, v115, 15
	v_fmac_f32_e32 v81, s10, v72
	v_readlane_b32 s10, v112, 0
	v_fmac_f32_e32 v114, s11, v73
	v_readlane_b32 s11, v112, 1
	v_fmac_f32_e32 v81, s100, v66
	v_readlane_b32 s100, v112, 2
	v_fmac_f32_e32 v114, s101, v67
	v_readlane_b32 s101, v112, 3
	v_add_f32_e32 v81, v81, v114
	v_sub_f32_e32 v64, v64, v81
	v_fma_f32 v81, v5, s10, 0
	v_readlane_b32 s10, v112, 4
	v_fma_f32 v114, v4, s11, 0
	v_readlane_b32 s11, v112, 5
	v_fmac_f32_e32 v81, s100, v124
	v_readlane_b32 s100, v112, 6
	v_fmac_f32_e32 v114, s101, v71
; __device__ __forceinline__ void gd_prep_item(CArgs* a, LAS unsigned char* lds, int l, int item) {
;     ...
;         for (int t = 1; t < 64; ++t) { float s0 = 0.f, s1 = 0.f;
; #pragma unroll
;             for (int sI = 0; sI < t; ++sI) { const float cf = __builtin_bit_cast(float, __builtin_amdgcn_readlane(__builtin_bit_cast(int, nrow[t]), sI)); if (sI & 1) s1 += cf * x[sI]; else s0 += cf * x[sI]; }
;             x[t] -= s0 + s1; }
	v_readlane_b32 s101, v112, 7
	v_fmac_f32_e32 v81, s10, v70
	v_readlane_b32 s10, v112, 8
	v_fmac_f32_e32 v114, s11, v74
	v_readlane_b32 s11, v112, 9
	v_fmac_f32_e32 v81, s100, v75
	v_readlane_b32 s100, v112, 10
	v_fmac_f32_e32 v114, s101, v80
	v_readlane_b32 s101, v112, 11
	v_fmac_f32_e32 v81, s10, v78
	v_readlane_b32 s10, v112, 12
	v_fmac_f32_e32 v114, s11, v79
	v_readlane_b32 s11, v112, 13
	v_fmac_f32_e32 v81, s100, v76
	v_readlane_b32 s100, v112, 14
	v_fmac_f32_e32 v114, s101, v77
	v_readlane_b32 s101, v112, 15
	v_fmac_f32_e32 v81, s10, v72
	v_readlane_b32 s10, v112, 16
	v_fmac_f32_e32 v114, s11, v73
	v_readlane_b32 s11, v113, 0
	v_fmac_f32_e32 v81, s100, v66
	v_readlane_b32 s100, v113, 1
	v_fmac_f32_e32 v114, s101, v67
	v_readlane_b32 s101, v113, 2
	v_fmac_f32_e32 v81, s10, v64
	v_readlane_b32 s10, v113, 3
	v_add_f32_e32 v81, v114, v81
	v_sub_f32_e32 v65, v65, v81
	v_fma_f32 v81, v5, s11, 0
	v_readlane_b32 s11, v113, 4
	v_fma_f32 v112, v4, s100, 0
	v_readlane_b32 s100, v113, 5
	v_fmac_f32_e32 v81, s101, v124
	v_readlane_b32 s101, v113, 6
	v_fmac_f32_e32 v112, s10, v71
	v_readlane_b32 s10, v113, 7
	v_fmac_f32_e32 v81, s11, v70
	v_readlane_b32 s11, v113, 8
	v_fmac_f32_e32 v112, s100, v74
	v_readlane_b32 s100, v113, 9
	v_fmac_f32_e32 v81, s101, v75
	v_readlane_b32 s101, v113, 10
	v_fmac_f32_e32 v112, s10, v80
	v_readlane_b32 s10, v113, 11
	v_fmac_f32_e32 v81, s11, v78
	v_readlane_b32 s11, v113, 12
	v_fmac_f32_e32 v112, s100, v79
	v_readlane_b32 s100, v113, 13
	v_fmac_f32_e32 v81, s101, v76
	v_readlane_b32 s101, v113, 14
	v_fmac_f32_e32 v112, s10, v77
	v_readlane_b32 s10, v113, 15
	v_fmac_f32_e32 v81, s11, v72
	v_readlane_b32 s11, v113, 16
	v_fmac_f32_e32 v112, s100, v73
	v_readlane_b32 s100, v113, 17
	v_fmac_f32_e32 v81, s101, v66
	v_readlane_b32 s101, v110, 0
	v_fmac_f32_e32 v112, s10, v67
	v_readlane_b32 s10, v110, 1
	v_fmac_f32_e32 v81, s11, v64
	v_readlane_b32 s11, v110, 2
	v_fmac_f32_e32 v112, s100, v65
	v_readlane_b32 s100, v110, 3
	v_add_f32_e32 v81, v81, v112
	v_sub_f32_e32 v62, v62, v81
	v_fma_f32 v81, v5, s101, 0
	v_readlane_b32 s101, v110, 4
	v_fma_f32 v112, v4, s10, 0
	v_readlane_b32 s10, v110, 5
	v_fmac_f32_e32 v81, s11, v124
	v_readlane_b32 s11, v110, 6
	v_fmac_f32_e32 v112, s100, v71
	v_readlane_b32 s100, v110, 7
	v_fmac_f32_e32 v81, s101, v70
	v_readlane_b32 s101, v110, 8
	v_fmac_f32_e32 v112, s10, v74
	v_readlane_b32 s10, v110, 9
	v_fmac_f32_e32 v81, s11, v75
	v_readlane_b32 s11, v110, 10
	v_fmac_f32_e32 v112, s100, v80
	v_readlane_b32 s100, v110, 11
	v_fmac_f32_e32 v81, s101, v78
	v_readlane_b32 s101, v110, 12
	v_fmac_f32_e32 v112, s10, v79
	v_readlane_b32 s10, v110, 13
	v_fmac_f32_e32 v81, s11, v76
	v_readlane_b32 s11, v110, 14
	v_fmac_f32_e32 v112, s100, v77
	v_readlane_b32 s100, v110, 15
	v_fmac_f32_e32 v81, s101, v72
	v_readlane_b32 s101, v110, 16
	v_fmac_f32_e32 v112, s10, v73
	v_readlane_b32 s10, v110, 17
	v_fmac_f32_e32 v81, s11, v66
	v_readlane_b32 s11, v110, 18
	v_fmac_f32_e32 v112, s100, v67
	v_readlane_b32 s100, v111, 0
	v_fmac_f32_e32 v81, s101, v64
	v_readlane_b32 s101, v111, 1
	v_fmac_f32_e32 v112, s10, v65
	v_readlane_b32 s10, v111, 2
	v_fmac_f32_e32 v81, s11, v62
	v_readlane_b32 s11, v111, 3
	v_add_f32_e32 v81, v112, v81
	v_sub_f32_e32 v63, v63, v81
	v_fma_f32 v81, v5, s100, 0
	v_readlane_b32 s100, v111, 4
	v_fma_f32 v110, v4, s101, 0
	v_readlane_b32 s101, v111, 5
	v_fmac_f32_e32 v81, s10, v124
	v_readlane_b32 s10, v111, 6
	v_fmac_f32_e32 v110, s11, v71
	v_readlane_b32 s11, v111, 7
	v_fmac_f32_e32 v81, s100, v70
	v_readlane_b32 s100, v111, 8
	v_fmac_f32_e32 v110, s101, v74
	v_readlane_b32 s101, v111, 9
	v_fmac_f32_e32 v81, s10, v75
	v_readlane_b32 s10, v111, 10
	v_fmac_f32_e32 v110, s11, v80
	v_readlane_b32 s11, v111, 11
	v_fmac_f32_e32 v81, s100, v78
	v_readlane_b32 s100, v111, 12
	v_fmac_f32_e32 v110, s101, v79
	v_readlane_b32 s101, v111, 13
	v_fmac_f32_e32 v81, s10, v76
	v_readlane_b32 s10, v111, 14
	v_fmac_f32_e32 v110, s11, v77
	v_readlane_b32 s11, v111, 15
	v_fmac_f32_e32 v81, s100, v72
	v_readlane_b32 s100, v111, 16
	v_fmac_f32_e32 v110, s101, v73
	v_readlane_b32 s101, v111, 17
	v_fmac_f32_e32 v81, s10, v66
	v_readlane_b32 s10, v111, 18
	v_fmac_f32_e32 v110, s11, v67
	v_readlane_b32 s11, v111, 19
	v_fmac_f32_e32 v81, s100, v64
	v_readlane_b32 s100, v108, 0
	v_fmac_f32_e32 v110, s101, v65
	v_readlane_b32 s101, v108, 1
	v_fmac_f32_e32 v81, s10, v62
	v_readlane_b32 s10, v108, 2
	v_fmac_f32_e32 v110, s11, v63
	v_readlane_b32 s11, v108, 3
	v_add_f32_e32 v81, v81, v110
	v_sub_f32_e32 v60, v60, v81
	v_fma_f32 v81, v5, s100, 0
	v_readlane_b32 s100, v108, 4
	v_fma_f32 v110, v4, s101, 0
	v_readlane_b32 s101, v108, 5
	v_fmac_f32_e32 v81, s10, v124
	v_readlane_b32 s10, v108, 6
	v_fmac_f32_e32 v110, s11, v71
	v_readlane_b32 s11, v108, 7
	v_fmac_f32_e32 v81, s100, v70
	v_readlane_b32 s100, v108, 8
	v_fmac_f32_e32 v110, s101, v74
	v_readlane_b32 s101, v108, 9
	v_fmac_f32_e32 v81, s10, v75
	v_readlane_b32 s10, v108, 10
	v_fmac_f32_e32 v110, s11, v80
	v_readlane_b32 s11, v108, 11
	v_fmac_f32_e32 v81, s100, v78
	v_readlane_b32 s100, v108, 12
	v_fmac_f32_e32 v110, s101, v79
	v_readlane_b32 s101, v108, 13
	v_fmac_f32_e32 v81, s10, v76
	v_readlane_b32 s10, v108, 14
	v_fmac_f32_e32 v110, s11, v77
	v_readlane_b32 s11, v108, 15
	v_fmac_f32_e32 v81, s100, v72
	v_readlane_b32 s100, v108, 16
	v_fmac_f32_e32 v110, s101, v73
	v_readlane_b32 s101, v108, 17
	v_fmac_f32_e32 v81, s10, v66
	v_readlane_b32 s10, v108, 18
	v_fmac_f32_e32 v110, s11, v67
	v_readlane_b32 s11, v108, 19
	v_fmac_f32_e32 v81, s100, v64
	v_readlane_b32 s100, v108, 20
	v_fmac_f32_e32 v110, s101, v65
	v_readlane_b32 s101, v109, 0
	v_fmac_f32_e32 v81, s10, v62
; __device__ __forceinline__ void gd_prep_item(CArgs* a, LAS unsigned char* lds, int l, int item) {
;     ...
;         for (int t = 1; t < 64; ++t) { float s0 = 0.f, s1 = 0.f;
; #pragma unroll
;             for (int sI = 0; sI < t; ++sI) { const float cf = __builtin_bit_cast(float, __builtin_amdgcn_readlane(__builtin_bit_cast(int, nrow[t]), sI)); if (sI & 1) s1 += cf * x[sI]; else s0 += cf * x[sI]; }
;             x[t] -= s0 + s1; }
	v_readlane_b32 s10, v109, 1
	v_fmac_f32_e32 v110, s11, v63
	v_readlane_b32 s11, v109, 2
	v_fmac_f32_e32 v81, s100, v60
	v_readlane_b32 s100, v109, 3
	v_add_f32_e32 v81, v110, v81
	v_sub_f32_e32 v61, v61, v81
	v_fma_f32 v81, v5, s101, 0
	v_readlane_b32 s101, v109, 4
	v_fma_f32 v108, v4, s10, 0
	v_readlane_b32 s10, v109, 5
	v_fmac_f32_e32 v81, s11, v124
	v_readlane_b32 s11, v109, 6
	v_fmac_f32_e32 v108, s100, v71
	v_readlane_b32 s100, v109, 7
	v_fmac_f32_e32 v81, s101, v70
	v_readlane_b32 s101, v109, 8
	v_fmac_f32_e32 v108, s10, v74
	v_readlane_b32 s10, v109, 9
	v_fmac_f32_e32 v81, s11, v75
	v_readlane_b32 s11, v109, 10
	v_fmac_f32_e32 v108, s100, v80
	v_readlane_b32 s100, v109, 11
	v_fmac_f32_e32 v81, s101, v78
	v_readlane_b32 s101, v109, 12
	v_fmac_f32_e32 v108, s10, v79
	v_readlane_b32 s10, v109, 13
	v_fmac_f32_e32 v81, s11, v76
	v_readlane_b32 s11, v109, 14
	v_fmac_f32_e32 v108, s100, v77
	v_readlane_b32 s100, v109, 15
	v_fmac_f32_e32 v81, s101, v72
	v_readlane_b32 s101, v109, 16
	v_fmac_f32_e32 v108, s10, v73
	v_readlane_b32 s10, v109, 17
	v_fmac_f32_e32 v81, s11, v66
	v_readlane_b32 s11, v109, 18
	v_fmac_f32_e32 v108, s100, v67
	v_readlane_b32 s100, v109, 19
	v_fmac_f32_e32 v81, s101, v64
	v_readlane_b32 s101, v109, 20
	v_fmac_f32_e32 v108, s10, v65
	v_readlane_b32 s10, v109, 21
	v_fmac_f32_e32 v81, s11, v62
	v_readlane_b32 s11, v106, 0
	v_fmac_f32_e32 v108, s100, v63
	v_readlane_b32 s100, v106, 1
	v_fmac_f32_e32 v81, s101, v60
	v_readlane_b32 s101, v106, 2
	v_fmac_f32_e32 v108, s10, v61
	v_readlane_b32 s10, v106, 3
	v_add_f32_e32 v81, v81, v108
	v_sub_f32_e32 v56, v56, v81
	v_fma_f32 v81, v5, s11, 0
	v_readlane_b32 s11, v106, 4
	v_fma_f32 v108, v4, s100, 0
	v_readlane_b32 s100, v106, 5
	v_fmac_f32_e32 v81, s101, v124
	v_readlane_b32 s101, v106, 6
	v_fmac_f32_e32 v108, s10, v71
	v_readlane_b32 s10, v106, 7
	v_fmac_f32_e32 v81, s11, v70
	v_readlane_b32 s11, v106, 8
	v_fmac_f32_e32 v108, s100, v74
	v_readlane_b32 s100, v106, 9
	v_fmac_f32_e32 v81, s101, v75
	v_readlane_b32 s101, v106, 10
	v_fmac_f32_e32 v108, s10, v80
	v_readlane_b32 s10, v106, 11
	v_fmac_f32_e32 v81, s11, v78
	v_readlane_b32 s11, v106, 12
	v_fmac_f32_e32 v108, s100, v79
	v_readlane_b32 s100, v106, 13
	v_fmac_f32_e32 v81, s101, v76
	v_readlane_b32 s101, v106, 14
	v_fmac_f32_e32 v108, s10, v77
	v_readlane_b32 s10, v106, 15
	v_fmac_f32_e32 v81, s11, v72
	v_readlane_b32 s11, v106, 16
	v_fmac_f32_e32 v108, s100, v73
	v_readlane_b32 s100, v106, 17
	v_fmac_f32_e32 v81, s101, v66
	v_readlane_b32 s101, v106, 18
	v_fmac_f32_e32 v108, s10, v67
	v_readlane_b32 s10, v106, 19
	v_fmac_f32_e32 v81, s11, v64
	v_readlane_b32 s11, v106, 20
	v_fmac_f32_e32 v108, s100, v65
	v_readlane_b32 s100, v106, 21
	v_fmac_f32_e32 v81, s101, v62
	v_readlane_b32 s101, v106, 22
	v_fmac_f32_e32 v108, s10, v63
	v_readlane_b32 s10, v107, 0
	v_fmac_f32_e32 v81, s11, v60
	v_readlane_b32 s11, v107, 1
	v_fmac_f32_e32 v108, s100, v61
	v_readlane_b32 s100, v107, 2
	v_fmac_f32_e32 v81, s101, v56
	v_readlane_b32 s101, v107, 3
	v_add_f32_e32 v81, v108, v81
	v_sub_f32_e32 v57, v57, v81
	v_fma_f32 v81, v5, s10, 0
	v_readlane_b32 s10, v107, 4
	v_fma_f32 v106, v4, s11, 0
	v_readlane_b32 s11, v107, 5
	v_fmac_f32_e32 v81, s100, v124
	v_readlane_b32 s100, v107, 6
	v_fmac_f32_e32 v106, s101, v71
	v_readlane_b32 s101, v107, 7
	v_fmac_f32_e32 v81, s10, v70
	v_readlane_b32 s10, v107, 8
	v_fmac_f32_e32 v106, s11, v74
	v_readlane_b32 s11, v107, 9
	v_fmac_f32_e32 v81, s100, v75
	v_readlane_b32 s100, v107, 10
	v_fmac_f32_e32 v106, s101, v80
	v_readlane_b32 s101, v107, 11
	v_fmac_f32_e32 v81, s10, v78
	v_readlane_b32 s10, v107, 12
	v_fmac_f32_e32 v106, s11, v79
	v_readlane_b32 s11, v107, 13
	v_fmac_f32_e32 v81, s100, v76
	v_readlane_b32 s100, v107, 14
	v_fmac_f32_e32 v106, s101, v77
	v_readlane_b32 s101, v107, 15
	v_fmac_f32_e32 v81, s10, v72
	v_readlane_b32 s10, v107, 16
	v_fmac_f32_e32 v106, s11, v73
	v_readlane_b32 s11, v107, 17
	v_fmac_f32_e32 v81, s100, v66
	v_readlane_b32 s100, v107, 18
	v_fmac_f32_e32 v106, s101, v67
	v_readlane_b32 s101, v107, 19
	v_fmac_f32_e32 v81, s10, v64
	v_readlane_b32 s10, v107, 20
	v_fmac_f32_e32 v106, s11, v65
	v_readlane_b32 s11, v107, 21
	v_fmac_f32_e32 v81, s100, v62
	v_readlane_b32 s100, v107, 22
	v_fmac_f32_e32 v106, s101, v63
	v_readlane_b32 s101, v107, 23
	v_fmac_f32_e32 v81, s10, v60
	v_readlane_b32 s10, v104, 0
	v_fmac_f32_e32 v106, s11, v61
	v_readlane_b32 s11, v104, 1
	v_fmac_f32_e32 v81, s100, v56
	v_readlane_b32 s100, v104, 2
	v_fmac_f32_e32 v106, s101, v57
	v_readlane_b32 s101, v104, 3
	v_add_f32_e32 v81, v81, v106
	v_sub_f32_e32 v54, v54, v81
	v_fma_f32 v81, v5, s10, 0
	v_readlane_b32 s10, v104, 4
	v_fma_f32 v106, v4, s11, 0
	v_readlane_b32 s11, v104, 5
	v_fmac_f32_e32 v81, s100, v124
	v_readlane_b32 s100, v104, 6
	v_fmac_f32_e32 v106, s101, v71
	v_readlane_b32 s101, v104, 7
	v_fmac_f32_e32 v81, s10, v70
	v_readlane_b32 s10, v104, 8
	v_fmac_f32_e32 v106, s11, v74
	v_readlane_b32 s11, v104, 9
	v_fmac_f32_e32 v81, s100, v75
	v_readlane_b32 s100, v104, 10
	v_fmac_f32_e32 v106, s101, v80
	v_readlane_b32 s101, v104, 11
	v_fmac_f32_e32 v81, s10, v78
	v_readlane_b32 s10, v104, 12
	v_fmac_f32_e32 v106, s11, v79
	v_readlane_b32 s11, v104, 13
	v_fmac_f32_e32 v81, s100, v76
	v_readlane_b32 s100, v104, 14
	v_fmac_f32_e32 v106, s101, v77
	v_readlane_b32 s101, v104, 15
	v_fmac_f32_e32 v81, s10, v72
	v_readlane_b32 s10, v104, 16
	v_fmac_f32_e32 v106, s11, v73
	v_readlane_b32 s11, v104, 17
	v_fmac_f32_e32 v81, s100, v66
	v_readlane_b32 s100, v104, 18
	v_fmac_f32_e32 v106, s101, v67
	v_readlane_b32 s101, v104, 19
	v_fmac_f32_e32 v81, s10, v64
	v_readlane_b32 s10, v104, 20
	v_fmac_f32_e32 v106, s11, v65
; __device__ __forceinline__ void gd_prep_item(CArgs* a, LAS unsigned char* lds, int l, int item) {
;     ...
;         for (int t = 1; t < 64; ++t) { float s0 = 0.f, s1 = 0.f;
; #pragma unroll
;             for (int sI = 0; sI < t; ++sI) { const float cf = __builtin_bit_cast(float, __builtin_amdgcn_readlane(__builtin_bit_cast(int, nrow[t]), sI)); if (sI & 1) s1 += cf * x[sI]; else s0 += cf * x[sI]; }
;             x[t] -= s0 + s1; }
	v_readlane_b32 s11, v104, 21
	v_fmac_f32_e32 v81, s100, v62
	v_readlane_b32 s100, v104, 22
	v_fmac_f32_e32 v106, s101, v63
	v_readlane_b32 s101, v104, 23
	v_fmac_f32_e32 v81, s10, v60
	v_readlane_b32 s10, v104, 24
	v_fmac_f32_e32 v106, s11, v61
	v_readlane_b32 s11, v105, 0
	v_fmac_f32_e32 v81, s100, v56
	v_readlane_b32 s100, v105, 1
	v_fmac_f32_e32 v106, s101, v57
	v_readlane_b32 s101, v105, 2
	v_fmac_f32_e32 v81, s10, v54
	v_readlane_b32 s10, v105, 3
	v_add_f32_e32 v81, v106, v81
	v_sub_f32_e32 v55, v55, v81
	v_fma_f32 v81, v5, s11, 0
	v_readlane_b32 s11, v105, 4
	v_fma_f32 v104, v4, s100, 0
	v_readlane_b32 s100, v105, 5
	v_fmac_f32_e32 v81, s101, v124
	v_readlane_b32 s101, v105, 6
	v_fmac_f32_e32 v104, s10, v71
	v_readlane_b32 s10, v105, 7
	v_fmac_f32_e32 v81, s11, v70
	v_readlane_b32 s11, v105, 8
	v_fmac_f32_e32 v104, s100, v74
	v_readlane_b32 s100, v105, 9
	v_fmac_f32_e32 v81, s101, v75
	v_readlane_b32 s101, v105, 10
	v_fmac_f32_e32 v104, s10, v80
	v_readlane_b32 s10, v105, 11
	v_fmac_f32_e32 v81, s11, v78
	v_readlane_b32 s11, v105, 12
	v_fmac_f32_e32 v104, s100, v79
	v_readlane_b32 s100, v105, 13
	v_fmac_f32_e32 v81, s101, v76
	v_readlane_b32 s101, v105, 14
	v_fmac_f32_e32 v104, s10, v77
	v_readlane_b32 s10, v105, 15
	v_fmac_f32_e32 v81, s11, v72
	v_readlane_b32 s11, v105, 16
	v_fmac_f32_e32 v104, s100, v73
	v_readlane_b32 s100, v105, 17
	v_fmac_f32_e32 v81, s101, v66
	v_readlane_b32 s101, v105, 18
	v_fmac_f32_e32 v104, s10, v67
	v_readlane_b32 s10, v105, 19
	v_fmac_f32_e32 v81, s11, v64
	v_readlane_b32 s11, v105, 20
	v_fmac_f32_e32 v104, s100, v65
	v_readlane_b32 s100, v105, 21
	v_fmac_f32_e32 v81, s101, v62
	v_readlane_b32 s101, v105, 22
	v_fmac_f32_e32 v104, s10, v63
	v_readlane_b32 s10, v105, 23
	v_fmac_f32_e32 v81, s11, v60
	v_readlane_b32 s11, v105, 24
	v_fmac_f32_e32 v104, s100, v61
	v_readlane_b32 s100, v105, 25
	v_fmac_f32_e32 v81, s101, v56
	v_readlane_b32 s101, v102, 0
	v_fmac_f32_e32 v104, s10, v57
	v_readlane_b32 s10, v102, 1
	v_fmac_f32_e32 v81, s11, v54
	v_readlane_b32 s11, v102, 2
	v_fmac_f32_e32 v104, s100, v55
	v_readlane_b32 s100, v102, 3
	v_add_f32_e32 v81, v81, v104
	v_sub_f32_e32 v52, v52, v81
	v_fma_f32 v81, v5, s101, 0
	v_readlane_b32 s101, v102, 4
	v_fma_f32 v104, v4, s10, 0
	v_readlane_b32 s10, v102, 5
	v_fmac_f32_e32 v81, s11, v124
	v_readlane_b32 s11, v102, 6
	v_fmac_f32_e32 v104, s100, v71
	v_readlane_b32 s100, v102, 7
	v_fmac_f32_e32 v81, s101, v70
	v_readlane_b32 s101, v102, 8
	v_fmac_f32_e32 v104, s10, v74
	v_readlane_b32 s10, v102, 9
	v_fmac_f32_e32 v81, s11, v75
	v_readlane_b32 s11, v102, 10
	v_fmac_f32_e32 v104, s100, v80
	v_readlane_b32 s100, v102, 11
	v_fmac_f32_e32 v81, s101, v78
	v_readlane_b32 s101, v102, 12
	v_fmac_f32_e32 v104, s10, v79
	v_readlane_b32 s10, v102, 13
	v_fmac_f32_e32 v81, s11, v76
	v_readlane_b32 s11, v102, 14
	v_fmac_f32_e32 v104, s100, v77
	v_readlane_b32 s100, v102, 15
	v_fmac_f32_e32 v81, s101, v72
	v_readlane_b32 s101, v102, 16
	v_fmac_f32_e32 v104, s10, v73
	v_readlane_b32 s10, v102, 17
	v_fmac_f32_e32 v81, s11, v66
	v_readlane_b32 s11, v102, 18
	v_fmac_f32_e32 v104, s100, v67
	v_readlane_b32 s100, v102, 19
	v_fmac_f32_e32 v81, s101, v64
	v_readlane_b32 s101, v102, 20
	v_fmac_f32_e32 v104, s10, v65
	v_readlane_b32 s10, v102, 21
	v_fmac_f32_e32 v81, s11, v62
	v_readlane_b32 s11, v102, 22
	v_fmac_f32_e32 v104, s100, v63
	v_readlane_b32 s100, v102, 23
	v_fmac_f32_e32 v81, s101, v60
	v_readlane_b32 s101, v102, 24
	v_fmac_f32_e32 v104, s10, v61
	v_readlane_b32 s10, v102, 25
	v_fmac_f32_e32 v81, s11, v56
	v_readlane_b32 s11, v102, 26
	v_fmac_f32_e32 v104, s100, v57
	v_readlane_b32 s100, v103, 0
	v_fmac_f32_e32 v81, s101, v54
	v_readlane_b32 s101, v103, 1
	v_fmac_f32_e32 v104, s10, v55
	v_readlane_b32 s10, v103, 2
	v_fmac_f32_e32 v81, s11, v52
	v_readlane_b32 s11, v103, 3
	v_add_f32_e32 v81, v104, v81
	v_sub_f32_e32 v53, v53, v81
	v_fma_f32 v81, v5, s100, 0
	v_readlane_b32 s100, v103, 4
	v_fma_f32 v102, v4, s101, 0
	v_readlane_b32 s101, v103, 5
	v_fmac_f32_e32 v81, s10, v124
	v_readlane_b32 s10, v103, 6
	v_fmac_f32_e32 v102, s11, v71
	v_readlane_b32 s11, v103, 7
	v_fmac_f32_e32 v81, s100, v70
	v_readlane_b32 s100, v103, 8
	v_fmac_f32_e32 v102, s101, v74
	v_readlane_b32 s101, v103, 9
	v_fmac_f32_e32 v81, s10, v75
	v_readlane_b32 s10, v103, 10
	v_fmac_f32_e32 v102, s11, v80
	v_readlane_b32 s11, v103, 11
	v_fmac_f32_e32 v81, s100, v78
	v_readlane_b32 s100, v103, 12
	v_fmac_f32_e32 v102, s101, v79
	v_readlane_b32 s101, v103, 13
	v_fmac_f32_e32 v81, s10, v76
	v_readlane_b32 s10, v103, 14
	v_fmac_f32_e32 v102, s11, v77
	v_readlane_b32 s11, v103, 15
	v_fmac_f32_e32 v81, s100, v72
	v_readlane_b32 s100, v103, 16
	v_fmac_f32_e32 v102, s101, v73
	v_readlane_b32 s101, v103, 17
	v_fmac_f32_e32 v81, s10, v66
	v_readlane_b32 s10, v103, 18
	v_fmac_f32_e32 v102, s11, v67
	v_readlane_b32 s11, v103, 19
	v_fmac_f32_e32 v81, s100, v64
	v_readlane_b32 s100, v103, 20
	v_fmac_f32_e32 v102, s101, v65
	v_readlane_b32 s101, v103, 21
	v_fmac_f32_e32 v81, s10, v62
	v_readlane_b32 s10, v103, 22
	v_fmac_f32_e32 v102, s11, v63
	v_readlane_b32 s11, v103, 23
	v_fmac_f32_e32 v81, s100, v60
	v_readlane_b32 s100, v103, 24
	v_fmac_f32_e32 v102, s101, v61
	v_readlane_b32 s101, v103, 25
	v_fmac_f32_e32 v81, s10, v56
	v_readlane_b32 s10, v103, 26
	v_fmac_f32_e32 v102, s11, v57
	v_readlane_b32 s11, v103, 27
	v_fmac_f32_e32 v81, s100, v54
	v_readlane_b32 s100, v100, 0
	v_fmac_f32_e32 v102, s101, v55
	v_readlane_b32 s101, v100, 1
	v_fmac_f32_e32 v81, s10, v52
	v_readlane_b32 s10, v100, 2
	v_fmac_f32_e32 v102, s11, v53
	v_readlane_b32 s11, v100, 3
	v_add_f32_e32 v81, v81, v102
	v_sub_f32_e32 v48, v48, v81
; __device__ __forceinline__ void gd_prep_item(CArgs* a, LAS unsigned char* lds, int l, int item) {
;     ...
;         for (int t = 1; t < 64; ++t) { float s0 = 0.f, s1 = 0.f;
; #pragma unroll
;             for (int sI = 0; sI < t; ++sI) { const float cf = __builtin_bit_cast(float, __builtin_amdgcn_readlane(__builtin_bit_cast(int, nrow[t]), sI)); if (sI & 1) s1 += cf * x[sI]; else s0 += cf * x[sI]; }
;             x[t] -= s0 + s1; }
	v_fma_f32 v81, v5, s100, 0
	v_readlane_b32 s100, v100, 4
	v_fma_f32 v102, v4, s101, 0
	v_readlane_b32 s101, v100, 5
	v_fmac_f32_e32 v81, s10, v124
	v_readlane_b32 s10, v100, 6
	v_fmac_f32_e32 v102, s11, v71
	v_readlane_b32 s11, v100, 7
	v_fmac_f32_e32 v81, s100, v70
	v_readlane_b32 s100, v100, 8
	v_fmac_f32_e32 v102, s101, v74
	v_readlane_b32 s101, v100, 9
	v_fmac_f32_e32 v81, s10, v75
	v_readlane_b32 s10, v100, 10
	v_fmac_f32_e32 v102, s11, v80
	v_readlane_b32 s11, v100, 11
	v_fmac_f32_e32 v81, s100, v78
	v_readlane_b32 s100, v100, 12
	v_fmac_f32_e32 v102, s101, v79
	v_readlane_b32 s101, v100, 13
	v_fmac_f32_e32 v81, s10, v76
	v_readlane_b32 s10, v100, 14
	v_fmac_f32_e32 v102, s11, v77
	v_readlane_b32 s11, v100, 15
	v_fmac_f32_e32 v81, s100, v72
	v_readlane_b32 s100, v100, 16
	v_fmac_f32_e32 v102, s101, v73
	v_readlane_b32 s101, v100, 17
	v_fmac_f32_e32 v81, s10, v66
	v_readlane_b32 s10, v100, 18
	v_fmac_f32_e32 v102, s11, v67
	v_readlane_b32 s11, v100, 19
	v_fmac_f32_e32 v81, s100, v64
	v_readlane_b32 s100, v100, 20
	v_fmac_f32_e32 v102, s101, v65
	v_readlane_b32 s101, v100, 21
	v_fmac_f32_e32 v81, s10, v62
	v_readlane_b32 s10, v100, 22
	v_fmac_f32_e32 v102, s11, v63
	v_readlane_b32 s11, v100, 23
	v_fmac_f32_e32 v81, s100, v60
	v_readlane_b32 s100, v100, 24
	v_fmac_f32_e32 v102, s101, v61
	v_readlane_b32 s101, v100, 25
	v_fmac_f32_e32 v81, s10, v56
	v_readlane_b32 s10, v100, 26
	v_fmac_f32_e32 v102, s11, v57
	v_readlane_b32 s11, v100, 27
	v_fmac_f32_e32 v81, s100, v54
	v_readlane_b32 s100, v100, 28
	v_fmac_f32_e32 v102, s101, v55
	v_readlane_b32 s101, v101, 0
	v_fmac_f32_e32 v81, s10, v52
	v_readlane_b32 s10, v101, 1
	v_fmac_f32_e32 v102, s11, v53
	v_readlane_b32 s11, v101, 2
	v_fmac_f32_e32 v81, s100, v48
	v_readlane_b32 s100, v101, 3
	v_add_f32_e32 v81, v102, v81
	v_sub_f32_e32 v49, v49, v81
	v_fma_f32 v81, v5, s101, 0
	v_readlane_b32 s101, v101, 4
	v_fma_f32 v100, v4, s10, 0
	v_readlane_b32 s10, v101, 5
	v_fmac_f32_e32 v81, s11, v124
	v_readlane_b32 s11, v101, 6
	v_fmac_f32_e32 v100, s100, v71
	v_readlane_b32 s100, v101, 7
	v_fmac_f32_e32 v81, s101, v70
	v_readlane_b32 s101, v101, 8
	v_fmac_f32_e32 v100, s10, v74
	v_readlane_b32 s10, v101, 9
	v_fmac_f32_e32 v81, s11, v75
	v_readlane_b32 s11, v101, 10
	v_fmac_f32_e32 v100, s100, v80
	v_readlane_b32 s100, v101, 11
	v_fmac_f32_e32 v81, s101, v78
	v_readlane_b32 s101, v101, 12
	v_fmac_f32_e32 v100, s10, v79
	v_readlane_b32 s10, v101, 13
	v_fmac_f32_e32 v81, s11, v76
	v_readlane_b32 s11, v101, 14
	v_fmac_f32_e32 v100, s100, v77
	v_readlane_b32 s100, v101, 15
	v_fmac_f32_e32 v81, s101, v72
	v_readlane_b32 s101, v101, 16
	v_fmac_f32_e32 v100, s10, v73
	v_readlane_b32 s10, v101, 17
	v_fmac_f32_e32 v81, s11, v66
	v_readlane_b32 s11, v101, 18
	v_fmac_f32_e32 v100, s100, v67
	v_readlane_b32 s100, v101, 19
	v_fmac_f32_e32 v81, s101, v64
	v_readlane_b32 s101, v101, 20
	v_fmac_f32_e32 v100, s10, v65
	v_readlane_b32 s10, v101, 21
	v_fmac_f32_e32 v81, s11, v62
	v_readlane_b32 s11, v101, 22
	v_fmac_f32_e32 v100, s100, v63
	v_readlane_b32 s100, v101, 23
	v_fmac_f32_e32 v81, s101, v60
	v_readlane_b32 s101, v101, 24
	v_fmac_f32_e32 v100, s10, v61
	v_readlane_b32 s10, v101, 25
	v_fmac_f32_e32 v81, s11, v56
	v_readlane_b32 s11, v101, 26
	v_fmac_f32_e32 v100, s100, v57
	v_readlane_b32 s100, v101, 27
	v_fmac_f32_e32 v81, s101, v54
	v_readlane_b32 s101, v101, 28
	v_fmac_f32_e32 v100, s10, v55
	v_readlane_b32 s10, v101, 29
	v_fmac_f32_e32 v81, s11, v52
	v_readlane_b32 s11, v98, 0
	v_fmac_f32_e32 v100, s100, v53
	v_readlane_b32 s100, v98, 1
	v_fmac_f32_e32 v81, s101, v48
	v_readlane_b32 s101, v98, 2
	v_fmac_f32_e32 v100, s10, v49
	v_readlane_b32 s10, v98, 3
	v_add_f32_e32 v81, v81, v100
	v_sub_f32_e32 v46, v46, v81
	v_fma_f32 v81, v5, s11, 0
	v_readlane_b32 s11, v98, 4
	v_fma_f32 v100, v4, s100, 0
	v_readlane_b32 s100, v98, 5
	v_fmac_f32_e32 v81, s101, v124
	v_readlane_b32 s101, v98, 6
	v_fmac_f32_e32 v100, s10, v71
	v_readlane_b32 s10, v98, 7
	v_fmac_f32_e32 v81, s11, v70
	v_readlane_b32 s11, v98, 8
	v_fmac_f32_e32 v100, s100, v74
	v_readlane_b32 s100, v98, 9
	v_fmac_f32_e32 v81, s101, v75
	v_readlane_b32 s101, v98, 10
	v_fmac_f32_e32 v100, s10, v80
	v_readlane_b32 s10, v98, 11
	v_fmac_f32_e32 v81, s11, v78
	v_readlane_b32 s11, v98, 12
	v_fmac_f32_e32 v100, s100, v79
	v_readlane_b32 s100, v98, 13
	v_fmac_f32_e32 v81, s101, v76
	v_readlane_b32 s101, v98, 14
	v_fmac_f32_e32 v100, s10, v77
	v_readlane_b32 s10, v98, 15
	v_fmac_f32_e32 v81, s11, v72
	v_readlane_b32 s11, v98, 16
	v_fmac_f32_e32 v100, s100, v73
	v_readlane_b32 s100, v98, 17
	v_fmac_f32_e32 v81, s101, v66
	v_readlane_b32 s101, v98, 18
	v_fmac_f32_e32 v100, s10, v67
	v_readlane_b32 s10, v98, 19
	v_fmac_f32_e32 v81, s11, v64
	v_readlane_b32 s11, v98, 20
	v_fmac_f32_e32 v100, s100, v65
	v_readlane_b32 s100, v98, 21
	v_fmac_f32_e32 v81, s101, v62
	v_readlane_b32 s101, v98, 22
	v_fmac_f32_e32 v100, s10, v63
	v_readlane_b32 s10, v98, 23
	v_fmac_f32_e32 v81, s11, v60
	v_readlane_b32 s11, v98, 24
	v_fmac_f32_e32 v100, s100, v61
	v_readlane_b32 s100, v98, 25
	v_fmac_f32_e32 v81, s101, v56
	v_readlane_b32 s101, v98, 26
	v_fmac_f32_e32 v100, s10, v57
	v_readlane_b32 s10, v98, 27
	v_fmac_f32_e32 v81, s11, v54
	v_readlane_b32 s11, v98, 28
	v_fmac_f32_e32 v100, s100, v55
	v_readlane_b32 s100, v98, 29
	v_fmac_f32_e32 v81, s101, v52
	v_readlane_b32 s101, v98, 30
	v_fmac_f32_e32 v100, s10, v53
	v_readlane_b32 s10, v99, 0
	v_fmac_f32_e32 v81, s11, v48
	v_readlane_b32 s11, v99, 1
	v_fmac_f32_e32 v100, s100, v49
	v_readlane_b32 s100, v99, 2
	v_fmac_f32_e32 v81, s101, v46
	v_readlane_b32 s101, v99, 3
	v_add_f32_e32 v81, v100, v81
	v_sub_f32_e32 v47, v47, v81
; __device__ __forceinline__ void gd_prep_item(CArgs* a, LAS unsigned char* lds, int l, int item) {
;     ...
;         for (int t = 1; t < 64; ++t) { float s0 = 0.f, s1 = 0.f;
; #pragma unroll
;             for (int sI = 0; sI < t; ++sI) { const float cf = __builtin_bit_cast(float, __builtin_amdgcn_readlane(__builtin_bit_cast(int, nrow[t]), sI)); if (sI & 1) s1 += cf * x[sI]; else s0 += cf * x[sI]; }
;             x[t] -= s0 + s1; }
	v_fma_f32 v81, v5, s10, 0
	v_readlane_b32 s10, v99, 4
	v_fma_f32 v98, v4, s11, 0
	v_readlane_b32 s11, v99, 5
	v_fmac_f32_e32 v81, s100, v124
	v_readlane_b32 s100, v99, 6
	v_fmac_f32_e32 v98, s101, v71
	v_readlane_b32 s101, v99, 7
	v_fmac_f32_e32 v81, s10, v70
	v_readlane_b32 s10, v99, 8
	v_fmac_f32_e32 v98, s11, v74
	v_readlane_b32 s11, v99, 9
	v_fmac_f32_e32 v81, s100, v75
	v_readlane_b32 s100, v99, 10
	v_fmac_f32_e32 v98, s101, v80
	v_readlane_b32 s101, v99, 11
	v_fmac_f32_e32 v81, s10, v78
	v_readlane_b32 s10, v99, 12
	v_fmac_f32_e32 v98, s11, v79
	v_readlane_b32 s11, v99, 13
	v_fmac_f32_e32 v81, s100, v76
	v_readlane_b32 s100, v99, 14
	v_fmac_f32_e32 v98, s101, v77
	v_readlane_b32 s101, v99, 15
	v_fmac_f32_e32 v81, s10, v72
	v_readlane_b32 s10, v99, 16
	v_fmac_f32_e32 v98, s11, v73
	v_readlane_b32 s11, v99, 17
	v_fmac_f32_e32 v81, s100, v66
	v_readlane_b32 s100, v99, 18
	v_fmac_f32_e32 v98, s101, v67
	v_readlane_b32 s101, v99, 19
	v_fmac_f32_e32 v81, s10, v64
	v_readlane_b32 s10, v99, 20
	v_fmac_f32_e32 v98, s11, v65
	v_readlane_b32 s11, v99, 21
	v_fmac_f32_e32 v81, s100, v62
	v_readlane_b32 s100, v99, 22
	v_fmac_f32_e32 v98, s101, v63
	v_readlane_b32 s101, v99, 23
	v_fmac_f32_e32 v81, s10, v60
	v_readlane_b32 s10, v99, 24
	v_fmac_f32_e32 v98, s11, v61
	v_readlane_b32 s11, v99, 25
	v_fmac_f32_e32 v81, s100, v56
	v_readlane_b32 s100, v99, 26
	v_fmac_f32_e32 v98, s101, v57
	v_readlane_b32 s101, v99, 27
	v_fmac_f32_e32 v81, s10, v54
	v_readlane_b32 s10, v99, 28
	v_fmac_f32_e32 v98, s11, v55
	v_readlane_b32 s11, v99, 29
	v_fmac_f32_e32 v81, s100, v52
	v_readlane_b32 s100, v99, 30
	v_fmac_f32_e32 v98, s101, v53
	v_readlane_b32 s101, v99, 31
	v_fmac_f32_e32 v81, s10, v48
	v_fmac_f32_e32 v98, s11, v49
	v_fmac_f32_e32 v81, s100, v46
	v_fmac_f32_e32 v98, s101, v47
	v_add_f32_e32 v81, v81, v98
	s_waitcnt lgkmcnt(14)
	v_readlane_b32 s10, v96, 0
	v_readlane_b32 s11, v96, 1
	v_readlane_b32 s100, v96, 2
	v_readlane_b32 s101, v96, 3
	v_sub_f32_e32 v42, v42, v81
	v_fma_f32 v81, v5, s10, 0
	v_readlane_b32 s10, v96, 4
	v_fma_f32 v98, v4, s11, 0
	v_readlane_b32 s11, v96, 5
	v_fmac_f32_e32 v81, s100, v124
	v_readlane_b32 s100, v96, 6
	v_fmac_f32_e32 v98, s101, v71
	v_readlane_b32 s101, v96, 7
	v_fmac_f32_e32 v81, s10, v70
	v_readlane_b32 s10, v96, 8
	v_fmac_f32_e32 v98, s11, v74
	v_readlane_b32 s11, v96, 9
	v_fmac_f32_e32 v81, s100, v75
	v_readlane_b32 s100, v96, 10
	v_fmac_f32_e32 v98, s101, v80
	v_readlane_b32 s101, v96, 11
	v_fmac_f32_e32 v81, s10, v78
	v_readlane_b32 s10, v96, 12
	v_fmac_f32_e32 v98, s11, v79
	v_readlane_b32 s11, v96, 13
	v_fmac_f32_e32 v81, s100, v76
	v_readlane_b32 s100, v96, 14
	v_fmac_f32_e32 v98, s101, v77
	v_readlane_b32 s101, v96, 15
	v_fmac_f32_e32 v81, s10, v72
	v_readlane_b32 s10, v96, 16
	v_fmac_f32_e32 v98, s11, v73
	v_readlane_b32 s11, v96, 17
	v_fmac_f32_e32 v81, s100, v66
	v_readlane_b32 s100, v96, 18
	v_fmac_f32_e32 v98, s101, v67
	v_readlane_b32 s101, v96, 19
	v_fmac_f32_e32 v81, s10, v64
	v_readlane_b32 s10, v96, 20
	v_fmac_f32_e32 v98, s11, v65
	v_readlane_b32 s11, v96, 21
	v_fmac_f32_e32 v81, s100, v62
	v_readlane_b32 s100, v96, 22
	v_fmac_f32_e32 v98, s101, v63
	v_readlane_b32 s101, v96, 23
	v_fmac_f32_e32 v81, s10, v60
	v_readlane_b32 s10, v96, 24
	v_fmac_f32_e32 v98, s11, v61
	v_readlane_b32 s11, v96, 25
	v_fmac_f32_e32 v81, s100, v56
	v_readlane_b32 s100, v96, 26
	v_fmac_f32_e32 v98, s101, v57
	v_readlane_b32 s101, v96, 27
	v_fmac_f32_e32 v81, s10, v54
	v_readlane_b32 s10, v96, 28
	v_fmac_f32_e32 v98, s11, v55
	v_readlane_b32 s11, v96, 29
	v_fmac_f32_e32 v81, s100, v52
	v_readlane_b32 s100, v96, 30
	v_fmac_f32_e32 v98, s101, v53
	v_readlane_b32 s101, v96, 31
	v_fmac_f32_e32 v81, s10, v48
	v_readlane_b32 s10, v96, 32
	v_fmac_f32_e32 v98, s11, v49
	v_readlane_b32 s11, v97, 0
	v_fmac_f32_e32 v81, s100, v46
	v_readlane_b32 s100, v97, 1
	v_fmac_f32_e32 v98, s101, v47
	v_readlane_b32 s101, v97, 2
	v_fmac_f32_e32 v81, s10, v42
	v_readlane_b32 s10, v97, 3
	v_add_f32_e32 v81, v98, v81
	v_sub_f32_e32 v43, v43, v81
	v_fma_f32 v81, v5, s11, 0
	v_readlane_b32 s11, v97, 4
	v_fma_f32 v96, v4, s100, 0
	v_readlane_b32 s100, v97, 5
	v_fmac_f32_e32 v81, s101, v124
	v_readlane_b32 s101, v97, 6
	v_fmac_f32_e32 v96, s10, v71
	v_readlane_b32 s10, v97, 7
	v_fmac_f32_e32 v81, s11, v70
	v_readlane_b32 s11, v97, 8
	v_fmac_f32_e32 v96, s100, v74
	v_readlane_b32 s100, v97, 9
	v_fmac_f32_e32 v81, s101, v75
	v_readlane_b32 s101, v97, 10
	v_fmac_f32_e32 v96, s10, v80
	v_readlane_b32 s10, v97, 11
	v_fmac_f32_e32 v81, s11, v78
	v_readlane_b32 s11, v97, 12
	v_fmac_f32_e32 v96, s100, v79
	v_readlane_b32 s100, v97, 13
	v_fmac_f32_e32 v81, s101, v76
	v_readlane_b32 s101, v97, 14
	v_fmac_f32_e32 v96, s10, v77
	v_readlane_b32 s10, v97, 15
	v_fmac_f32_e32 v81, s11, v72
	v_readlane_b32 s11, v97, 16
	v_fmac_f32_e32 v96, s100, v73
	v_readlane_b32 s100, v97, 17
	v_fmac_f32_e32 v81, s101, v66
	v_readlane_b32 s101, v97, 18
	v_fmac_f32_e32 v96, s10, v67
	v_readlane_b32 s10, v97, 19
	v_fmac_f32_e32 v81, s11, v64
	v_readlane_b32 s11, v97, 20
	v_fmac_f32_e32 v96, s100, v65
	v_readlane_b32 s100, v97, 21
	v_fmac_f32_e32 v81, s101, v62
	v_readlane_b32 s101, v97, 22
	v_fmac_f32_e32 v96, s10, v63
	v_readlane_b32 s10, v97, 23
	v_fmac_f32_e32 v81, s11, v60
	v_readlane_b32 s11, v97, 24
	v_fmac_f32_e32 v96, s100, v61
	v_readlane_b32 s100, v97, 25
	v_fmac_f32_e32 v81, s101, v56
	v_readlane_b32 s101, v97, 26
	v_fmac_f32_e32 v96, s10, v57
	v_readlane_b32 s10, v97, 27
	v_fmac_f32_e32 v81, s11, v54
	v_readlane_b32 s11, v97, 28
	v_fmac_f32_e32 v96, s100, v55
	v_readlane_b32 s100, v97, 29
	v_fmac_f32_e32 v81, s101, v52
	v_readlane_b32 s101, v97, 30
	v_fmac_f32_e32 v96, s10, v53
; __device__ __forceinline__ void gd_prep_item(CArgs* a, LAS unsigned char* lds, int l, int item) {
;     ...
;         for (int t = 1; t < 64; ++t) { float s0 = 0.f, s1 = 0.f;
; #pragma unroll
;             for (int sI = 0; sI < t; ++sI) { const float cf = __builtin_bit_cast(float, __builtin_amdgcn_readlane(__builtin_bit_cast(int, nrow[t]), sI)); if (sI & 1) s1 += cf * x[sI]; else s0 += cf * x[sI]; }
;             x[t] -= s0 + s1; }
	v_readlane_b32 s10, v97, 31
	v_fmac_f32_e32 v81, s11, v48
	v_readlane_b32 s11, v97, 32
	v_fmac_f32_e32 v96, s100, v49
	v_readlane_b32 s100, v97, 33
	v_fmac_f32_e32 v81, s101, v46
	v_readlane_b32 s101, v94, 0
	v_fmac_f32_e32 v96, s10, v47
	v_readlane_b32 s10, v94, 1
	v_fmac_f32_e32 v81, s11, v42
	v_readlane_b32 s11, v94, 2
	v_fmac_f32_e32 v96, s100, v43
	v_readlane_b32 s100, v94, 3
	v_add_f32_e32 v81, v81, v96
	v_sub_f32_e32 v40, v40, v81
	v_fma_f32 v81, v5, s101, 0
	v_readlane_b32 s101, v94, 4
	v_fma_f32 v96, v4, s10, 0
	v_readlane_b32 s10, v94, 5
	v_fmac_f32_e32 v81, s11, v124
	v_readlane_b32 s11, v94, 6
	v_fmac_f32_e32 v96, s100, v71
	v_readlane_b32 s100, v94, 7
	v_fmac_f32_e32 v81, s101, v70
	v_readlane_b32 s101, v94, 8
	v_fmac_f32_e32 v96, s10, v74
	v_readlane_b32 s10, v94, 9
	v_fmac_f32_e32 v81, s11, v75
	v_readlane_b32 s11, v94, 10
	v_fmac_f32_e32 v96, s100, v80
	v_readlane_b32 s100, v94, 11
	v_fmac_f32_e32 v81, s101, v78
	v_readlane_b32 s101, v94, 12
	v_fmac_f32_e32 v96, s10, v79
	v_readlane_b32 s10, v94, 13
	v_fmac_f32_e32 v81, s11, v76
	v_readlane_b32 s11, v94, 14
	v_fmac_f32_e32 v96, s100, v77
	v_readlane_b32 s100, v94, 15
	v_fmac_f32_e32 v81, s101, v72
	v_readlane_b32 s101, v94, 16
	v_fmac_f32_e32 v96, s10, v73
	v_readlane_b32 s10, v94, 17
	v_fmac_f32_e32 v81, s11, v66
	v_readlane_b32 s11, v94, 18
	v_fmac_f32_e32 v96, s100, v67
	v_readlane_b32 s100, v94, 19
	v_fmac_f32_e32 v81, s101, v64
	v_readlane_b32 s101, v94, 20
	v_fmac_f32_e32 v96, s10, v65
	v_readlane_b32 s10, v94, 21
	v_fmac_f32_e32 v81, s11, v62
	v_readlane_b32 s11, v94, 22
	v_fmac_f32_e32 v96, s100, v63
	v_readlane_b32 s100, v94, 23
	v_fmac_f32_e32 v81, s101, v60
	v_readlane_b32 s101, v94, 24
	v_fmac_f32_e32 v96, s10, v61
	v_readlane_b32 s10, v94, 25
	v_fmac_f32_e32 v81, s11, v56
	v_readlane_b32 s11, v94, 26
	v_fmac_f32_e32 v96, s100, v57
	v_readlane_b32 s100, v94, 27
	v_fmac_f32_e32 v81, s101, v54
	v_readlane_b32 s101, v94, 28
	v_fmac_f32_e32 v96, s10, v55
	v_readlane_b32 s10, v94, 29
	v_fmac_f32_e32 v81, s11, v52
	v_readlane_b32 s11, v94, 30
	v_fmac_f32_e32 v96, s100, v53
	v_readlane_b32 s100, v94, 31
	v_fmac_f32_e32 v81, s101, v48
	v_readlane_b32 s101, v94, 32
	v_fmac_f32_e32 v96, s10, v49
	v_readlane_b32 s10, v94, 33
	v_fmac_f32_e32 v81, s11, v46
	v_readlane_b32 s11, v94, 34
	v_fmac_f32_e32 v96, s100, v47
	v_readlane_b32 s100, v95, 0
	v_fmac_f32_e32 v81, s101, v42
	v_readlane_b32 s101, v95, 1
	v_fmac_f32_e32 v96, s10, v43
	v_readlane_b32 s10, v95, 2
	v_fmac_f32_e32 v81, s11, v40
	v_readlane_b32 s11, v95, 3
	v_add_f32_e32 v81, v96, v81
	v_sub_f32_e32 v41, v41, v81
	v_fma_f32 v81, v5, s100, 0
	v_readlane_b32 s100, v95, 4
	v_fma_f32 v94, v4, s101, 0
	v_readlane_b32 s101, v95, 5
	v_fmac_f32_e32 v81, s10, v124
	v_readlane_b32 s10, v95, 6
	v_fmac_f32_e32 v94, s11, v71
	v_readlane_b32 s11, v95, 7
	v_fmac_f32_e32 v81, s100, v70
	v_readlane_b32 s100, v95, 8
	v_fmac_f32_e32 v94, s101, v74
	v_readlane_b32 s101, v95, 9
	v_fmac_f32_e32 v81, s10, v75
	v_readlane_b32 s10, v95, 10
	v_fmac_f32_e32 v94, s11, v80
	v_readlane_b32 s11, v95, 11
	v_fmac_f32_e32 v81, s100, v78
	v_readlane_b32 s100, v95, 12
	v_fmac_f32_e32 v94, s101, v79
	v_readlane_b32 s101, v95, 13
	v_fmac_f32_e32 v81, s10, v76
	v_readlane_b32 s10, v95, 14
	v_fmac_f32_e32 v94, s11, v77
	v_readlane_b32 s11, v95, 15
	v_fmac_f32_e32 v81, s100, v72
	v_readlane_b32 s100, v95, 16
	v_fmac_f32_e32 v94, s101, v73
	v_readlane_b32 s101, v95, 17
	v_fmac_f32_e32 v81, s10, v66
	v_readlane_b32 s10, v95, 18
	v_fmac_f32_e32 v94, s11, v67
	v_readlane_b32 s11, v95, 19
	v_fmac_f32_e32 v81, s100, v64
	v_readlane_b32 s100, v95, 20
	v_fmac_f32_e32 v94, s101, v65
	v_readlane_b32 s101, v95, 21
	v_fmac_f32_e32 v81, s10, v62
	v_readlane_b32 s10, v95, 22
	v_fmac_f32_e32 v94, s11, v63
	v_readlane_b32 s11, v95, 23
	v_fmac_f32_e32 v81, s100, v60
	v_readlane_b32 s100, v95, 24
	v_fmac_f32_e32 v94, s101, v61
	v_readlane_b32 s101, v95, 25
	v_fmac_f32_e32 v81, s10, v56
	v_readlane_b32 s10, v95, 26
	v_fmac_f32_e32 v94, s11, v57
	v_readlane_b32 s11, v95, 27
	v_fmac_f32_e32 v81, s100, v54
	v_readlane_b32 s100, v95, 28
	v_fmac_f32_e32 v94, s101, v55
	v_readlane_b32 s101, v95, 29
	v_fmac_f32_e32 v81, s10, v52
	v_readlane_b32 s10, v95, 30
	v_fmac_f32_e32 v94, s11, v53
	v_readlane_b32 s11, v95, 31
	v_fmac_f32_e32 v81, s100, v48
	v_readlane_b32 s100, v95, 32
	v_fmac_f32_e32 v94, s101, v49
	v_readlane_b32 s101, v95, 33
	v_fmac_f32_e32 v81, s10, v46
	v_readlane_b32 s10, v95, 34
	v_fmac_f32_e32 v94, s11, v47
	v_readlane_b32 s11, v95, 35
	v_fmac_f32_e32 v81, s100, v42
	v_fmac_f32_e32 v94, s101, v43
	v_fmac_f32_e32 v81, s10, v40
	v_fmac_f32_e32 v94, s11, v41
	v_add_f32_e32 v81, v81, v94
	s_waitcnt lgkmcnt(13)
; __device__ __forceinline__ void gd_prep_item(CArgs* a, LAS unsigned char* lds, int l, int item) {
;     ...
;         for (int t = 1; t < 64; ++t) { float s0 = 0.f, s1 = 0.f;
; #pragma unroll
;             for (int sI = 0; sI < t; ++sI) { const float cf = __builtin_bit_cast(float, __builtin_amdgcn_readlane(__builtin_bit_cast(int, nrow[t]), sI)); if (sI & 1) s1 += cf * x[sI]; else s0 += cf * x[sI]; }
;             x[t] -= s0 + s1; }
	v_readlane_b32 s100, v92, 0
	v_readlane_b32 s101, v92, 1
	v_readlane_b32 s10, v92, 2
	v_readlane_b32 s11, v92, 3
	v_sub_f32_e32 v36, v36, v81
	v_fma_f32 v81, v5, s100, 0
	v_readlane_b32 s100, v92, 4
	v_fma_f32 v94, v4, s101, 0
	v_readlane_b32 s101, v92, 5
	v_fmac_f32_e32 v81, s10, v124
	v_readlane_b32 s10, v92, 6
	v_fmac_f32_e32 v94, s11, v71
	v_readlane_b32 s11, v92, 7
	v_fmac_f32_e32 v81, s100, v70
	v_readlane_b32 s100, v92, 8
	v_fmac_f32_e32 v94, s101, v74
	v_readlane_b32 s101, v92, 9
	v_fmac_f32_e32 v81, s10, v75
	v_readlane_b32 s10, v92, 10
	v_fmac_f32_e32 v94, s11, v80
	v_readlane_b32 s11, v92, 11
	v_fmac_f32_e32 v81, s100, v78
	v_readlane_b32 s100, v92, 12
	v_fmac_f32_e32 v94, s101, v79
	v_readlane_b32 s101, v92, 13
	v_fmac_f32_e32 v81, s10, v76
	v_readlane_b32 s10, v92, 14
	v_fmac_f32_e32 v94, s11, v77
	v_readlane_b32 s11, v92, 15
	v_fmac_f32_e32 v81, s100, v72
	v_readlane_b32 s100, v92, 16
	v_fmac_f32_e32 v94, s101, v73
	v_readlane_b32 s101, v92, 17
	v_fmac_f32_e32 v81, s10, v66
	v_readlane_b32 s10, v92, 18
	v_fmac_f32_e32 v94, s11, v67
	v_readlane_b32 s11, v92, 19
	v_fmac_f32_e32 v81, s100, v64
	v_readlane_b32 s100, v92, 20
	v_fmac_f32_e32 v94, s101, v65
	v_readlane_b32 s101, v92, 21
	v_fmac_f32_e32 v81, s10, v62
	v_readlane_b32 s10, v92, 22
	v_fmac_f32_e32 v94, s11, v63
	v_readlane_b32 s11, v92, 23
	v_fmac_f32_e32 v81, s100, v60
	v_readlane_b32 s100, v92, 24
	v_fmac_f32_e32 v94, s101, v61
	v_readlane_b32 s101, v92, 25
	v_fmac_f32_e32 v81, s10, v56
	v_readlane_b32 s10, v92, 26
	v_fmac_f32_e32 v94, s11, v57
	v_readlane_b32 s11, v92, 27
	v_fmac_f32_e32 v81, s100, v54
	v_readlane_b32 s100, v92, 28
	v_fmac_f32_e32 v94, s101, v55
	v_readlane_b32 s101, v92, 29
	v_fmac_f32_e32 v81, s10, v52
	v_readlane_b32 s10, v92, 30
	v_fmac_f32_e32 v94, s11, v53
	v_readlane_b32 s11, v92, 31
	v_fmac_f32_e32 v81, s100, v48
	v_readlane_b32 s100, v92, 32
	v_fmac_f32_e32 v94, s101, v49
	v_readlane_b32 s101, v92, 33
	v_fmac_f32_e32 v81, s10, v46
	v_readlane_b32 s10, v92, 34
	v_fmac_f32_e32 v94, s11, v47
	v_readlane_b32 s11, v92, 35
	v_fmac_f32_e32 v81, s100, v42
	v_readlane_b32 s100, v92, 36
	v_fmac_f32_e32 v94, s101, v43
	v_readlane_b32 s101, v93, 0
	v_fmac_f32_e32 v81, s10, v40
	v_readlane_b32 s10, v93, 1
	v_fmac_f32_e32 v94, s11, v41
	v_readlane_b32 s11, v93, 2
	v_fmac_f32_e32 v81, s100, v36
	v_readlane_b32 s100, v93, 3
	v_add_f32_e32 v81, v94, v81
	v_sub_f32_e32 v37, v37, v81
	v_fma_f32 v81, v5, s101, 0
	v_readlane_b32 s101, v93, 4
	v_fma_f32 v92, v4, s10, 0
	v_readlane_b32 s10, v93, 5
	v_fmac_f32_e32 v81, s11, v124
	v_readlane_b32 s11, v93, 6
	v_fmac_f32_e32 v92, s100, v71
	v_readlane_b32 s100, v93, 7
	v_fmac_f32_e32 v81, s101, v70
	v_readlane_b32 s101, v93, 8
	v_fmac_f32_e32 v92, s10, v74
	v_readlane_b32 s10, v93, 9
	v_fmac_f32_e32 v81, s11, v75
	v_readlane_b32 s11, v93, 10
	v_fmac_f32_e32 v92, s100, v80
	v_readlane_b32 s100, v93, 11
	v_fmac_f32_e32 v81, s101, v78
	v_readlane_b32 s101, v93, 12
	v_fmac_f32_e32 v92, s10, v79
	v_readlane_b32 s10, v93, 13
	v_fmac_f32_e32 v81, s11, v76
	v_readlane_b32 s11, v93, 14
	v_fmac_f32_e32 v92, s100, v77
	v_readlane_b32 s100, v93, 15
	v_fmac_f32_e32 v81, s101, v72
	v_readlane_b32 s101, v93, 16
	v_fmac_f32_e32 v92, s10, v73
	v_readlane_b32 s10, v93, 17
	v_fmac_f32_e32 v81, s11, v66
	v_readlane_b32 s11, v93, 18
	v_fmac_f32_e32 v92, s100, v67
	v_readlane_b32 s100, v93, 19
	v_fmac_f32_e32 v81, s101, v64
	v_readlane_b32 s101, v93, 20
	v_fmac_f32_e32 v92, s10, v65
	v_readlane_b32 s10, v93, 21
	v_fmac_f32_e32 v81, s11, v62
	v_readlane_b32 s11, v93, 22
	v_fmac_f32_e32 v92, s100, v63
	v_readlane_b32 s100, v93, 23
	v_fmac_f32_e32 v81, s101, v60
	v_readlane_b32 s101, v93, 24
	v_fmac_f32_e32 v92, s10, v61
	v_readlane_b32 s10, v93, 25
	v_fmac_f32_e32 v81, s11, v56
	v_readlane_b32 s11, v93, 26
	v_fmac_f32_e32 v92, s100, v57
	v_readlane_b32 s100, v93, 27
	v_fmac_f32_e32 v81, s101, v54
	v_readlane_b32 s101, v93, 28
	v_fmac_f32_e32 v92, s10, v55
	v_readlane_b32 s10, v93, 29
	v_fmac_f32_e32 v81, s11, v52
	v_readlane_b32 s11, v93, 30
	v_fmac_f32_e32 v92, s100, v53
	v_readlane_b32 s100, v93, 31
	v_fmac_f32_e32 v81, s101, v48
	v_readlane_b32 s101, v93, 32
	v_fmac_f32_e32 v92, s10, v49
	v_readlane_b32 s10, v93, 33
	v_fmac_f32_e32 v81, s11, v46
	v_readlane_b32 s11, v93, 34
	v_fmac_f32_e32 v92, s100, v47
	v_readlane_b32 s100, v93, 35
	v_fmac_f32_e32 v81, s101, v42
	v_readlane_b32 s101, v93, 36
	v_fmac_f32_e32 v92, s10, v43
	v_readlane_b32 s10, v93, 37
	v_fmac_f32_e32 v81, s11, v40
	v_fmac_f32_e32 v92, s100, v41
	v_fmac_f32_e32 v81, s101, v36
	v_fmac_f32_e32 v92, s10, v37
	v_add_f32_e32 v81, v81, v92
	s_waitcnt lgkmcnt(12)
; __device__ __forceinline__ void gd_prep_item(CArgs* a, LAS unsigned char* lds, int l, int item) {
;     ...
;         for (int t = 1; t < 64; ++t) { float s0 = 0.f, s1 = 0.f;
; #pragma unroll
;             for (int sI = 0; sI < t; ++sI) { const float cf = __builtin_bit_cast(float, __builtin_amdgcn_readlane(__builtin_bit_cast(int, nrow[t]), sI)); if (sI & 1) s1 += cf * x[sI]; else s0 += cf * x[sI]; }
;             x[t] -= s0 + s1; }
	v_readlane_b32 s11, v90, 0
	v_readlane_b32 s100, v90, 1
	v_readlane_b32 s101, v90, 2
	v_readlane_b32 s10, v90, 3
	v_sub_f32_e32 v34, v34, v81
	v_fma_f32 v81, v5, s11, 0
	v_readlane_b32 s11, v90, 4
	v_fma_f32 v92, v4, s100, 0
	v_readlane_b32 s100, v90, 5
	v_fmac_f32_e32 v81, s101, v124
	v_readlane_b32 s101, v90, 6
	v_fmac_f32_e32 v92, s10, v71
	v_readlane_b32 s10, v90, 7
	v_fmac_f32_e32 v81, s11, v70
	v_readlane_b32 s11, v90, 8
	v_fmac_f32_e32 v92, s100, v74
	v_readlane_b32 s100, v90, 9
	v_fmac_f32_e32 v81, s101, v75
	v_readlane_b32 s101, v90, 10
	v_fmac_f32_e32 v92, s10, v80
	v_readlane_b32 s10, v90, 11
	v_fmac_f32_e32 v81, s11, v78
	v_readlane_b32 s11, v90, 12
	v_fmac_f32_e32 v92, s100, v79
	v_readlane_b32 s100, v90, 13
	v_fmac_f32_e32 v81, s101, v76
	v_readlane_b32 s101, v90, 14
	v_fmac_f32_e32 v92, s10, v77
	v_readlane_b32 s10, v90, 15
	v_fmac_f32_e32 v81, s11, v72
	v_readlane_b32 s11, v90, 16
	v_fmac_f32_e32 v92, s100, v73
	v_readlane_b32 s100, v90, 17
	v_fmac_f32_e32 v81, s101, v66
	v_readlane_b32 s101, v90, 18
	v_fmac_f32_e32 v92, s10, v67
	v_readlane_b32 s10, v90, 19
	v_fmac_f32_e32 v81, s11, v64
	v_readlane_b32 s11, v90, 20
	v_fmac_f32_e32 v92, s100, v65
	v_readlane_b32 s100, v90, 21
	v_fmac_f32_e32 v81, s101, v62
	v_readlane_b32 s101, v90, 22
	v_fmac_f32_e32 v92, s10, v63
	v_readlane_b32 s10, v90, 23
	v_fmac_f32_e32 v81, s11, v60
	v_readlane_b32 s11, v90, 24
	v_fmac_f32_e32 v92, s100, v61
	v_readlane_b32 s100, v90, 25
	v_fmac_f32_e32 v81, s101, v56
	v_readlane_b32 s101, v90, 26
	v_fmac_f32_e32 v92, s10, v57
	v_readlane_b32 s10, v90, 27
	v_fmac_f32_e32 v81, s11, v54
	v_readlane_b32 s11, v90, 28
	v_fmac_f32_e32 v92, s100, v55
	v_readlane_b32 s100, v90, 29
	v_fmac_f32_e32 v81, s101, v52
	v_readlane_b32 s101, v90, 30
	v_fmac_f32_e32 v92, s10, v53
	v_readlane_b32 s10, v90, 31
	v_fmac_f32_e32 v81, s11, v48
	v_readlane_b32 s11, v90, 32
	v_fmac_f32_e32 v92, s100, v49
	v_readlane_b32 s100, v90, 33
	v_fmac_f32_e32 v81, s101, v46
	v_readlane_b32 s101, v90, 34
	v_fmac_f32_e32 v92, s10, v47
	v_readlane_b32 s10, v90, 35
	v_fmac_f32_e32 v81, s11, v42
	v_readlane_b32 s11, v90, 36
	v_fmac_f32_e32 v92, s100, v43
	v_readlane_b32 s100, v90, 37
	v_fmac_f32_e32 v81, s101, v40
	v_readlane_b32 s101, v90, 38
	v_fmac_f32_e32 v92, s10, v41
	v_readlane_b32 s10, v91, 0
	v_fmac_f32_e32 v81, s11, v36
	v_readlane_b32 s11, v91, 1
	v_fmac_f32_e32 v92, s100, v37
	v_readlane_b32 s100, v91, 2
	v_fmac_f32_e32 v81, s101, v34
	v_readlane_b32 s101, v91, 3
	v_add_f32_e32 v81, v92, v81
	v_sub_f32_e32 v35, v35, v81
	v_fma_f32 v81, v5, s10, 0
	v_readlane_b32 s10, v91, 4
	v_fma_f32 v90, v4, s11, 0
	v_readlane_b32 s11, v91, 5
	v_fmac_f32_e32 v81, s100, v124
	v_readlane_b32 s100, v91, 6
	v_fmac_f32_e32 v90, s101, v71
	v_readlane_b32 s101, v91, 7
	v_fmac_f32_e32 v81, s10, v70
	v_readlane_b32 s10, v91, 8
	v_fmac_f32_e32 v90, s11, v74
	v_readlane_b32 s11, v91, 9
	v_fmac_f32_e32 v81, s100, v75
	v_readlane_b32 s100, v91, 10
	v_fmac_f32_e32 v90, s101, v80
	v_readlane_b32 s101, v91, 11
	v_fmac_f32_e32 v81, s10, v78
	v_readlane_b32 s10, v91, 12
	v_fmac_f32_e32 v90, s11, v79
	v_readlane_b32 s11, v91, 13
	v_fmac_f32_e32 v81, s100, v76
	v_readlane_b32 s100, v91, 14
	v_fmac_f32_e32 v90, s101, v77
	v_readlane_b32 s101, v91, 15
	v_fmac_f32_e32 v81, s10, v72
	v_readlane_b32 s10, v91, 16
	v_fmac_f32_e32 v90, s11, v73
	v_readlane_b32 s11, v91, 17
	v_fmac_f32_e32 v81, s100, v66
	v_readlane_b32 s100, v91, 18
	v_fmac_f32_e32 v90, s101, v67
	v_readlane_b32 s101, v91, 19
	v_fmac_f32_e32 v81, s10, v64
	v_readlane_b32 s10, v91, 20
	v_fmac_f32_e32 v90, s11, v65
	v_readlane_b32 s11, v91, 21
	v_fmac_f32_e32 v81, s100, v62
	v_readlane_b32 s100, v91, 22
	v_fmac_f32_e32 v90, s101, v63
	v_readlane_b32 s101, v91, 23
	v_fmac_f32_e32 v81, s10, v60
	v_readlane_b32 s10, v91, 24
	v_fmac_f32_e32 v90, s11, v61
	v_readlane_b32 s11, v91, 25
	v_fmac_f32_e32 v81, s100, v56
	v_readlane_b32 s100, v91, 26
	v_fmac_f32_e32 v90, s101, v57
	v_readlane_b32 s101, v91, 27
	v_fmac_f32_e32 v81, s10, v54
	v_readlane_b32 s10, v91, 28
	v_fmac_f32_e32 v90, s11, v55
	v_readlane_b32 s11, v91, 29
	v_fmac_f32_e32 v81, s100, v52
	v_readlane_b32 s100, v91, 30
	v_fmac_f32_e32 v90, s101, v53
	v_readlane_b32 s101, v91, 31
	v_fmac_f32_e32 v81, s10, v48
	v_readlane_b32 s10, v91, 32
	v_fmac_f32_e32 v90, s11, v49
	v_readlane_b32 s11, v91, 33
	v_fmac_f32_e32 v81, s100, v46
	v_readlane_b32 s100, v91, 34
	v_fmac_f32_e32 v90, s101, v47
	v_readlane_b32 s101, v91, 35
	v_fmac_f32_e32 v81, s10, v42
	v_readlane_b32 s10, v91, 36
	v_fmac_f32_e32 v90, s11, v43
	v_readlane_b32 s11, v91, 37
	v_fmac_f32_e32 v81, s100, v40
	v_readlane_b32 s100, v91, 38
	v_fmac_f32_e32 v90, s101, v41
	v_readlane_b32 s101, v91, 39
	v_fmac_f32_e32 v81, s10, v36
	v_fmac_f32_e32 v90, s11, v37
	v_fmac_f32_e32 v81, s100, v34
	v_fmac_f32_e32 v90, s101, v35
	v_add_f32_e32 v81, v81, v90
	s_waitcnt lgkmcnt(11)
; __device__ __forceinline__ void gd_prep_item(CArgs* a, LAS unsigned char* lds, int l, int item) {
;     ...
;         for (int t = 1; t < 64; ++t) { float s0 = 0.f, s1 = 0.f;
; #pragma unroll
;             for (int sI = 0; sI < t; ++sI) { const float cf = __builtin_bit_cast(float, __builtin_amdgcn_readlane(__builtin_bit_cast(int, nrow[t]), sI)); if (sI & 1) s1 += cf * x[sI]; else s0 += cf * x[sI]; }
;             x[t] -= s0 + s1; }
	v_readlane_b32 s10, v88, 0
	v_readlane_b32 s11, v88, 1
	v_readlane_b32 s100, v88, 2
	v_readlane_b32 s101, v88, 3
	v_sub_f32_e32 v30, v30, v81
	v_fma_f32 v81, v5, s10, 0
	v_readlane_b32 s10, v88, 4
	v_fma_f32 v90, v4, s11, 0
	v_readlane_b32 s11, v88, 5
	v_fmac_f32_e32 v81, s100, v124
	v_readlane_b32 s100, v88, 6
	v_fmac_f32_e32 v90, s101, v71
	v_readlane_b32 s101, v88, 7
	v_fmac_f32_e32 v81, s10, v70
	v_readlane_b32 s10, v88, 8
	v_fmac_f32_e32 v90, s11, v74
	v_readlane_b32 s11, v88, 9
	v_fmac_f32_e32 v81, s100, v75
	v_readlane_b32 s100, v88, 10
	v_fmac_f32_e32 v90, s101, v80
	v_readlane_b32 s101, v88, 11
	v_fmac_f32_e32 v81, s10, v78
	v_readlane_b32 s10, v88, 12
	v_fmac_f32_e32 v90, s11, v79
	v_readlane_b32 s11, v88, 13
	v_fmac_f32_e32 v81, s100, v76
	v_readlane_b32 s100, v88, 14
	v_fmac_f32_e32 v90, s101, v77
	v_readlane_b32 s101, v88, 15
	v_fmac_f32_e32 v81, s10, v72
	v_readlane_b32 s10, v88, 16
	v_fmac_f32_e32 v90, s11, v73
	v_readlane_b32 s11, v88, 17
	v_fmac_f32_e32 v81, s100, v66
	v_readlane_b32 s100, v88, 18
	v_fmac_f32_e32 v90, s101, v67
	v_readlane_b32 s101, v88, 19
	v_fmac_f32_e32 v81, s10, v64
	v_readlane_b32 s10, v88, 20
	v_fmac_f32_e32 v90, s11, v65
	v_readlane_b32 s11, v88, 21
	v_fmac_f32_e32 v81, s100, v62
	v_readlane_b32 s100, v88, 22
	v_fmac_f32_e32 v90, s101, v63
	v_readlane_b32 s101, v88, 23
	v_fmac_f32_e32 v81, s10, v60
	v_readlane_b32 s10, v88, 24
	v_fmac_f32_e32 v90, s11, v61
	v_readlane_b32 s11, v88, 25
	v_fmac_f32_e32 v81, s100, v56
	v_readlane_b32 s100, v88, 26
	v_fmac_f32_e32 v90, s101, v57
	v_readlane_b32 s101, v88, 27
	v_fmac_f32_e32 v81, s10, v54
	v_readlane_b32 s10, v88, 28
	v_fmac_f32_e32 v90, s11, v55
	v_readlane_b32 s11, v88, 29
	v_fmac_f32_e32 v81, s100, v52
	v_readlane_b32 s100, v88, 30
	v_fmac_f32_e32 v90, s101, v53
	v_readlane_b32 s101, v88, 31
	v_fmac_f32_e32 v81, s10, v48
	v_readlane_b32 s10, v88, 32
	v_fmac_f32_e32 v90, s11, v49
	v_readlane_b32 s11, v88, 33
	v_fmac_f32_e32 v81, s100, v46
	v_readlane_b32 s100, v88, 34
	v_fmac_f32_e32 v90, s101, v47
	v_readlane_b32 s101, v88, 35
	v_fmac_f32_e32 v81, s10, v42
	v_readlane_b32 s10, v88, 36
	v_fmac_f32_e32 v90, s11, v43
	v_readlane_b32 s11, v88, 37
	v_fmac_f32_e32 v81, s100, v40
	v_readlane_b32 s100, v88, 38
	v_fmac_f32_e32 v90, s101, v41
	v_readlane_b32 s101, v88, 39
	v_fmac_f32_e32 v81, s10, v36
	v_readlane_b32 s10, v88, 40
	v_fmac_f32_e32 v90, s11, v37
	v_readlane_b32 s11, v89, 0
	v_fmac_f32_e32 v81, s100, v34
	v_readlane_b32 s100, v89, 1
	v_fmac_f32_e32 v90, s101, v35
	v_readlane_b32 s101, v89, 2
	v_fmac_f32_e32 v81, s10, v30
	v_readlane_b32 s10, v89, 3
	v_add_f32_e32 v81, v90, v81
	v_sub_f32_e32 v31, v31, v81
	v_fma_f32 v81, v5, s11, 0
	v_readlane_b32 s11, v89, 4
	v_fma_f32 v88, v4, s100, 0
	v_readlane_b32 s100, v89, 5
	v_fmac_f32_e32 v81, s101, v124
	v_readlane_b32 s101, v89, 6
	v_fmac_f32_e32 v88, s10, v71
	v_readlane_b32 s10, v89, 7
	v_fmac_f32_e32 v81, s11, v70
	v_readlane_b32 s11, v89, 8
	v_fmac_f32_e32 v88, s100, v74
	v_readlane_b32 s100, v89, 9
	v_fmac_f32_e32 v81, s101, v75
	v_readlane_b32 s101, v89, 10
	v_fmac_f32_e32 v88, s10, v80
	v_readlane_b32 s10, v89, 11
	v_fmac_f32_e32 v81, s11, v78
	v_readlane_b32 s11, v89, 12
	v_fmac_f32_e32 v88, s100, v79
	v_readlane_b32 s100, v89, 13
	v_fmac_f32_e32 v81, s101, v76
	v_readlane_b32 s101, v89, 14
	v_fmac_f32_e32 v88, s10, v77
	v_readlane_b32 s10, v89, 15
	v_fmac_f32_e32 v81, s11, v72
	v_readlane_b32 s11, v89, 16
	v_fmac_f32_e32 v88, s100, v73
	v_readlane_b32 s100, v89, 17
	v_fmac_f32_e32 v81, s101, v66
	v_readlane_b32 s101, v89, 18
	v_fmac_f32_e32 v88, s10, v67
	v_readlane_b32 s10, v89, 19
	v_fmac_f32_e32 v81, s11, v64
	v_readlane_b32 s11, v89, 20
	v_fmac_f32_e32 v88, s100, v65
	v_readlane_b32 s100, v89, 21
	v_fmac_f32_e32 v81, s101, v62
	v_readlane_b32 s101, v89, 22
	v_fmac_f32_e32 v88, s10, v63
	v_readlane_b32 s10, v89, 23
	v_fmac_f32_e32 v81, s11, v60
	v_readlane_b32 s11, v89, 24
	v_fmac_f32_e32 v88, s100, v61
	v_readlane_b32 s100, v89, 25
	v_fmac_f32_e32 v81, s101, v56
	v_readlane_b32 s101, v89, 26
	v_fmac_f32_e32 v88, s10, v57
	v_readlane_b32 s10, v89, 27
	v_fmac_f32_e32 v81, s11, v54
	v_readlane_b32 s11, v89, 28
	v_fmac_f32_e32 v88, s100, v55
	v_readlane_b32 s100, v89, 29
	v_fmac_f32_e32 v81, s101, v52
	v_readlane_b32 s101, v89, 30
	v_fmac_f32_e32 v88, s10, v53
	v_readlane_b32 s10, v89, 31
	v_fmac_f32_e32 v81, s11, v48
	v_readlane_b32 s11, v89, 32
	v_fmac_f32_e32 v88, s100, v49
	v_readlane_b32 s100, v89, 33
	v_fmac_f32_e32 v81, s101, v46
	v_readlane_b32 s101, v89, 34
	v_fmac_f32_e32 v88, s10, v47
	v_readlane_b32 s10, v89, 35
	v_fmac_f32_e32 v81, s11, v42
	v_readlane_b32 s11, v89, 36
	v_fmac_f32_e32 v88, s100, v43
	v_readlane_b32 s100, v89, 37
	v_fmac_f32_e32 v81, s101, v40
	v_readlane_b32 s101, v89, 38
	v_fmac_f32_e32 v88, s10, v41
	v_readlane_b32 s10, v89, 39
	v_fmac_f32_e32 v81, s11, v36
	v_readlane_b32 s11, v89, 40
	v_fmac_f32_e32 v88, s100, v37
	v_readlane_b32 s100, v89, 41
	v_fmac_f32_e32 v81, s101, v34
	v_fmac_f32_e32 v88, s10, v35
	v_fmac_f32_e32 v81, s11, v30
	v_fmac_f32_e32 v88, s100, v31
	v_add_f32_e32 v81, v81, v88
	s_waitcnt lgkmcnt(10)
; __device__ __forceinline__ void gd_prep_item(CArgs* a, LAS unsigned char* lds, int l, int item) {
;     ...
;         for (int t = 1; t < 64; ++t) { float s0 = 0.f, s1 = 0.f;
; #pragma unroll
;             for (int sI = 0; sI < t; ++sI) { const float cf = __builtin_bit_cast(float, __builtin_amdgcn_readlane(__builtin_bit_cast(int, nrow[t]), sI)); if (sI & 1) s1 += cf * x[sI]; else s0 += cf * x[sI]; }
;             x[t] -= s0 + s1; }
	v_readlane_b32 s101, v86, 0
	v_readlane_b32 s10, v86, 1
	v_readlane_b32 s11, v86, 2
	v_readlane_b32 s100, v86, 3
	v_sub_f32_e32 v26, v26, v81
	v_fma_f32 v81, v5, s101, 0
	v_readlane_b32 s101, v86, 4
	v_fma_f32 v88, v4, s10, 0
	v_readlane_b32 s10, v86, 5
	v_fmac_f32_e32 v81, s11, v124
	v_readlane_b32 s11, v86, 6
	v_fmac_f32_e32 v88, s100, v71
	v_readlane_b32 s100, v86, 7
	v_fmac_f32_e32 v81, s101, v70
	v_readlane_b32 s101, v86, 8
	v_fmac_f32_e32 v88, s10, v74
	v_readlane_b32 s10, v86, 9
	v_fmac_f32_e32 v81, s11, v75
	v_readlane_b32 s11, v86, 10
	v_fmac_f32_e32 v88, s100, v80
	v_readlane_b32 s100, v86, 11
	v_fmac_f32_e32 v81, s101, v78
	v_readlane_b32 s101, v86, 12
	v_fmac_f32_e32 v88, s10, v79
	v_readlane_b32 s10, v86, 13
	v_fmac_f32_e32 v81, s11, v76
	v_readlane_b32 s11, v86, 14
	v_fmac_f32_e32 v88, s100, v77
	v_readlane_b32 s100, v86, 15
	v_fmac_f32_e32 v81, s101, v72
	v_readlane_b32 s101, v86, 16
	v_fmac_f32_e32 v88, s10, v73
	v_readlane_b32 s10, v86, 17
	v_fmac_f32_e32 v81, s11, v66
	v_readlane_b32 s11, v86, 18
	v_fmac_f32_e32 v88, s100, v67
	v_readlane_b32 s100, v86, 19
	v_fmac_f32_e32 v81, s101, v64
	v_readlane_b32 s101, v86, 20
	v_fmac_f32_e32 v88, s10, v65
	v_readlane_b32 s10, v86, 21
	v_fmac_f32_e32 v81, s11, v62
	v_readlane_b32 s11, v86, 22
	v_fmac_f32_e32 v88, s100, v63
	v_readlane_b32 s100, v86, 23
	v_fmac_f32_e32 v81, s101, v60
	v_readlane_b32 s101, v86, 24
	v_fmac_f32_e32 v88, s10, v61
	v_readlane_b32 s10, v86, 25
	v_fmac_f32_e32 v81, s11, v56
	v_readlane_b32 s11, v86, 26
	v_fmac_f32_e32 v88, s100, v57
	v_readlane_b32 s100, v86, 27
	v_fmac_f32_e32 v81, s101, v54
	v_readlane_b32 s101, v86, 28
	v_fmac_f32_e32 v88, s10, v55
	v_readlane_b32 s10, v86, 29
	v_fmac_f32_e32 v81, s11, v52
	v_readlane_b32 s11, v86, 30
	v_fmac_f32_e32 v88, s100, v53
	v_readlane_b32 s100, v86, 31
	v_fmac_f32_e32 v81, s101, v48
	v_readlane_b32 s101, v86, 32
	v_fmac_f32_e32 v88, s10, v49
	v_readlane_b32 s10, v86, 33
	v_fmac_f32_e32 v81, s11, v46
	v_readlane_b32 s11, v86, 34
	v_fmac_f32_e32 v88, s100, v47
	v_readlane_b32 s100, v86, 35
	v_fmac_f32_e32 v81, s101, v42
	v_readlane_b32 s101, v86, 36
	v_fmac_f32_e32 v88, s10, v43
	v_readlane_b32 s10, v86, 37
	v_fmac_f32_e32 v81, s11, v40
	v_readlane_b32 s11, v86, 38
	v_fmac_f32_e32 v88, s100, v41
	v_readlane_b32 s100, v86, 39
	v_fmac_f32_e32 v81, s101, v36
	v_readlane_b32 s101, v86, 40
	v_fmac_f32_e32 v88, s10, v37
	v_readlane_b32 s10, v86, 41
	v_fmac_f32_e32 v81, s11, v34
	v_readlane_b32 s11, v86, 42
	v_fmac_f32_e32 v88, s100, v35
	v_readlane_b32 s100, v87, 0
	v_fmac_f32_e32 v81, s101, v30
	v_readlane_b32 s101, v87, 1
	v_fmac_f32_e32 v88, s10, v31
	v_readlane_b32 s10, v87, 2
	v_fmac_f32_e32 v81, s11, v26
	v_readlane_b32 s11, v87, 3
	v_add_f32_e32 v81, v88, v81
	v_sub_f32_e32 v27, v27, v81
	v_fma_f32 v81, v5, s100, 0
	v_readlane_b32 s100, v87, 4
	v_fma_f32 v86, v4, s101, 0
	v_readlane_b32 s101, v87, 5
	v_fmac_f32_e32 v81, s10, v124
	v_readlane_b32 s10, v87, 6
	v_fmac_f32_e32 v86, s11, v71
	v_readlane_b32 s11, v87, 7
	v_fmac_f32_e32 v81, s100, v70
	v_readlane_b32 s100, v87, 8
	v_fmac_f32_e32 v86, s101, v74
	v_readlane_b32 s101, v87, 9
	v_fmac_f32_e32 v81, s10, v75
	v_readlane_b32 s10, v87, 10
	v_fmac_f32_e32 v86, s11, v80
	v_readlane_b32 s11, v87, 11
	v_fmac_f32_e32 v81, s100, v78
	v_readlane_b32 s100, v87, 12
	v_fmac_f32_e32 v86, s101, v79
	v_readlane_b32 s101, v87, 13
	v_fmac_f32_e32 v81, s10, v76
	v_readlane_b32 s10, v87, 14
	v_fmac_f32_e32 v86, s11, v77
	v_readlane_b32 s11, v87, 15
	v_fmac_f32_e32 v81, s100, v72
	v_readlane_b32 s100, v87, 16
	v_fmac_f32_e32 v86, s101, v73
	v_readlane_b32 s101, v87, 17
	v_fmac_f32_e32 v81, s10, v66
	v_readlane_b32 s10, v87, 18
	v_fmac_f32_e32 v86, s11, v67
	v_readlane_b32 s11, v87, 19
	v_fmac_f32_e32 v81, s100, v64
	v_readlane_b32 s100, v87, 20
	v_fmac_f32_e32 v86, s101, v65
	v_readlane_b32 s101, v87, 21
	v_fmac_f32_e32 v81, s10, v62
	v_readlane_b32 s10, v87, 22
	v_fmac_f32_e32 v86, s11, v63
	v_readlane_b32 s11, v87, 23
	v_fmac_f32_e32 v81, s100, v60
	v_readlane_b32 s100, v87, 24
	v_fmac_f32_e32 v86, s101, v61
	v_readlane_b32 s101, v87, 25
	v_fmac_f32_e32 v81, s10, v56
	v_readlane_b32 s10, v87, 26
	v_fmac_f32_e32 v86, s11, v57
	v_readlane_b32 s11, v87, 27
	v_fmac_f32_e32 v81, s100, v54
	v_readlane_b32 s100, v87, 28
	v_fmac_f32_e32 v86, s101, v55
	v_readlane_b32 s101, v87, 29
	v_fmac_f32_e32 v81, s10, v52
	v_readlane_b32 s10, v87, 30
	v_fmac_f32_e32 v86, s11, v53
	v_readlane_b32 s11, v87, 31
	v_fmac_f32_e32 v81, s100, v48
	v_readlane_b32 s100, v87, 32
	v_fmac_f32_e32 v86, s101, v49
	v_readlane_b32 s101, v87, 33
	v_fmac_f32_e32 v81, s10, v46
	v_readlane_b32 s10, v87, 34
	v_fmac_f32_e32 v86, s11, v47
	v_readlane_b32 s11, v87, 35
	v_fmac_f32_e32 v81, s100, v42
	v_readlane_b32 s100, v87, 36
	v_fmac_f32_e32 v86, s101, v43
	v_readlane_b32 s101, v87, 37
	v_fmac_f32_e32 v81, s10, v40
	v_readlane_b32 s10, v87, 38
	v_fmac_f32_e32 v86, s11, v41
	v_readlane_b32 s11, v87, 39
	v_fmac_f32_e32 v81, s100, v36
	v_readlane_b32 s100, v87, 40
	v_fmac_f32_e32 v86, s101, v37
	v_readlane_b32 s101, v87, 41
	v_fmac_f32_e32 v81, s10, v34
	v_readlane_b32 s10, v87, 42
	v_fmac_f32_e32 v86, s11, v35
	v_readlane_b32 s11, v87, 43
	v_fmac_f32_e32 v81, s100, v30
	v_fmac_f32_e32 v86, s101, v31
	v_fmac_f32_e32 v81, s10, v26
	v_fmac_f32_e32 v86, s11, v27
	v_add_f32_e32 v81, v81, v86
	s_waitcnt lgkmcnt(9)
; __device__ __forceinline__ void gd_prep_item(CArgs* a, LAS unsigned char* lds, int l, int item) {
;     ...
;         for (int t = 1; t < 64; ++t) { float s0 = 0.f, s1 = 0.f;
; #pragma unroll
;             for (int sI = 0; sI < t; ++sI) { const float cf = __builtin_bit_cast(float, __builtin_amdgcn_readlane(__builtin_bit_cast(int, nrow[t]), sI)); if (sI & 1) s1 += cf * x[sI]; else s0 += cf * x[sI]; }
;             x[t] -= s0 + s1; }
	v_readlane_b32 s100, v84, 0
	v_readlane_b32 s101, v84, 1
	v_readlane_b32 s10, v84, 2
	v_readlane_b32 s11, v84, 3
	v_sub_f32_e32 v24, v24, v81
	v_fma_f32 v81, v5, s100, 0
	v_readlane_b32 s100, v84, 4
	v_fma_f32 v86, v4, s101, 0
	v_readlane_b32 s101, v84, 5
	v_fmac_f32_e32 v81, s10, v124
	v_readlane_b32 s10, v84, 6
	v_fmac_f32_e32 v86, s11, v71
	v_readlane_b32 s11, v84, 7
	v_fmac_f32_e32 v81, s100, v70
	v_readlane_b32 s100, v84, 8
	v_fmac_f32_e32 v86, s101, v74
	v_readlane_b32 s101, v84, 9
	v_fmac_f32_e32 v81, s10, v75
	v_readlane_b32 s10, v84, 10
	v_fmac_f32_e32 v86, s11, v80
	v_readlane_b32 s11, v84, 11
	v_fmac_f32_e32 v81, s100, v78
	v_readlane_b32 s100, v84, 12
	v_fmac_f32_e32 v86, s101, v79
	v_readlane_b32 s101, v84, 13
	v_fmac_f32_e32 v81, s10, v76
	v_readlane_b32 s10, v84, 14
	v_fmac_f32_e32 v86, s11, v77
	v_readlane_b32 s11, v84, 15
	v_fmac_f32_e32 v81, s100, v72
	v_readlane_b32 s100, v84, 16
	v_fmac_f32_e32 v86, s101, v73
	v_readlane_b32 s101, v84, 17
	v_fmac_f32_e32 v81, s10, v66
	v_readlane_b32 s10, v84, 18
	v_fmac_f32_e32 v86, s11, v67
	v_readlane_b32 s11, v84, 19
	v_fmac_f32_e32 v81, s100, v64
	v_readlane_b32 s100, v84, 20
	v_fmac_f32_e32 v86, s101, v65
	v_readlane_b32 s101, v84, 21
	v_fmac_f32_e32 v81, s10, v62
	v_readlane_b32 s10, v84, 22
	v_fmac_f32_e32 v86, s11, v63
	v_readlane_b32 s11, v84, 23
	v_fmac_f32_e32 v81, s100, v60
	v_readlane_b32 s100, v84, 24
	v_fmac_f32_e32 v86, s101, v61
	v_readlane_b32 s101, v84, 25
	v_fmac_f32_e32 v81, s10, v56
	v_readlane_b32 s10, v84, 26
	v_fmac_f32_e32 v86, s11, v57
	v_readlane_b32 s11, v84, 27
	v_fmac_f32_e32 v81, s100, v54
	v_readlane_b32 s100, v84, 28
	v_fmac_f32_e32 v86, s101, v55
	v_readlane_b32 s101, v84, 29
	v_fmac_f32_e32 v81, s10, v52
	v_readlane_b32 s10, v84, 30
	v_fmac_f32_e32 v86, s11, v53
	v_readlane_b32 s11, v84, 31
	v_fmac_f32_e32 v81, s100, v48
	v_readlane_b32 s100, v84, 32
	v_fmac_f32_e32 v86, s101, v49
	v_readlane_b32 s101, v84, 33
	v_fmac_f32_e32 v81, s10, v46
	v_readlane_b32 s10, v84, 34
	v_fmac_f32_e32 v86, s11, v47
	v_readlane_b32 s11, v84, 35
	v_fmac_f32_e32 v81, s100, v42
	v_readlane_b32 s100, v84, 36
	v_fmac_f32_e32 v86, s101, v43
	v_readlane_b32 s101, v84, 37
	v_fmac_f32_e32 v81, s10, v40
	v_readlane_b32 s10, v84, 38
	v_fmac_f32_e32 v86, s11, v41
	v_readlane_b32 s11, v84, 39
	v_fmac_f32_e32 v81, s100, v36
	v_readlane_b32 s100, v84, 40
	v_fmac_f32_e32 v86, s101, v37
	v_readlane_b32 s101, v84, 41
	v_fmac_f32_e32 v81, s10, v34
	v_readlane_b32 s10, v84, 42
	v_fmac_f32_e32 v86, s11, v35
	v_readlane_b32 s11, v84, 43
	v_fmac_f32_e32 v81, s100, v30
	v_readlane_b32 s100, v84, 44
	v_fmac_f32_e32 v86, s101, v31
	v_readlane_b32 s101, v85, 0
	v_fmac_f32_e32 v81, s10, v26
	v_readlane_b32 s10, v85, 1
	v_fmac_f32_e32 v86, s11, v27
	v_readlane_b32 s11, v85, 2
	v_fmac_f32_e32 v81, s100, v24
	v_readlane_b32 s100, v85, 3
	v_add_f32_e32 v81, v86, v81
	v_sub_f32_e32 v25, v25, v81
	v_fma_f32 v81, v5, s101, 0
	v_readlane_b32 s101, v85, 4
	v_fma_f32 v84, v4, s10, 0
	v_readlane_b32 s10, v85, 5
	v_fmac_f32_e32 v81, s11, v124
	v_readlane_b32 s11, v85, 6
	v_fmac_f32_e32 v84, s100, v71
	v_readlane_b32 s100, v85, 7
	v_fmac_f32_e32 v81, s101, v70
	v_readlane_b32 s101, v85, 8
	v_fmac_f32_e32 v84, s10, v74
	v_readlane_b32 s10, v85, 9
	v_fmac_f32_e32 v81, s11, v75
	v_readlane_b32 s11, v85, 10
	v_fmac_f32_e32 v84, s100, v80
	v_readlane_b32 s100, v85, 11
	v_fmac_f32_e32 v81, s101, v78
	v_readlane_b32 s101, v85, 12
	v_fmac_f32_e32 v84, s10, v79
	v_readlane_b32 s10, v85, 13
	v_fmac_f32_e32 v81, s11, v76
	v_readlane_b32 s11, v85, 14
	v_fmac_f32_e32 v84, s100, v77
	v_readlane_b32 s100, v85, 15
	v_fmac_f32_e32 v81, s101, v72
	v_readlane_b32 s101, v85, 16
	v_fmac_f32_e32 v84, s10, v73
	v_readlane_b32 s10, v85, 17
	v_fmac_f32_e32 v81, s11, v66
	v_readlane_b32 s11, v85, 18
	v_fmac_f32_e32 v84, s100, v67
	v_readlane_b32 s100, v85, 19
	v_fmac_f32_e32 v81, s101, v64
	v_readlane_b32 s101, v85, 20
	v_fmac_f32_e32 v84, s10, v65
	v_readlane_b32 s10, v85, 21
	v_fmac_f32_e32 v81, s11, v62
	v_readlane_b32 s11, v85, 22
	v_fmac_f32_e32 v84, s100, v63
	v_readlane_b32 s100, v85, 23
	v_fmac_f32_e32 v81, s101, v60
	v_readlane_b32 s101, v85, 24
	v_fmac_f32_e32 v84, s10, v61
	v_readlane_b32 s10, v85, 25
	v_fmac_f32_e32 v81, s11, v56
	v_readlane_b32 s11, v85, 26
	v_fmac_f32_e32 v84, s100, v57
	v_readlane_b32 s100, v85, 27
	v_fmac_f32_e32 v81, s101, v54
	v_readlane_b32 s101, v85, 28
	v_fmac_f32_e32 v84, s10, v55
	v_readlane_b32 s10, v85, 29
	v_fmac_f32_e32 v81, s11, v52
	v_readlane_b32 s11, v85, 30
	v_fmac_f32_e32 v84, s100, v53
	v_readlane_b32 s100, v85, 31
	v_fmac_f32_e32 v81, s101, v48
	v_readlane_b32 s101, v85, 32
	v_fmac_f32_e32 v84, s10, v49
	v_readlane_b32 s10, v85, 33
	v_fmac_f32_e32 v81, s11, v46
	v_readlane_b32 s11, v85, 34
	v_fmac_f32_e32 v84, s100, v47
	v_readlane_b32 s100, v85, 35
	v_fmac_f32_e32 v81, s101, v42
	v_readlane_b32 s101, v85, 36
	v_fmac_f32_e32 v84, s10, v43
	v_readlane_b32 s10, v85, 37
	v_fmac_f32_e32 v81, s11, v40
	v_readlane_b32 s11, v85, 38
	v_fmac_f32_e32 v84, s100, v41
	v_readlane_b32 s100, v85, 39
	v_fmac_f32_e32 v81, s101, v36
	v_readlane_b32 s101, v85, 40
	v_fmac_f32_e32 v84, s10, v37
	v_readlane_b32 s10, v85, 41
	v_fmac_f32_e32 v81, s11, v34
	v_readlane_b32 s11, v85, 42
	v_fmac_f32_e32 v84, s100, v35
	v_readlane_b32 s100, v85, 43
	v_fmac_f32_e32 v81, s101, v30
	v_readlane_b32 s101, v85, 44
	v_fmac_f32_e32 v84, s10, v31
	v_readlane_b32 s10, v85, 45
	v_fmac_f32_e32 v81, s11, v26
	v_fmac_f32_e32 v84, s100, v27
	v_fmac_f32_e32 v81, s101, v24
	v_fmac_f32_e32 v84, s10, v25
	v_add_f32_e32 v81, v81, v84
	s_waitcnt lgkmcnt(8)
; __device__ __forceinline__ void gd_prep_item(CArgs* a, LAS unsigned char* lds, int l, int item) {
;     ...
;         for (int t = 1; t < 64; ++t) { float s0 = 0.f, s1 = 0.f;
; #pragma unroll
;             for (int sI = 0; sI < t; ++sI) { const float cf = __builtin_bit_cast(float, __builtin_amdgcn_readlane(__builtin_bit_cast(int, nrow[t]), sI)); if (sI & 1) s1 += cf * x[sI]; else s0 += cf * x[sI]; }
;             x[t] -= s0 + s1; }
	v_readlane_b32 s11, v82, 0
	v_readlane_b32 s100, v82, 1
	v_readlane_b32 s101, v82, 2
	v_readlane_b32 s10, v82, 3
	v_sub_f32_e32 v20, v20, v81
	v_fma_f32 v81, v5, s11, 0
	v_readlane_b32 s11, v82, 4
	v_fma_f32 v84, v4, s100, 0
	v_readlane_b32 s100, v82, 5
	v_fmac_f32_e32 v81, s101, v124
	v_readlane_b32 s101, v82, 6
	v_fmac_f32_e32 v84, s10, v71
	v_readlane_b32 s10, v82, 7
	v_fmac_f32_e32 v81, s11, v70
	v_readlane_b32 s11, v82, 8
	v_fmac_f32_e32 v84, s100, v74
	v_readlane_b32 s100, v82, 9
	v_fmac_f32_e32 v81, s101, v75
	v_readlane_b32 s101, v82, 10
	v_fmac_f32_e32 v84, s10, v80
	v_readlane_b32 s10, v82, 11
	v_fmac_f32_e32 v81, s11, v78
	v_readlane_b32 s11, v82, 12
	v_fmac_f32_e32 v84, s100, v79
	v_readlane_b32 s100, v82, 13
	v_fmac_f32_e32 v81, s101, v76
	v_readlane_b32 s101, v82, 14
	v_fmac_f32_e32 v84, s10, v77
	v_readlane_b32 s10, v82, 15
	v_fmac_f32_e32 v81, s11, v72
	v_readlane_b32 s11, v82, 16
	v_fmac_f32_e32 v84, s100, v73
	v_readlane_b32 s100, v82, 17
	v_fmac_f32_e32 v81, s101, v66
	v_readlane_b32 s101, v82, 18
	v_fmac_f32_e32 v84, s10, v67
	v_readlane_b32 s10, v82, 19
	v_fmac_f32_e32 v81, s11, v64
	v_readlane_b32 s11, v82, 20
	v_fmac_f32_e32 v84, s100, v65
	v_readlane_b32 s100, v82, 21
	v_fmac_f32_e32 v81, s101, v62
	v_readlane_b32 s101, v82, 22
	v_fmac_f32_e32 v84, s10, v63
	v_readlane_b32 s10, v82, 23
	v_fmac_f32_e32 v81, s11, v60
	v_readlane_b32 s11, v82, 24
	v_fmac_f32_e32 v84, s100, v61
	v_readlane_b32 s100, v82, 25
	v_fmac_f32_e32 v81, s101, v56
	v_readlane_b32 s101, v82, 26
	v_fmac_f32_e32 v84, s10, v57
	v_readlane_b32 s10, v82, 27
	v_fmac_f32_e32 v81, s11, v54
	v_readlane_b32 s11, v82, 28
	v_fmac_f32_e32 v84, s100, v55
	v_readlane_b32 s100, v82, 29
	v_fmac_f32_e32 v81, s101, v52
	v_readlane_b32 s101, v82, 30
	v_fmac_f32_e32 v84, s10, v53
	v_readlane_b32 s10, v82, 31
	v_fmac_f32_e32 v81, s11, v48
	v_readlane_b32 s11, v82, 32
	v_fmac_f32_e32 v84, s100, v49
	v_readlane_b32 s100, v82, 33
	v_fmac_f32_e32 v81, s101, v46
	v_readlane_b32 s101, v82, 34
	v_fmac_f32_e32 v84, s10, v47
	v_readlane_b32 s10, v82, 35
	v_fmac_f32_e32 v81, s11, v42
	v_readlane_b32 s11, v82, 36
	v_fmac_f32_e32 v84, s100, v43
	v_readlane_b32 s100, v82, 37
	v_fmac_f32_e32 v81, s101, v40
	v_readlane_b32 s101, v82, 38
	v_fmac_f32_e32 v84, s10, v41
	v_readlane_b32 s10, v82, 39
	v_fmac_f32_e32 v81, s11, v36
	v_readlane_b32 s11, v82, 40
	v_fmac_f32_e32 v84, s100, v37
	v_readlane_b32 s100, v82, 41
	v_fmac_f32_e32 v81, s101, v34
	v_readlane_b32 s101, v82, 42
	v_fmac_f32_e32 v84, s10, v35
	v_readlane_b32 s10, v82, 43
	v_fmac_f32_e32 v81, s11, v30
	v_readlane_b32 s11, v82, 44
	v_fmac_f32_e32 v84, s100, v31
	v_readlane_b32 s100, v82, 45
	v_fmac_f32_e32 v81, s101, v26
	v_readlane_b32 s101, v82, 46
	v_fmac_f32_e32 v84, s10, v27
	v_readlane_b32 s10, v83, 0
	v_fmac_f32_e32 v81, s11, v24
	v_readlane_b32 s11, v83, 1
	v_fmac_f32_e32 v84, s100, v25
	v_readlane_b32 s100, v83, 2
	v_fmac_f32_e32 v81, s101, v20
	v_readlane_b32 s101, v83, 3
	v_add_f32_e32 v81, v84, v81
	v_sub_f32_e32 v21, v21, v81
	v_fma_f32 v81, v5, s10, 0
	v_readlane_b32 s10, v83, 4
	v_fma_f32 v82, v4, s11, 0
	v_readlane_b32 s11, v83, 5
	v_fmac_f32_e32 v81, s100, v124
	v_readlane_b32 s100, v83, 6
	v_fmac_f32_e32 v82, s101, v71
	v_readlane_b32 s101, v83, 7
	v_fmac_f32_e32 v81, s10, v70
	v_readlane_b32 s10, v83, 8
	v_fmac_f32_e32 v82, s11, v74
	v_readlane_b32 s11, v83, 9
	v_fmac_f32_e32 v81, s100, v75
	v_readlane_b32 s100, v83, 10
	v_fmac_f32_e32 v82, s101, v80
	v_readlane_b32 s101, v83, 11
	v_fmac_f32_e32 v81, s10, v78
	v_readlane_b32 s10, v83, 12
	v_fmac_f32_e32 v82, s11, v79
	v_readlane_b32 s11, v83, 13
	v_fmac_f32_e32 v81, s100, v76
	v_readlane_b32 s100, v83, 14
	v_fmac_f32_e32 v82, s101, v77
	v_readlane_b32 s101, v83, 15
	v_fmac_f32_e32 v81, s10, v72
	v_readlane_b32 s10, v83, 16
	v_fmac_f32_e32 v82, s11, v73
	v_readlane_b32 s11, v83, 17
	v_fmac_f32_e32 v81, s100, v66
	v_readlane_b32 s100, v83, 18
	v_fmac_f32_e32 v82, s101, v67
	v_readlane_b32 s101, v83, 19
	v_fmac_f32_e32 v81, s10, v64
	v_readlane_b32 s10, v83, 20
	v_fmac_f32_e32 v82, s11, v65
	v_readlane_b32 s11, v83, 21
	v_fmac_f32_e32 v81, s100, v62
	v_readlane_b32 s100, v83, 22
	v_fmac_f32_e32 v82, s101, v63
	v_readlane_b32 s101, v83, 23
	v_fmac_f32_e32 v81, s10, v60
	v_readlane_b32 s10, v83, 24
	v_fmac_f32_e32 v82, s11, v61
	v_readlane_b32 s11, v83, 25
	v_fmac_f32_e32 v81, s100, v56
	v_readlane_b32 s100, v83, 26
	v_fmac_f32_e32 v82, s101, v57
	v_readlane_b32 s101, v83, 27
	v_fmac_f32_e32 v81, s10, v54
	v_readlane_b32 s10, v83, 28
	v_fmac_f32_e32 v82, s11, v55
	v_readlane_b32 s11, v83, 29
	v_fmac_f32_e32 v81, s100, v52
	v_readlane_b32 s100, v83, 30
	v_fmac_f32_e32 v82, s101, v53
	v_readlane_b32 s101, v83, 31
	v_fmac_f32_e32 v81, s10, v48
	v_readlane_b32 s10, v83, 32
	v_fmac_f32_e32 v82, s11, v49
	v_readlane_b32 s11, v83, 33
	v_fmac_f32_e32 v81, s100, v46
	v_readlane_b32 s100, v83, 34
	v_fmac_f32_e32 v82, s101, v47
	v_readlane_b32 s101, v83, 35
	v_fmac_f32_e32 v81, s10, v42
	v_readlane_b32 s10, v83, 36
	v_fmac_f32_e32 v82, s11, v43
	v_readlane_b32 s11, v83, 37
	v_fmac_f32_e32 v81, s100, v40
	v_readlane_b32 s100, v83, 38
	v_fmac_f32_e32 v82, s101, v41
	v_readlane_b32 s101, v83, 39
	v_fmac_f32_e32 v81, s10, v36
	v_readlane_b32 s10, v83, 40
	v_fmac_f32_e32 v82, s11, v37
	v_readlane_b32 s11, v83, 41
	v_fmac_f32_e32 v81, s100, v34
	v_readlane_b32 s100, v83, 42
	v_fmac_f32_e32 v82, s101, v35
	v_readlane_b32 s101, v83, 43
	v_fmac_f32_e32 v81, s10, v30
	v_readlane_b32 s10, v83, 44
	v_fmac_f32_e32 v82, s11, v31
	v_readlane_b32 s11, v83, 45
	v_fmac_f32_e32 v81, s100, v26
	v_readlane_b32 s100, v83, 46
	v_fmac_f32_e32 v82, s101, v27
	v_readlane_b32 s101, v83, 47
	v_fmac_f32_e32 v81, s10, v24
	v_fmac_f32_e32 v82, s11, v25
	v_fmac_f32_e32 v81, s100, v20
	v_fmac_f32_e32 v82, s101, v21
	v_add_f32_e32 v81, v81, v82
	s_waitcnt lgkmcnt(7)
; __device__ __forceinline__ void gd_prep_item(CArgs* a, LAS unsigned char* lds, int l, int item) {
;     ...
;         for (int t = 1; t < 64; ++t) { float s0 = 0.f, s1 = 0.f;
; #pragma unroll
;             for (int sI = 0; sI < t; ++sI) { const float cf = __builtin_bit_cast(float, __builtin_amdgcn_readlane(__builtin_bit_cast(int, nrow[t]), sI)); if (sI & 1) s1 += cf * x[sI]; else s0 += cf * x[sI]; }
;             x[t] -= s0 + s1; }
	v_readlane_b32 s10, v68, 0
	v_readlane_b32 s11, v68, 1
	v_readlane_b32 s100, v68, 2
	v_readlane_b32 s101, v68, 3
	v_sub_f32_e32 v18, v18, v81
	v_fma_f32 v81, v5, s10, 0
	v_readlane_b32 s10, v68, 4
	v_fma_f32 v82, v4, s11, 0
	v_readlane_b32 s11, v68, 5
	v_fmac_f32_e32 v81, s100, v124
	v_readlane_b32 s100, v68, 6
	v_fmac_f32_e32 v82, s101, v71
	v_readlane_b32 s101, v68, 7
	v_fmac_f32_e32 v81, s10, v70
	v_readlane_b32 s10, v68, 8
	v_fmac_f32_e32 v82, s11, v74
	v_readlane_b32 s11, v68, 9
	v_fmac_f32_e32 v81, s100, v75
	v_readlane_b32 s100, v68, 10
	v_fmac_f32_e32 v82, s101, v80
	v_readlane_b32 s101, v68, 11
	v_fmac_f32_e32 v81, s10, v78
	v_readlane_b32 s10, v68, 12
	v_fmac_f32_e32 v82, s11, v79
	v_readlane_b32 s11, v68, 13
	v_fmac_f32_e32 v81, s100, v76
	v_readlane_b32 s100, v68, 14
	v_fmac_f32_e32 v82, s101, v77
	v_readlane_b32 s101, v68, 15
	v_fmac_f32_e32 v81, s10, v72
	v_readlane_b32 s10, v68, 16
	v_fmac_f32_e32 v82, s11, v73
	v_readlane_b32 s11, v68, 17
	v_fmac_f32_e32 v81, s100, v66
	v_readlane_b32 s100, v68, 18
	v_fmac_f32_e32 v82, s101, v67
	v_readlane_b32 s101, v68, 19
	v_fmac_f32_e32 v81, s10, v64
	v_readlane_b32 s10, v68, 20
	v_fmac_f32_e32 v82, s11, v65
	v_readlane_b32 s11, v68, 21
	v_fmac_f32_e32 v81, s100, v62
	v_readlane_b32 s100, v68, 22
	v_fmac_f32_e32 v82, s101, v63
	v_readlane_b32 s101, v68, 23
	v_fmac_f32_e32 v81, s10, v60
	v_readlane_b32 s10, v68, 24
	v_fmac_f32_e32 v82, s11, v61
	v_readlane_b32 s11, v68, 25
	v_fmac_f32_e32 v81, s100, v56
	v_readlane_b32 s100, v68, 26
	v_fmac_f32_e32 v82, s101, v57
	v_readlane_b32 s101, v68, 27
	v_fmac_f32_e32 v81, s10, v54
	v_readlane_b32 s10, v68, 28
	v_fmac_f32_e32 v82, s11, v55
	v_readlane_b32 s11, v68, 29
	v_fmac_f32_e32 v81, s100, v52
	v_readlane_b32 s100, v68, 30
	v_fmac_f32_e32 v82, s101, v53
	v_readlane_b32 s101, v68, 31
	v_fmac_f32_e32 v81, s10, v48
	v_readlane_b32 s10, v68, 32
	v_fmac_f32_e32 v82, s11, v49
	v_readlane_b32 s11, v68, 33
	v_fmac_f32_e32 v81, s100, v46
	v_readlane_b32 s100, v68, 34
	v_fmac_f32_e32 v82, s101, v47
	v_readlane_b32 s101, v68, 35
	v_fmac_f32_e32 v81, s10, v42
	v_readlane_b32 s10, v68, 36
	v_fmac_f32_e32 v82, s11, v43
	v_readlane_b32 s11, v68, 37
	v_fmac_f32_e32 v81, s100, v40
	v_readlane_b32 s100, v68, 38
	v_fmac_f32_e32 v82, s101, v41
	v_readlane_b32 s101, v68, 39
	v_fmac_f32_e32 v81, s10, v36
	v_readlane_b32 s10, v68, 40
	v_fmac_f32_e32 v82, s11, v37
	v_readlane_b32 s11, v68, 41
	v_fmac_f32_e32 v81, s100, v34
	v_readlane_b32 s100, v68, 42
	v_fmac_f32_e32 v82, s101, v35
	v_readlane_b32 s101, v68, 43
	v_fmac_f32_e32 v81, s10, v30
	v_readlane_b32 s10, v68, 44
	v_fmac_f32_e32 v82, s11, v31
	v_readlane_b32 s11, v68, 45
	v_fmac_f32_e32 v81, s100, v26
	v_readlane_b32 s100, v68, 46
	v_fmac_f32_e32 v82, s101, v27
	v_readlane_b32 s101, v68, 47
	v_fmac_f32_e32 v81, s10, v24
	v_readlane_b32 s10, v68, 48
	v_fmac_f32_e32 v82, s11, v25
	v_readlane_b32 s11, v69, 0
	v_fmac_f32_e32 v81, s100, v20
	v_readlane_b32 s100, v69, 1
	v_fmac_f32_e32 v82, s101, v21
	v_readlane_b32 s101, v69, 2
	v_fmac_f32_e32 v81, s10, v18
	v_readlane_b32 s10, v69, 3
	v_add_f32_e32 v68, v82, v81
	v_sub_f32_e32 v19, v19, v68
	v_fma_f32 v68, v5, s11, 0
	v_readlane_b32 s11, v69, 4
	v_fma_f32 v81, v4, s100, 0
	v_readlane_b32 s100, v69, 5
	v_fmac_f32_e32 v68, s101, v124
	v_readlane_b32 s101, v69, 6
	v_fmac_f32_e32 v81, s10, v71
	v_readlane_b32 s10, v69, 7
	v_fmac_f32_e32 v68, s11, v70
	v_readlane_b32 s11, v69, 8
	v_fmac_f32_e32 v81, s100, v74
	v_readlane_b32 s100, v69, 9
	v_fmac_f32_e32 v68, s101, v75
	v_readlane_b32 s101, v69, 10
	v_fmac_f32_e32 v81, s10, v80
	v_readlane_b32 s10, v69, 11
	v_fmac_f32_e32 v68, s11, v78
	v_readlane_b32 s11, v69, 12
	v_fmac_f32_e32 v81, s100, v79
	v_readlane_b32 s100, v69, 13
	v_fmac_f32_e32 v68, s101, v76
	v_readlane_b32 s101, v69, 14
	v_fmac_f32_e32 v81, s10, v77
	v_readlane_b32 s10, v69, 15
	v_fmac_f32_e32 v68, s11, v72
	v_readlane_b32 s11, v69, 16
	v_fmac_f32_e32 v81, s100, v73
	v_readlane_b32 s100, v69, 17
	v_fmac_f32_e32 v68, s101, v66
	v_readlane_b32 s101, v69, 18
	v_fmac_f32_e32 v81, s10, v67
	v_readlane_b32 s10, v69, 19
	v_fmac_f32_e32 v68, s11, v64
	v_readlane_b32 s11, v69, 20
	v_fmac_f32_e32 v81, s100, v65
	v_readlane_b32 s100, v69, 21
	v_fmac_f32_e32 v68, s101, v62
	v_readlane_b32 s101, v69, 22
	v_fmac_f32_e32 v81, s10, v63
	v_readlane_b32 s10, v69, 23
	v_fmac_f32_e32 v68, s11, v60
	v_readlane_b32 s11, v69, 24
	v_fmac_f32_e32 v81, s100, v61
	v_readlane_b32 s100, v69, 25
	v_fmac_f32_e32 v68, s101, v56
	v_readlane_b32 s101, v69, 26
	v_fmac_f32_e32 v81, s10, v57
	v_readlane_b32 s10, v69, 27
	v_fmac_f32_e32 v68, s11, v54
	v_readlane_b32 s11, v69, 28
	v_fmac_f32_e32 v81, s100, v55
	v_readlane_b32 s100, v69, 29
	v_fmac_f32_e32 v68, s101, v52
	v_readlane_b32 s101, v69, 30
	v_fmac_f32_e32 v81, s10, v53
	v_readlane_b32 s10, v69, 31
	v_fmac_f32_e32 v68, s11, v48
	v_readlane_b32 s11, v69, 32
	v_fmac_f32_e32 v81, s100, v49
	v_readlane_b32 s100, v69, 33
	v_fmac_f32_e32 v68, s101, v46
	v_readlane_b32 s101, v69, 34
	v_fmac_f32_e32 v81, s10, v47
	v_readlane_b32 s10, v69, 35
	v_fmac_f32_e32 v68, s11, v42
	v_readlane_b32 s11, v69, 36
	v_fmac_f32_e32 v81, s100, v43
	v_readlane_b32 s100, v69, 37
	v_fmac_f32_e32 v68, s101, v40
	v_readlane_b32 s101, v69, 38
	v_fmac_f32_e32 v81, s10, v41
	v_readlane_b32 s10, v69, 39
	v_fmac_f32_e32 v68, s11, v36
	v_readlane_b32 s11, v69, 40
	v_fmac_f32_e32 v81, s100, v37
	v_readlane_b32 s100, v69, 41
	v_fmac_f32_e32 v68, s101, v34
	v_readlane_b32 s101, v69, 42
	v_fmac_f32_e32 v81, s10, v35
	v_readlane_b32 s10, v69, 43
	v_fmac_f32_e32 v68, s11, v30
	v_readlane_b32 s11, v69, 44
	v_fmac_f32_e32 v81, s100, v31
	v_readlane_b32 s100, v69, 45
	v_fmac_f32_e32 v68, s101, v26
	v_readlane_b32 s101, v69, 46
	v_fmac_f32_e32 v81, s10, v27
	v_readlane_b32 s10, v69, 47
	v_fmac_f32_e32 v68, s11, v24
	v_readlane_b32 s11, v69, 48
	v_fmac_f32_e32 v81, s100, v25
	v_readlane_b32 s100, v69, 49
	v_fmac_f32_e32 v68, s101, v20
	v_fmac_f32_e32 v81, s10, v21
	v_fmac_f32_e32 v68, s11, v18
	v_fmac_f32_e32 v81, s100, v19
	v_add_f32_e32 v68, v68, v81
	s_waitcnt lgkmcnt(6)
; __device__ __forceinline__ void gd_prep_item(CArgs* a, LAS unsigned char* lds, int l, int item) {
;     ...
;         float nrow[64];
; #pragma unroll
;         for (int t = 1; t < 64; ++t) nrow[t] = NM[t * 64 + lane];
; #pragma unroll
;         for (int t = 1; t < 64; ++t) { float s0 = 0.f, s1 = 0.f;
; #pragma unroll
;             for (int sI = 0; sI < t; ++sI) { const float cf = __builtin_bit_cast(float, __builtin_amdgcn_readlane(__builtin_bit_cast(int, nrow[t]), sI)); if (sI & 1) s1 += cf * x[sI]; else s0 += cf * x[sI]; }
;             x[t] -= s0 + s1; }
	v_readlane_b32 s101, v58, 0
	v_readlane_b32 s10, v58, 1
	v_readlane_b32 s11, v58, 2
	v_readlane_b32 s100, v58, 3
	v_sub_f32_e32 v14, v14, v68
	v_fma_f32 v68, v5, s101, 0
	v_readlane_b32 s101, v58, 4
	v_fma_f32 v69, v4, s10, 0
	v_readlane_b32 s10, v58, 5
	v_fmac_f32_e32 v68, s11, v124
	v_readlane_b32 s11, v58, 6
	v_fmac_f32_e32 v69, s100, v71
	v_readlane_b32 s100, v58, 7
	v_fmac_f32_e32 v68, s101, v70
	v_readlane_b32 s101, v58, 8
	v_fmac_f32_e32 v69, s10, v74
	v_readlane_b32 s10, v58, 9
	v_fmac_f32_e32 v68, s11, v75
	v_readlane_b32 s11, v58, 10
	v_fmac_f32_e32 v69, s100, v80
	v_readlane_b32 s100, v58, 11
	v_fmac_f32_e32 v68, s101, v78
	v_readlane_b32 s101, v58, 12
	v_fmac_f32_e32 v69, s10, v79
	v_readlane_b32 s10, v58, 13
	v_fmac_f32_e32 v68, s11, v76
	v_readlane_b32 s11, v58, 14
	v_fmac_f32_e32 v69, s100, v77
	v_readlane_b32 s100, v58, 15
	v_fmac_f32_e32 v68, s101, v72
	v_readlane_b32 s101, v58, 16
	v_fmac_f32_e32 v69, s10, v73
	v_readlane_b32 s10, v58, 17
	v_fmac_f32_e32 v68, s11, v66
	v_readlane_b32 s11, v58, 18
	v_fmac_f32_e32 v69, s100, v67
	v_readlane_b32 s100, v58, 19
	v_fmac_f32_e32 v68, s101, v64
	v_readlane_b32 s101, v58, 20
	v_fmac_f32_e32 v69, s10, v65
	v_readlane_b32 s10, v58, 21
	v_fmac_f32_e32 v68, s11, v62
	v_readlane_b32 s11, v58, 22
	v_fmac_f32_e32 v69, s100, v63
	v_readlane_b32 s100, v58, 23
	v_fmac_f32_e32 v68, s101, v60
	v_readlane_b32 s101, v58, 24
	v_fmac_f32_e32 v69, s10, v61
	v_readlane_b32 s10, v58, 25
	v_fmac_f32_e32 v68, s11, v56
	v_readlane_b32 s11, v58, 26
	v_fmac_f32_e32 v69, s100, v57
	v_readlane_b32 s100, v58, 27
	v_fmac_f32_e32 v68, s101, v54
	v_readlane_b32 s101, v58, 28
	v_fmac_f32_e32 v69, s10, v55
	v_readlane_b32 s10, v58, 29
	v_fmac_f32_e32 v68, s11, v52
	v_readlane_b32 s11, v58, 30
	v_fmac_f32_e32 v69, s100, v53
	v_readlane_b32 s100, v58, 31
	v_fmac_f32_e32 v68, s101, v48
	v_readlane_b32 s101, v58, 32
	v_fmac_f32_e32 v69, s10, v49
	v_readlane_b32 s10, v58, 33
	v_fmac_f32_e32 v68, s11, v46
	v_readlane_b32 s11, v58, 34
	v_fmac_f32_e32 v69, s100, v47
	v_readlane_b32 s100, v58, 35
	v_fmac_f32_e32 v68, s101, v42
	v_readlane_b32 s101, v58, 36
	v_fmac_f32_e32 v69, s10, v43
	v_readlane_b32 s10, v58, 37
	v_fmac_f32_e32 v68, s11, v40
	v_readlane_b32 s11, v58, 38
	v_fmac_f32_e32 v69, s100, v41
	v_readlane_b32 s100, v58, 39
	v_fmac_f32_e32 v68, s101, v36
	v_readlane_b32 s101, v58, 40
	v_fmac_f32_e32 v69, s10, v37
	v_readlane_b32 s10, v58, 41
	v_fmac_f32_e32 v68, s11, v34
	v_readlane_b32 s11, v58, 42
	v_fmac_f32_e32 v69, s100, v35
	v_readlane_b32 s100, v58, 43
	v_fmac_f32_e32 v68, s101, v30
	v_readlane_b32 s101, v58, 44
	v_fmac_f32_e32 v69, s10, v31
	v_readlane_b32 s10, v58, 45
	v_fmac_f32_e32 v68, s11, v26
	v_readlane_b32 s11, v58, 46
	v_fmac_f32_e32 v69, s100, v27
	v_readlane_b32 s100, v58, 47
	v_fmac_f32_e32 v68, s101, v24
	v_readlane_b32 s101, v58, 48
	v_fmac_f32_e32 v69, s10, v25
	v_readlane_b32 s10, v58, 49
	v_fmac_f32_e32 v68, s11, v20
	v_readlane_b32 s11, v58, 50
	v_fmac_f32_e32 v69, s100, v21
	v_readlane_b32 s100, v59, 0
	v_fmac_f32_e32 v68, s101, v18
	v_readlane_b32 s101, v59, 1
	v_fmac_f32_e32 v69, s10, v19
	v_readlane_b32 s10, v59, 2
	v_fmac_f32_e32 v68, s11, v14
	v_readlane_b32 s11, v59, 3
	v_add_f32_e32 v58, v69, v68
	v_sub_f32_e32 v15, v15, v58
	v_fma_f32 v58, v5, s100, 0
	v_readlane_b32 s100, v59, 4
	v_fma_f32 v68, v4, s101, 0
	v_readlane_b32 s101, v59, 5
	v_fmac_f32_e32 v58, s10, v124
	v_readlane_b32 s10, v59, 6
	v_fmac_f32_e32 v68, s11, v71
	v_readlane_b32 s11, v59, 7
	v_fmac_f32_e32 v58, s100, v70
	v_readlane_b32 s100, v59, 8
	v_fmac_f32_e32 v68, s101, v74
	v_readlane_b32 s101, v59, 9
	v_fmac_f32_e32 v58, s10, v75
	v_readlane_b32 s10, v59, 10
	v_fmac_f32_e32 v68, s11, v80
	v_readlane_b32 s11, v59, 11
	v_fmac_f32_e32 v58, s100, v78
	v_readlane_b32 s100, v59, 12
	v_fmac_f32_e32 v68, s101, v79
	v_readlane_b32 s101, v59, 13
	v_fmac_f32_e32 v58, s10, v76
	v_readlane_b32 s10, v59, 14
	v_fmac_f32_e32 v68, s11, v77
	v_readlane_b32 s11, v59, 15
	v_fmac_f32_e32 v58, s100, v72
	v_readlane_b32 s100, v59, 16
	v_fmac_f32_e32 v68, s101, v73
	v_readlane_b32 s101, v59, 17
	v_fmac_f32_e32 v58, s10, v66
	v_readlane_b32 s10, v59, 18
	v_fmac_f32_e32 v68, s11, v67
	v_readlane_b32 s11, v59, 19
	v_fmac_f32_e32 v58, s100, v64
	v_readlane_b32 s100, v59, 20
	v_fmac_f32_e32 v68, s101, v65
	v_readlane_b32 s101, v59, 21
	v_fmac_f32_e32 v58, s10, v62
	v_readlane_b32 s10, v59, 22
	v_fmac_f32_e32 v68, s11, v63
	v_readlane_b32 s11, v59, 23
	v_fmac_f32_e32 v58, s100, v60
	v_readlane_b32 s100, v59, 24
	v_fmac_f32_e32 v68, s101, v61
	v_readlane_b32 s101, v59, 25
	v_fmac_f32_e32 v58, s10, v56
	v_readlane_b32 s10, v59, 26
	v_fmac_f32_e32 v68, s11, v57
	v_readlane_b32 s11, v59, 27
	v_fmac_f32_e32 v58, s100, v54
	v_readlane_b32 s100, v59, 28
	v_fmac_f32_e32 v68, s101, v55
	v_readlane_b32 s101, v59, 29
	v_fmac_f32_e32 v58, s10, v52
	v_readlane_b32 s10, v59, 30
	v_fmac_f32_e32 v68, s11, v53
	v_readlane_b32 s11, v59, 31
	v_fmac_f32_e32 v58, s100, v48
	v_readlane_b32 s100, v59, 32
	v_fmac_f32_e32 v68, s101, v49
	v_readlane_b32 s101, v59, 33
	v_fmac_f32_e32 v58, s10, v46
	v_readlane_b32 s10, v59, 34
	v_fmac_f32_e32 v68, s11, v47
	v_readlane_b32 s11, v59, 35
	v_fmac_f32_e32 v58, s100, v42
	v_readlane_b32 s100, v59, 36
	v_fmac_f32_e32 v68, s101, v43
	v_readlane_b32 s101, v59, 37
	v_fmac_f32_e32 v58, s10, v40
	v_readlane_b32 s10, v59, 38
	v_fmac_f32_e32 v68, s11, v41
	v_readlane_b32 s11, v59, 39
	v_fmac_f32_e32 v58, s100, v36
	v_readlane_b32 s100, v59, 40
	v_fmac_f32_e32 v68, s101, v37
	v_readlane_b32 s101, v59, 41
	v_fmac_f32_e32 v58, s10, v34
	v_readlane_b32 s10, v59, 42
	v_fmac_f32_e32 v68, s11, v35
	v_readlane_b32 s11, v59, 43
	v_fmac_f32_e32 v58, s100, v30
	v_readlane_b32 s100, v59, 44
	v_fmac_f32_e32 v68, s101, v31
	v_readlane_b32 s101, v59, 45
	v_fmac_f32_e32 v58, s10, v26
	v_readlane_b32 s10, v59, 46
	v_fmac_f32_e32 v68, s11, v27
	v_readlane_b32 s11, v59, 47
	v_fmac_f32_e32 v58, s100, v24
	v_readlane_b32 s100, v59, 48
	v_fmac_f32_e32 v68, s101, v25
	v_readlane_b32 s101, v59, 49
	v_fmac_f32_e32 v58, s10, v20
	v_readlane_b32 s10, v59, 50
	v_fmac_f32_e32 v68, s11, v21
	v_readlane_b32 s11, v59, 51
	v_fmac_f32_e32 v58, s100, v18
	v_fmac_f32_e32 v68, s101, v19
	v_fmac_f32_e32 v58, s10, v14
	v_fmac_f32_e32 v68, s11, v15
	v_add_f32_e32 v58, v58, v68
	s_waitcnt lgkmcnt(5)
; __device__ __forceinline__ void gd_prep_item(CArgs* a, LAS unsigned char* lds, int l, int item) {
;     ...
;         float nrow[64];
; #pragma unroll
;         for (int t = 1; t < 64; ++t) nrow[t] = NM[t * 64 + lane];
; #pragma unroll
;         for (int t = 1; t < 64; ++t) { float s0 = 0.f, s1 = 0.f;
; #pragma unroll
;             for (int sI = 0; sI < t; ++sI) { const float cf = __builtin_bit_cast(float, __builtin_amdgcn_readlane(__builtin_bit_cast(int, nrow[t]), sI)); if (sI & 1) s1 += cf * x[sI]; else s0 += cf * x[sI]; }
;             x[t] -= s0 + s1; }
	v_readlane_b32 s100, v50, 0
	v_readlane_b32 s101, v50, 1
	v_readlane_b32 s10, v50, 2
	v_readlane_b32 s11, v50, 3
	v_sub_f32_e32 v10, v10, v58
	v_fma_f32 v58, v5, s100, 0
	v_readlane_b32 s100, v50, 4
	v_fma_f32 v59, v4, s101, 0
	v_readlane_b32 s101, v50, 5
	v_fmac_f32_e32 v58, s10, v124
	v_readlane_b32 s10, v50, 6
	v_fmac_f32_e32 v59, s11, v71
	v_readlane_b32 s11, v50, 7
	v_fmac_f32_e32 v58, s100, v70
	v_readlane_b32 s100, v50, 8
	v_fmac_f32_e32 v59, s101, v74
	v_readlane_b32 s101, v50, 9
	v_fmac_f32_e32 v58, s10, v75
	v_readlane_b32 s10, v50, 10
	v_fmac_f32_e32 v59, s11, v80
	v_readlane_b32 s11, v50, 11
	v_fmac_f32_e32 v58, s100, v78
	v_readlane_b32 s100, v50, 12
	v_fmac_f32_e32 v59, s101, v79
	v_readlane_b32 s101, v50, 13
	v_fmac_f32_e32 v58, s10, v76
	v_readlane_b32 s10, v50, 14
	v_fmac_f32_e32 v59, s11, v77
	v_readlane_b32 s11, v50, 15
	v_fmac_f32_e32 v58, s100, v72
	v_readlane_b32 s100, v50, 16
	v_fmac_f32_e32 v59, s101, v73
	v_readlane_b32 s101, v50, 17
	v_fmac_f32_e32 v58, s10, v66
	v_readlane_b32 s10, v50, 18
	v_fmac_f32_e32 v59, s11, v67
	v_readlane_b32 s11, v50, 19
	v_fmac_f32_e32 v58, s100, v64
	v_readlane_b32 s100, v50, 20
	v_fmac_f32_e32 v59, s101, v65
	v_readlane_b32 s101, v50, 21
	v_fmac_f32_e32 v58, s10, v62
	v_readlane_b32 s10, v50, 22
	v_fmac_f32_e32 v59, s11, v63
	v_readlane_b32 s11, v50, 23
	v_fmac_f32_e32 v58, s100, v60
	v_readlane_b32 s100, v50, 24
	v_fmac_f32_e32 v59, s101, v61
	v_readlane_b32 s101, v50, 25
	v_fmac_f32_e32 v58, s10, v56
	v_readlane_b32 s10, v50, 26
	v_fmac_f32_e32 v59, s11, v57
	v_readlane_b32 s11, v50, 27
	v_fmac_f32_e32 v58, s100, v54
	v_readlane_b32 s100, v50, 28
	v_fmac_f32_e32 v59, s101, v55
	v_readlane_b32 s101, v50, 29
	v_fmac_f32_e32 v58, s10, v52
	v_readlane_b32 s10, v50, 30
	v_fmac_f32_e32 v59, s11, v53
	v_readlane_b32 s11, v50, 31
	v_fmac_f32_e32 v58, s100, v48
	v_readlane_b32 s100, v50, 32
	v_fmac_f32_e32 v59, s101, v49
	v_readlane_b32 s101, v50, 33
	v_fmac_f32_e32 v58, s10, v46
	v_readlane_b32 s10, v50, 34
	v_fmac_f32_e32 v59, s11, v47
	v_readlane_b32 s11, v50, 35
	v_fmac_f32_e32 v58, s100, v42
	v_readlane_b32 s100, v50, 36
	v_fmac_f32_e32 v59, s101, v43
	v_readlane_b32 s101, v50, 37
	v_fmac_f32_e32 v58, s10, v40
	v_readlane_b32 s10, v50, 38
	v_fmac_f32_e32 v59, s11, v41
	v_readlane_b32 s11, v50, 39
	v_fmac_f32_e32 v58, s100, v36
	v_readlane_b32 s100, v50, 40
	v_fmac_f32_e32 v59, s101, v37
	v_readlane_b32 s101, v50, 41
	v_fmac_f32_e32 v58, s10, v34
	v_readlane_b32 s10, v50, 42
	v_fmac_f32_e32 v59, s11, v35
	v_readlane_b32 s11, v50, 43
	v_fmac_f32_e32 v58, s100, v30
	v_readlane_b32 s100, v50, 44
	v_fmac_f32_e32 v59, s101, v31
	v_readlane_b32 s101, v50, 45
	v_fmac_f32_e32 v58, s10, v26
	v_readlane_b32 s10, v50, 46
	v_fmac_f32_e32 v59, s11, v27
	v_readlane_b32 s11, v50, 47
	v_fmac_f32_e32 v58, s100, v24
	v_readlane_b32 s100, v50, 48
	v_fmac_f32_e32 v59, s101, v25
	v_readlane_b32 s101, v50, 49
	v_fmac_f32_e32 v58, s10, v20
	v_readlane_b32 s10, v50, 50
	v_fmac_f32_e32 v59, s11, v21
	v_readlane_b32 s11, v50, 51
	v_fmac_f32_e32 v58, s100, v18
	v_readlane_b32 s100, v50, 52
	v_fmac_f32_e32 v59, s101, v19
	v_readlane_b32 s101, v51, 0
	v_fmac_f32_e32 v58, s10, v14
	v_readlane_b32 s10, v51, 1
	v_fmac_f32_e32 v59, s11, v15
	v_readlane_b32 s11, v51, 2
	v_fmac_f32_e32 v58, s100, v10
	v_readlane_b32 s100, v51, 3
	v_add_f32_e32 v50, v59, v58
	v_sub_f32_e32 v11, v11, v50
	v_fma_f32 v50, v5, s101, 0
	v_readlane_b32 s101, v51, 4
	v_fma_f32 v58, v4, s10, 0
	v_readlane_b32 s10, v51, 5
	v_fmac_f32_e32 v50, s11, v124
	v_readlane_b32 s11, v51, 6
	v_fmac_f32_e32 v58, s100, v71
	v_readlane_b32 s100, v51, 7
	v_fmac_f32_e32 v50, s101, v70
	v_readlane_b32 s101, v51, 8
	v_fmac_f32_e32 v58, s10, v74
	v_readlane_b32 s10, v51, 9
	v_fmac_f32_e32 v50, s11, v75
	v_readlane_b32 s11, v51, 10
	v_fmac_f32_e32 v58, s100, v80
	v_readlane_b32 s100, v51, 11
	v_fmac_f32_e32 v50, s101, v78
	v_readlane_b32 s101, v51, 12
	v_fmac_f32_e32 v58, s10, v79
	v_readlane_b32 s10, v51, 13
	v_fmac_f32_e32 v50, s11, v76
	v_readlane_b32 s11, v51, 14
	v_fmac_f32_e32 v58, s100, v77
	v_readlane_b32 s100, v51, 15
	v_fmac_f32_e32 v50, s101, v72
	v_readlane_b32 s101, v51, 16
	v_fmac_f32_e32 v58, s10, v73
	v_readlane_b32 s10, v51, 17
	v_fmac_f32_e32 v50, s11, v66
	v_readlane_b32 s11, v51, 18
	v_fmac_f32_e32 v58, s100, v67
	v_readlane_b32 s100, v51, 19
	v_fmac_f32_e32 v50, s101, v64
	v_readlane_b32 s101, v51, 20
	v_fmac_f32_e32 v58, s10, v65
	v_readlane_b32 s10, v51, 21
	v_fmac_f32_e32 v50, s11, v62
	v_readlane_b32 s11, v51, 22
	v_fmac_f32_e32 v58, s100, v63
	v_readlane_b32 s100, v51, 23
	v_fmac_f32_e32 v50, s101, v60
	v_readlane_b32 s101, v51, 24
	v_fmac_f32_e32 v58, s10, v61
	v_readlane_b32 s10, v51, 25
	v_fmac_f32_e32 v50, s11, v56
	v_readlane_b32 s11, v51, 26
	v_fmac_f32_e32 v58, s100, v57
	v_readlane_b32 s100, v51, 27
	v_fmac_f32_e32 v50, s101, v54
	v_readlane_b32 s101, v51, 28
	v_fmac_f32_e32 v58, s10, v55
	v_readlane_b32 s10, v51, 29
	v_fmac_f32_e32 v50, s11, v52
	v_readlane_b32 s11, v51, 30
	v_fmac_f32_e32 v58, s100, v53
	v_readlane_b32 s100, v51, 31
	v_fmac_f32_e32 v50, s101, v48
	v_readlane_b32 s101, v51, 32
	v_fmac_f32_e32 v58, s10, v49
	v_readlane_b32 s10, v51, 33
	v_fmac_f32_e32 v50, s11, v46
	v_readlane_b32 s11, v51, 34
	v_fmac_f32_e32 v58, s100, v47
	v_readlane_b32 s100, v51, 35
	v_fmac_f32_e32 v50, s101, v42
	v_readlane_b32 s101, v51, 36
	v_fmac_f32_e32 v58, s10, v43
	v_readlane_b32 s10, v51, 37
	v_fmac_f32_e32 v50, s11, v40
	v_readlane_b32 s11, v51, 38
	v_fmac_f32_e32 v58, s100, v41
	v_readlane_b32 s100, v51, 39
	v_fmac_f32_e32 v50, s101, v36
	v_readlane_b32 s101, v51, 40
	v_fmac_f32_e32 v58, s10, v37
	v_readlane_b32 s10, v51, 41
	v_fmac_f32_e32 v50, s11, v34
	v_readlane_b32 s11, v51, 42
	v_fmac_f32_e32 v58, s100, v35
	v_readlane_b32 s100, v51, 43
	v_fmac_f32_e32 v50, s101, v30
	v_readlane_b32 s101, v51, 44
	v_fmac_f32_e32 v58, s10, v31
	v_readlane_b32 s10, v51, 45
	v_fmac_f32_e32 v50, s11, v26
	v_readlane_b32 s11, v51, 46
	v_fmac_f32_e32 v58, s100, v27
	v_readlane_b32 s100, v51, 47
	v_fmac_f32_e32 v50, s101, v24
	v_readlane_b32 s101, v51, 48
	v_fmac_f32_e32 v58, s10, v25
	v_readlane_b32 s10, v51, 49
	v_fmac_f32_e32 v50, s11, v20
	v_readlane_b32 s11, v51, 50
	v_fmac_f32_e32 v58, s100, v21
	v_readlane_b32 s100, v51, 51
	v_fmac_f32_e32 v50, s101, v18
	v_readlane_b32 s101, v51, 52
	v_fmac_f32_e32 v58, s10, v19
	v_readlane_b32 s10, v51, 53
	v_fmac_f32_e32 v50, s11, v14
	v_fmac_f32_e32 v58, s100, v15
	v_fmac_f32_e32 v50, s101, v10
	v_fmac_f32_e32 v58, s10, v11
	v_add_f32_e32 v50, v50, v58
	s_waitcnt lgkmcnt(4)
; __device__ __forceinline__ void gd_prep_item(CArgs* a, LAS unsigned char* lds, int l, int item) {
;     ...
;         float nrow[64];
; #pragma unroll
;         for (int t = 1; t < 64; ++t) nrow[t] = NM[t * 64 + lane];
; #pragma unroll
;         for (int t = 1; t < 64; ++t) { float s0 = 0.f, s1 = 0.f;
; #pragma unroll
;             for (int sI = 0; sI < t; ++sI) { const float cf = __builtin_bit_cast(float, __builtin_amdgcn_readlane(__builtin_bit_cast(int, nrow[t]), sI)); if (sI & 1) s1 += cf * x[sI]; else s0 += cf * x[sI]; }
;             x[t] -= s0 + s1; }
	v_readlane_b32 s11, v44, 0
	v_readlane_b32 s100, v44, 1
	v_readlane_b32 s101, v44, 2
	v_readlane_b32 s10, v44, 3
	v_sub_f32_e32 v8, v8, v50
	v_fma_f32 v50, v5, s11, 0
	v_readlane_b32 s11, v44, 4
	v_fma_f32 v51, v4, s100, 0
	v_readlane_b32 s100, v44, 5
	v_fmac_f32_e32 v50, s101, v124
	v_readlane_b32 s101, v44, 6
	v_fmac_f32_e32 v51, s10, v71
	v_readlane_b32 s10, v44, 7
	v_fmac_f32_e32 v50, s11, v70
	v_readlane_b32 s11, v44, 8
	v_fmac_f32_e32 v51, s100, v74
	v_readlane_b32 s100, v44, 9
	v_fmac_f32_e32 v50, s101, v75
	v_readlane_b32 s101, v44, 10
	v_fmac_f32_e32 v51, s10, v80
	v_readlane_b32 s10, v44, 11
	v_fmac_f32_e32 v50, s11, v78
	v_readlane_b32 s11, v44, 12
	v_fmac_f32_e32 v51, s100, v79
	v_readlane_b32 s100, v44, 13
	v_fmac_f32_e32 v50, s101, v76
	v_readlane_b32 s101, v44, 14
	v_fmac_f32_e32 v51, s10, v77
	v_readlane_b32 s10, v44, 15
	v_fmac_f32_e32 v50, s11, v72
	v_readlane_b32 s11, v44, 16
	v_fmac_f32_e32 v51, s100, v73
	v_readlane_b32 s100, v44, 17
	v_fmac_f32_e32 v50, s101, v66
	v_readlane_b32 s101, v44, 18
	v_fmac_f32_e32 v51, s10, v67
	v_readlane_b32 s10, v44, 19
	v_fmac_f32_e32 v50, s11, v64
	v_readlane_b32 s11, v44, 20
	v_fmac_f32_e32 v51, s100, v65
	v_readlane_b32 s100, v44, 21
	v_fmac_f32_e32 v50, s101, v62
	v_readlane_b32 s101, v44, 22
	v_fmac_f32_e32 v51, s10, v63
	v_readlane_b32 s10, v44, 23
	v_fmac_f32_e32 v50, s11, v60
	v_readlane_b32 s11, v44, 24
	v_fmac_f32_e32 v51, s100, v61
	v_readlane_b32 s100, v44, 25
	v_fmac_f32_e32 v50, s101, v56
	v_readlane_b32 s101, v44, 26
	v_fmac_f32_e32 v51, s10, v57
	v_readlane_b32 s10, v44, 27
	v_fmac_f32_e32 v50, s11, v54
	v_readlane_b32 s11, v44, 28
	v_fmac_f32_e32 v51, s100, v55
	v_readlane_b32 s100, v44, 29
	v_fmac_f32_e32 v50, s101, v52
	v_readlane_b32 s101, v44, 30
	v_fmac_f32_e32 v51, s10, v53
	v_readlane_b32 s10, v44, 31
	v_fmac_f32_e32 v50, s11, v48
	v_readlane_b32 s11, v44, 32
	v_fmac_f32_e32 v51, s100, v49
	v_readlane_b32 s100, v44, 33
	v_fmac_f32_e32 v50, s101, v46
	v_readlane_b32 s101, v44, 34
	v_fmac_f32_e32 v51, s10, v47
	v_readlane_b32 s10, v44, 35
	v_fmac_f32_e32 v50, s11, v42
	v_readlane_b32 s11, v44, 36
	v_fmac_f32_e32 v51, s100, v43
	v_readlane_b32 s100, v44, 37
	v_fmac_f32_e32 v50, s101, v40
	v_readlane_b32 s101, v44, 38
	v_fmac_f32_e32 v51, s10, v41
	v_readlane_b32 s10, v44, 39
	v_fmac_f32_e32 v50, s11, v36
	v_readlane_b32 s11, v44, 40
	v_fmac_f32_e32 v51, s100, v37
	v_readlane_b32 s100, v44, 41
	v_fmac_f32_e32 v50, s101, v34
	v_readlane_b32 s101, v44, 42
	v_fmac_f32_e32 v51, s10, v35
	v_readlane_b32 s10, v44, 43
	v_fmac_f32_e32 v50, s11, v30
	v_readlane_b32 s11, v44, 44
	v_fmac_f32_e32 v51, s100, v31
	v_readlane_b32 s100, v44, 45
	v_fmac_f32_e32 v50, s101, v26
	v_readlane_b32 s101, v44, 46
	v_fmac_f32_e32 v51, s10, v27
	v_readlane_b32 s10, v44, 47
	v_fmac_f32_e32 v50, s11, v24
	v_readlane_b32 s11, v44, 48
	v_fmac_f32_e32 v51, s100, v25
	v_readlane_b32 s100, v44, 49
	v_fmac_f32_e32 v50, s101, v20
	v_readlane_b32 s101, v44, 50
	v_fmac_f32_e32 v51, s10, v21
	v_readlane_b32 s10, v44, 51
	v_fmac_f32_e32 v50, s11, v18
	v_readlane_b32 s11, v44, 52
	v_fmac_f32_e32 v51, s100, v19
	v_readlane_b32 s100, v44, 53
	v_fmac_f32_e32 v50, s101, v14
	v_readlane_b32 s101, v44, 54
	v_fmac_f32_e32 v51, s10, v15
	v_readlane_b32 s10, v45, 0
	v_fmac_f32_e32 v50, s11, v10
	v_readlane_b32 s11, v45, 1
	v_fmac_f32_e32 v51, s100, v11
	v_readlane_b32 s100, v45, 2
	v_fmac_f32_e32 v50, s101, v8
	v_readlane_b32 s101, v45, 3
	v_add_f32_e32 v44, v51, v50
	v_sub_f32_e32 v9, v9, v44
	v_fma_f32 v44, v5, s10, 0
	v_readlane_b32 s10, v45, 4
	v_fma_f32 v50, v4, s11, 0
	v_readlane_b32 s11, v45, 5
	v_fmac_f32_e32 v44, s100, v124
	v_readlane_b32 s100, v45, 6
	v_fmac_f32_e32 v50, s101, v71
	v_readlane_b32 s101, v45, 7
	v_fmac_f32_e32 v44, s10, v70
	v_readlane_b32 s10, v45, 8
	v_fmac_f32_e32 v50, s11, v74
	v_readlane_b32 s11, v45, 9
	v_fmac_f32_e32 v44, s100, v75
	v_readlane_b32 s100, v45, 10
	v_fmac_f32_e32 v50, s101, v80
	v_readlane_b32 s101, v45, 11
	v_fmac_f32_e32 v44, s10, v78
	v_readlane_b32 s10, v45, 12
	v_fmac_f32_e32 v50, s11, v79
	v_readlane_b32 s11, v45, 13
	v_fmac_f32_e32 v44, s100, v76
	v_readlane_b32 s100, v45, 14
	v_fmac_f32_e32 v50, s101, v77
	v_readlane_b32 s101, v45, 15
	v_fmac_f32_e32 v44, s10, v72
	v_readlane_b32 s10, v45, 16
	v_fmac_f32_e32 v50, s11, v73
	v_readlane_b32 s11, v45, 17
	v_fmac_f32_e32 v44, s100, v66
	v_readlane_b32 s100, v45, 18
	v_fmac_f32_e32 v50, s101, v67
	v_readlane_b32 s101, v45, 19
	v_fmac_f32_e32 v44, s10, v64
	v_readlane_b32 s10, v45, 20
	v_fmac_f32_e32 v50, s11, v65
	v_readlane_b32 s11, v45, 21
	v_fmac_f32_e32 v44, s100, v62
	v_readlane_b32 s100, v45, 22
	v_fmac_f32_e32 v50, s101, v63
	v_readlane_b32 s101, v45, 23
	v_fmac_f32_e32 v44, s10, v60
	v_readlane_b32 s10, v45, 24
	v_fmac_f32_e32 v50, s11, v61
	v_readlane_b32 s11, v45, 25
	v_fmac_f32_e32 v44, s100, v56
	v_readlane_b32 s100, v45, 26
	v_fmac_f32_e32 v50, s101, v57
	v_readlane_b32 s101, v45, 27
	v_fmac_f32_e32 v44, s10, v54
	v_readlane_b32 s10, v45, 28
	v_fmac_f32_e32 v50, s11, v55
	v_readlane_b32 s11, v45, 29
	v_fmac_f32_e32 v44, s100, v52
	v_readlane_b32 s100, v45, 30
	v_fmac_f32_e32 v50, s101, v53
	v_readlane_b32 s101, v45, 31
	v_fmac_f32_e32 v44, s10, v48
	v_readlane_b32 s10, v45, 32
	v_fmac_f32_e32 v50, s11, v49
	v_readlane_b32 s11, v45, 33
	v_fmac_f32_e32 v44, s100, v46
	v_readlane_b32 s100, v45, 34
	v_fmac_f32_e32 v50, s101, v47
	v_readlane_b32 s101, v45, 35
	v_fmac_f32_e32 v44, s10, v42
	v_readlane_b32 s10, v45, 36
	v_fmac_f32_e32 v50, s11, v43
	v_readlane_b32 s11, v45, 37
	v_fmac_f32_e32 v44, s100, v40
	v_readlane_b32 s100, v45, 38
	v_fmac_f32_e32 v50, s101, v41
	v_readlane_b32 s101, v45, 39
	v_fmac_f32_e32 v44, s10, v36
	v_readlane_b32 s10, v45, 40
	v_fmac_f32_e32 v50, s11, v37
	v_readlane_b32 s11, v45, 41
	v_fmac_f32_e32 v44, s100, v34
	v_readlane_b32 s100, v45, 42
	v_fmac_f32_e32 v50, s101, v35
	v_readlane_b32 s101, v45, 43
	v_fmac_f32_e32 v44, s10, v30
	v_readlane_b32 s10, v45, 44
	v_fmac_f32_e32 v50, s11, v31
	v_readlane_b32 s11, v45, 45
	v_fmac_f32_e32 v44, s100, v26
	v_readlane_b32 s100, v45, 46
	v_fmac_f32_e32 v50, s101, v27
	v_readlane_b32 s101, v45, 47
	v_fmac_f32_e32 v44, s10, v24
	v_readlane_b32 s10, v45, 48
	v_fmac_f32_e32 v50, s11, v25
	v_readlane_b32 s11, v45, 49
	v_fmac_f32_e32 v44, s100, v20
	v_readlane_b32 s100, v45, 50
	v_fmac_f32_e32 v50, s101, v21
	v_readlane_b32 s101, v45, 51
	v_fmac_f32_e32 v44, s10, v18
	v_readlane_b32 s10, v45, 52
	v_fmac_f32_e32 v50, s11, v19
	v_readlane_b32 s11, v45, 53
	v_fmac_f32_e32 v44, s100, v14
	v_readlane_b32 s100, v45, 54
	v_fmac_f32_e32 v50, s101, v15
	v_readlane_b32 s101, v45, 55
	v_fmac_f32_e32 v44, s10, v10
	v_fmac_f32_e32 v50, s11, v11
	v_fmac_f32_e32 v44, s100, v8
	v_fmac_f32_e32 v50, s101, v9
	v_add_f32_e32 v44, v44, v50
	s_waitcnt lgkmcnt(3)
; __device__ __forceinline__ void gd_prep_item(CArgs* a, LAS unsigned char* lds, int l, int item) {
;     ...
;         float nrow[64];
; #pragma unroll
;         for (int t = 1; t < 64; ++t) nrow[t] = NM[t * 64 + lane];
; #pragma unroll
;         for (int t = 1; t < 64; ++t) { float s0 = 0.f, s1 = 0.f;
; #pragma unroll
;             for (int sI = 0; sI < t; ++sI) { const float cf = __builtin_bit_cast(float, __builtin_amdgcn_readlane(__builtin_bit_cast(int, nrow[t]), sI)); if (sI & 1) s1 += cf * x[sI]; else s0 += cf * x[sI]; }
;             x[t] -= s0 + s1; }
	v_readlane_b32 s10, v38, 0
	v_readlane_b32 s11, v38, 1
	v_readlane_b32 s100, v38, 2
	v_readlane_b32 s101, v38, 3
	v_sub_f32_e32 v6, v6, v44
	v_fma_f32 v44, v5, s10, 0
	v_readlane_b32 s10, v38, 4
	v_fma_f32 v45, v4, s11, 0
	v_readlane_b32 s11, v38, 5
	v_fmac_f32_e32 v44, s100, v124
	v_readlane_b32 s100, v38, 6
	v_fmac_f32_e32 v45, s101, v71
	v_readlane_b32 s101, v38, 7
	v_fmac_f32_e32 v44, s10, v70
	v_readlane_b32 s10, v38, 8
	v_fmac_f32_e32 v45, s11, v74
	v_readlane_b32 s11, v38, 9
	v_fmac_f32_e32 v44, s100, v75
	v_readlane_b32 s100, v38, 10
	v_fmac_f32_e32 v45, s101, v80
	v_readlane_b32 s101, v38, 11
	v_fmac_f32_e32 v44, s10, v78
	v_readlane_b32 s10, v38, 12
	v_fmac_f32_e32 v45, s11, v79
	v_readlane_b32 s11, v38, 13
	v_fmac_f32_e32 v44, s100, v76
	v_readlane_b32 s100, v38, 14
	v_fmac_f32_e32 v45, s101, v77
	v_readlane_b32 s101, v38, 15
	v_fmac_f32_e32 v44, s10, v72
	v_readlane_b32 s10, v38, 16
	v_fmac_f32_e32 v45, s11, v73
	v_readlane_b32 s11, v38, 17
	v_fmac_f32_e32 v44, s100, v66
	v_readlane_b32 s100, v38, 18
	v_fmac_f32_e32 v45, s101, v67
	v_readlane_b32 s101, v38, 19
	v_fmac_f32_e32 v44, s10, v64
	v_readlane_b32 s10, v38, 20
	v_fmac_f32_e32 v45, s11, v65
	v_readlane_b32 s11, v38, 21
	v_fmac_f32_e32 v44, s100, v62
	v_readlane_b32 s100, v38, 22
	v_fmac_f32_e32 v45, s101, v63
	v_readlane_b32 s101, v38, 23
	v_fmac_f32_e32 v44, s10, v60
	v_readlane_b32 s10, v38, 24
	v_fmac_f32_e32 v45, s11, v61
	v_readlane_b32 s11, v38, 25
	v_fmac_f32_e32 v44, s100, v56
	v_readlane_b32 s100, v38, 26
	v_fmac_f32_e32 v45, s101, v57
	v_readlane_b32 s101, v38, 27
	v_fmac_f32_e32 v44, s10, v54
	v_readlane_b32 s10, v38, 28
	v_fmac_f32_e32 v45, s11, v55
	v_readlane_b32 s11, v38, 29
	v_fmac_f32_e32 v44, s100, v52
	v_readlane_b32 s100, v38, 30
	v_fmac_f32_e32 v45, s101, v53
	v_readlane_b32 s101, v38, 31
	v_fmac_f32_e32 v44, s10, v48
	v_readlane_b32 s10, v38, 32
	v_fmac_f32_e32 v45, s11, v49
	v_readlane_b32 s11, v38, 33
	v_fmac_f32_e32 v44, s100, v46
	v_readlane_b32 s100, v38, 34
	v_fmac_f32_e32 v45, s101, v47
	v_readlane_b32 s101, v38, 35
	v_fmac_f32_e32 v44, s10, v42
	v_readlane_b32 s10, v38, 36
	v_fmac_f32_e32 v45, s11, v43
	v_readlane_b32 s11, v38, 37
	v_fmac_f32_e32 v44, s100, v40
	v_readlane_b32 s100, v38, 38
	v_fmac_f32_e32 v45, s101, v41
	v_readlane_b32 s101, v38, 39
	v_fmac_f32_e32 v44, s10, v36
	v_readlane_b32 s10, v38, 40
	v_fmac_f32_e32 v45, s11, v37
	v_readlane_b32 s11, v38, 41
	v_fmac_f32_e32 v44, s100, v34
	v_readlane_b32 s100, v38, 42
	v_fmac_f32_e32 v45, s101, v35
	v_readlane_b32 s101, v38, 43
	v_fmac_f32_e32 v44, s10, v30
	v_readlane_b32 s10, v38, 44
	v_fmac_f32_e32 v45, s11, v31
	v_readlane_b32 s11, v38, 45
	v_fmac_f32_e32 v44, s100, v26
	v_readlane_b32 s100, v38, 46
	v_fmac_f32_e32 v45, s101, v27
	v_readlane_b32 s101, v38, 47
	v_fmac_f32_e32 v44, s10, v24
	v_readlane_b32 s10, v38, 48
	v_fmac_f32_e32 v45, s11, v25
	v_readlane_b32 s11, v38, 49
	v_fmac_f32_e32 v44, s100, v20
	v_readlane_b32 s100, v38, 50
	v_fmac_f32_e32 v45, s101, v21
	v_readlane_b32 s101, v38, 51
	v_fmac_f32_e32 v44, s10, v18
	v_readlane_b32 s10, v38, 52
	v_fmac_f32_e32 v45, s11, v19
	v_readlane_b32 s11, v38, 53
	v_fmac_f32_e32 v44, s100, v14
	v_readlane_b32 s100, v38, 54
	v_fmac_f32_e32 v45, s101, v15
	v_readlane_b32 s101, v38, 55
	v_fmac_f32_e32 v44, s10, v10
	v_readlane_b32 s10, v38, 56
	v_fmac_f32_e32 v45, s11, v11
	v_readlane_b32 s11, v39, 0
	v_fmac_f32_e32 v44, s100, v8
	v_readlane_b32 s100, v39, 1
	v_fmac_f32_e32 v45, s101, v9
	v_readlane_b32 s101, v39, 2
	v_fmac_f32_e32 v44, s10, v6
	v_readlane_b32 s10, v39, 3
	v_add_f32_e32 v38, v45, v44
	v_sub_f32_e32 v7, v7, v38
	v_fma_f32 v38, v5, s11, 0
	v_readlane_b32 s11, v39, 4
	v_fma_f32 v44, v4, s100, 0
	v_readlane_b32 s100, v39, 5
	v_fmac_f32_e32 v38, s101, v124
	v_readlane_b32 s101, v39, 6
	v_fmac_f32_e32 v44, s10, v71
	v_readlane_b32 s10, v39, 7
	v_fmac_f32_e32 v38, s11, v70
	v_readlane_b32 s11, v39, 8
	v_fmac_f32_e32 v44, s100, v74
	v_readlane_b32 s100, v39, 9
	v_fmac_f32_e32 v38, s101, v75
	v_readlane_b32 s101, v39, 10
	v_fmac_f32_e32 v44, s10, v80
	v_readlane_b32 s10, v39, 11
	v_fmac_f32_e32 v38, s11, v78
	v_readlane_b32 s11, v39, 12
	v_fmac_f32_e32 v44, s100, v79
	v_readlane_b32 s100, v39, 13
	v_fmac_f32_e32 v38, s101, v76
	v_readlane_b32 s101, v39, 14
	v_fmac_f32_e32 v44, s10, v77
	v_readlane_b32 s10, v39, 15
	v_fmac_f32_e32 v38, s11, v72
	v_readlane_b32 s11, v39, 16
	v_fmac_f32_e32 v44, s100, v73
	v_readlane_b32 s100, v39, 17
	v_fmac_f32_e32 v38, s101, v66
	v_readlane_b32 s101, v39, 18
	v_fmac_f32_e32 v44, s10, v67
	v_readlane_b32 s10, v39, 19
	v_fmac_f32_e32 v38, s11, v64
	v_readlane_b32 s11, v39, 20
	v_fmac_f32_e32 v44, s100, v65
	v_readlane_b32 s100, v39, 21
	v_fmac_f32_e32 v38, s101, v62
	v_readlane_b32 s101, v39, 22
	v_fmac_f32_e32 v44, s10, v63
	v_readlane_b32 s10, v39, 23
	v_fmac_f32_e32 v38, s11, v60
	v_readlane_b32 s11, v39, 24
	v_fmac_f32_e32 v44, s100, v61
	v_readlane_b32 s100, v39, 25
	v_fmac_f32_e32 v38, s101, v56
	v_readlane_b32 s101, v39, 26
	v_fmac_f32_e32 v44, s10, v57
	v_readlane_b32 s10, v39, 27
	v_fmac_f32_e32 v38, s11, v54
	v_readlane_b32 s11, v39, 28
	v_fmac_f32_e32 v44, s100, v55
	v_readlane_b32 s100, v39, 29
	v_fmac_f32_e32 v38, s101, v52
	v_readlane_b32 s101, v39, 30
	v_fmac_f32_e32 v44, s10, v53
	v_readlane_b32 s10, v39, 31
	v_fmac_f32_e32 v38, s11, v48
	v_readlane_b32 s11, v39, 32
	v_fmac_f32_e32 v44, s100, v49
	v_readlane_b32 s100, v39, 33
	v_fmac_f32_e32 v38, s101, v46
	v_readlane_b32 s101, v39, 34
	v_fmac_f32_e32 v44, s10, v47
	v_readlane_b32 s10, v39, 35
	v_fmac_f32_e32 v38, s11, v42
	v_readlane_b32 s11, v39, 36
	v_fmac_f32_e32 v44, s100, v43
	v_readlane_b32 s100, v39, 37
	v_fmac_f32_e32 v38, s101, v40
	v_readlane_b32 s101, v39, 38
	v_fmac_f32_e32 v44, s10, v41
	v_readlane_b32 s10, v39, 39
	v_fmac_f32_e32 v38, s11, v36
	v_readlane_b32 s11, v39, 40
	v_fmac_f32_e32 v44, s100, v37
	v_readlane_b32 s100, v39, 41
	v_fmac_f32_e32 v38, s101, v34
	v_readlane_b32 s101, v39, 42
	v_fmac_f32_e32 v44, s10, v35
	v_readlane_b32 s10, v39, 43
	v_fmac_f32_e32 v38, s11, v30
	v_readlane_b32 s11, v39, 44
	v_fmac_f32_e32 v44, s100, v31
	v_readlane_b32 s100, v39, 45
	v_fmac_f32_e32 v38, s101, v26
	v_readlane_b32 s101, v39, 46
	v_fmac_f32_e32 v44, s10, v27
	v_readlane_b32 s10, v39, 47
	v_fmac_f32_e32 v38, s11, v24
	v_readlane_b32 s11, v39, 48
	v_fmac_f32_e32 v44, s100, v25
	v_readlane_b32 s100, v39, 49
	v_fmac_f32_e32 v38, s101, v20
	v_readlane_b32 s101, v39, 50
	v_fmac_f32_e32 v44, s10, v21
	v_readlane_b32 s10, v39, 51
	v_fmac_f32_e32 v38, s11, v18
	v_readlane_b32 s11, v39, 52
	v_fmac_f32_e32 v44, s100, v19
	v_readlane_b32 s100, v39, 53
	v_fmac_f32_e32 v38, s101, v14
	v_readlane_b32 s101, v39, 54
	v_fmac_f32_e32 v44, s10, v15
	v_readlane_b32 s10, v39, 55
	v_fmac_f32_e32 v38, s11, v10
	v_readlane_b32 s11, v39, 56
	v_fmac_f32_e32 v44, s100, v11
	v_readlane_b32 s100, v39, 57
	v_fmac_f32_e32 v38, s101, v8
	v_fmac_f32_e32 v44, s10, v9
	v_fmac_f32_e32 v38, s11, v6
	v_fmac_f32_e32 v44, s100, v7
	v_add_f32_e32 v38, v38, v44
	s_waitcnt lgkmcnt(2)
; __device__ __forceinline__ void gd_prep_item(CArgs* a, LAS unsigned char* lds, int l, int item) {
;     ...
;         float nrow[64];
; #pragma unroll
;         for (int t = 1; t < 64; ++t) nrow[t] = NM[t * 64 + lane];
; #pragma unroll
;         for (int t = 1; t < 64; ++t) { float s0 = 0.f, s1 = 0.f;
; #pragma unroll
;             for (int sI = 0; sI < t; ++sI) { const float cf = __builtin_bit_cast(float, __builtin_amdgcn_readlane(__builtin_bit_cast(int, nrow[t]), sI)); if (sI & 1) s1 += cf * x[sI]; else s0 += cf * x[sI]; }
;             x[t] -= s0 + s1; }
	v_readlane_b32 s101, v32, 0
	v_readlane_b32 s10, v32, 1
	v_readlane_b32 s11, v32, 2
	v_readlane_b32 s100, v32, 3
	v_sub_f32_e32 v16, v16, v38
	v_fma_f32 v38, v5, s101, 0
	v_readlane_b32 s101, v32, 4
	v_fma_f32 v39, v4, s10, 0
	v_readlane_b32 s10, v32, 5
	v_fmac_f32_e32 v38, s11, v124
	v_readlane_b32 s11, v32, 6
	v_fmac_f32_e32 v39, s100, v71
	v_readlane_b32 s100, v32, 7
	v_fmac_f32_e32 v38, s101, v70
	v_readlane_b32 s101, v32, 8
	v_fmac_f32_e32 v39, s10, v74
	v_readlane_b32 s10, v32, 9
	v_fmac_f32_e32 v38, s11, v75
	v_readlane_b32 s11, v32, 10
	v_fmac_f32_e32 v39, s100, v80
	v_readlane_b32 s100, v32, 11
	v_fmac_f32_e32 v38, s101, v78
	v_readlane_b32 s101, v32, 12
	v_fmac_f32_e32 v39, s10, v79
	v_readlane_b32 s10, v32, 13
	v_fmac_f32_e32 v38, s11, v76
	v_readlane_b32 s11, v32, 14
	v_fmac_f32_e32 v39, s100, v77
	v_readlane_b32 s100, v32, 15
	v_fmac_f32_e32 v38, s101, v72
	v_readlane_b32 s101, v32, 16
	v_fmac_f32_e32 v39, s10, v73
	v_readlane_b32 s10, v32, 17
	v_fmac_f32_e32 v38, s11, v66
	v_readlane_b32 s11, v32, 18
	v_fmac_f32_e32 v39, s100, v67
	v_readlane_b32 s100, v32, 19
	v_fmac_f32_e32 v38, s101, v64
	v_readlane_b32 s101, v32, 20
	v_fmac_f32_e32 v39, s10, v65
	v_readlane_b32 s10, v32, 21
	v_fmac_f32_e32 v38, s11, v62
	v_readlane_b32 s11, v32, 22
	v_fmac_f32_e32 v39, s100, v63
	v_readlane_b32 s100, v32, 23
	v_fmac_f32_e32 v38, s101, v60
	v_readlane_b32 s101, v32, 24
	v_fmac_f32_e32 v39, s10, v61
	v_readlane_b32 s10, v32, 25
	v_fmac_f32_e32 v38, s11, v56
	v_readlane_b32 s11, v32, 26
	v_fmac_f32_e32 v39, s100, v57
	v_readlane_b32 s100, v32, 27
	v_fmac_f32_e32 v38, s101, v54
	v_readlane_b32 s101, v32, 28
	v_fmac_f32_e32 v39, s10, v55
	v_readlane_b32 s10, v32, 29
	v_fmac_f32_e32 v38, s11, v52
	v_readlane_b32 s11, v32, 30
	v_fmac_f32_e32 v39, s100, v53
	v_readlane_b32 s100, v32, 31
	v_fmac_f32_e32 v38, s101, v48
	v_readlane_b32 s101, v32, 32
	v_fmac_f32_e32 v39, s10, v49
	v_readlane_b32 s10, v32, 33
	v_fmac_f32_e32 v38, s11, v46
	v_readlane_b32 s11, v32, 34
	v_fmac_f32_e32 v39, s100, v47
	v_readlane_b32 s100, v32, 35
	v_fmac_f32_e32 v38, s101, v42
	v_readlane_b32 s101, v32, 36
	v_fmac_f32_e32 v39, s10, v43
	v_readlane_b32 s10, v32, 37
	v_fmac_f32_e32 v38, s11, v40
	v_readlane_b32 s11, v32, 38
	v_fmac_f32_e32 v39, s100, v41
	v_readlane_b32 s100, v32, 39
	v_fmac_f32_e32 v38, s101, v36
	v_readlane_b32 s101, v32, 40
	v_fmac_f32_e32 v39, s10, v37
	v_readlane_b32 s10, v32, 41
	v_fmac_f32_e32 v38, s11, v34
	v_readlane_b32 s11, v32, 42
	v_fmac_f32_e32 v39, s100, v35
	v_readlane_b32 s100, v32, 43
	v_fmac_f32_e32 v38, s101, v30
	v_readlane_b32 s101, v32, 44
	v_fmac_f32_e32 v39, s10, v31
	v_readlane_b32 s10, v32, 45
	v_fmac_f32_e32 v38, s11, v26
	v_readlane_b32 s11, v32, 46
	v_fmac_f32_e32 v39, s100, v27
	v_readlane_b32 s100, v32, 47
	v_fmac_f32_e32 v38, s101, v24
	v_readlane_b32 s101, v32, 48
	v_fmac_f32_e32 v39, s10, v25
	v_readlane_b32 s10, v32, 49
	v_fmac_f32_e32 v38, s11, v20
	v_readlane_b32 s11, v32, 50
	v_fmac_f32_e32 v39, s100, v21
	v_readlane_b32 s100, v32, 51
	v_fmac_f32_e32 v38, s101, v18
	v_readlane_b32 s101, v32, 52
	v_fmac_f32_e32 v39, s10, v19
	v_readlane_b32 s10, v32, 53
	v_fmac_f32_e32 v38, s11, v14
	v_readlane_b32 s11, v32, 54
	v_fmac_f32_e32 v39, s100, v15
	v_readlane_b32 s100, v32, 55
	v_fmac_f32_e32 v38, s101, v10
	v_readlane_b32 s101, v32, 56
	v_fmac_f32_e32 v39, s10, v11
	v_readlane_b32 s10, v32, 57
	v_fmac_f32_e32 v38, s11, v8
	v_readlane_b32 s11, v32, 58
	v_fmac_f32_e32 v39, s100, v9
	v_readlane_b32 s100, v33, 0
	v_fmac_f32_e32 v38, s101, v6
	v_readlane_b32 s101, v33, 1
	v_fmac_f32_e32 v39, s10, v7
	v_readlane_b32 s10, v33, 2
	v_fmac_f32_e32 v38, s11, v16
	v_readlane_b32 s11, v33, 3
	v_add_f32_e32 v32, v39, v38
	v_sub_f32_e32 v17, v17, v32
	v_fma_f32 v32, v5, s100, 0
	v_readlane_b32 s100, v33, 4
	v_fma_f32 v38, v4, s101, 0
	v_readlane_b32 s101, v33, 5
	v_fmac_f32_e32 v32, s10, v124
	v_readlane_b32 s10, v33, 6
	v_fmac_f32_e32 v38, s11, v71
	v_readlane_b32 s11, v33, 7
	v_fmac_f32_e32 v32, s100, v70
	v_readlane_b32 s100, v33, 8
	v_fmac_f32_e32 v38, s101, v74
	v_readlane_b32 s101, v33, 9
	v_fmac_f32_e32 v32, s10, v75
	v_readlane_b32 s10, v33, 10
	v_fmac_f32_e32 v38, s11, v80
	v_readlane_b32 s11, v33, 11
	v_fmac_f32_e32 v32, s100, v78
	v_readlane_b32 s100, v33, 12
	v_fmac_f32_e32 v38, s101, v79
	v_readlane_b32 s101, v33, 13
	v_fmac_f32_e32 v32, s10, v76
	v_readlane_b32 s10, v33, 14
	v_fmac_f32_e32 v38, s11, v77
	v_readlane_b32 s11, v33, 15
	v_fmac_f32_e32 v32, s100, v72
	v_readlane_b32 s100, v33, 16
	v_fmac_f32_e32 v38, s101, v73
	v_readlane_b32 s101, v33, 17
	v_fmac_f32_e32 v32, s10, v66
	v_readlane_b32 s10, v33, 18
	v_fmac_f32_e32 v38, s11, v67
	v_readlane_b32 s11, v33, 19
	v_fmac_f32_e32 v32, s100, v64
	v_readlane_b32 s100, v33, 20
	v_fmac_f32_e32 v38, s101, v65
	v_readlane_b32 s101, v33, 21
	v_fmac_f32_e32 v32, s10, v62
	v_readlane_b32 s10, v33, 22
	v_fmac_f32_e32 v38, s11, v63
	v_readlane_b32 s11, v33, 23
	v_fmac_f32_e32 v32, s100, v60
	v_readlane_b32 s100, v33, 24
	v_fmac_f32_e32 v38, s101, v61
	v_readlane_b32 s101, v33, 25
	v_fmac_f32_e32 v32, s10, v56
	v_readlane_b32 s10, v33, 26
	v_fmac_f32_e32 v38, s11, v57
	v_readlane_b32 s11, v33, 27
	v_fmac_f32_e32 v32, s100, v54
	v_readlane_b32 s100, v33, 28
	v_fmac_f32_e32 v38, s101, v55
	v_readlane_b32 s101, v33, 29
	v_fmac_f32_e32 v32, s10, v52
	v_readlane_b32 s10, v33, 30
	v_fmac_f32_e32 v38, s11, v53
	v_readlane_b32 s11, v33, 31
	v_fmac_f32_e32 v32, s100, v48
	v_readlane_b32 s100, v33, 32
	v_fmac_f32_e32 v38, s101, v49
	v_readlane_b32 s101, v33, 33
	v_fmac_f32_e32 v32, s10, v46
	v_readlane_b32 s10, v33, 34
	v_fmac_f32_e32 v38, s11, v47
	v_readlane_b32 s11, v33, 35
; __device__ __forceinline__ void gd_prep_item(CArgs* a, LAS unsigned char* lds, int l, int item) {
;     ...
;         float nrow[64];
; #pragma unroll
;         for (int t = 1; t < 64; ++t) nrow[t] = NM[t * 64 + lane];
; #pragma unroll
;         for (int t = 1; t < 64; ++t) { float s0 = 0.f, s1 = 0.f;
; #pragma unroll
;             for (int sI = 0; sI < t; ++sI) { const float cf = __builtin_bit_cast(float, __builtin_amdgcn_readlane(__builtin_bit_cast(int, nrow[t]), sI)); if (sI & 1) s1 += cf * x[sI]; else s0 += cf * x[sI]; }
;             x[t] -= s0 + s1; }
	v_fmac_f32_e32 v32, s100, v42
	v_readlane_b32 s100, v33, 36
	v_fmac_f32_e32 v38, s101, v43
	v_readlane_b32 s101, v33, 37
	v_fmac_f32_e32 v32, s10, v40
	v_readlane_b32 s10, v33, 38
	v_fmac_f32_e32 v38, s11, v41
	v_readlane_b32 s11, v33, 39
	v_fmac_f32_e32 v32, s100, v36
	v_readlane_b32 s100, v33, 40
	v_fmac_f32_e32 v38, s101, v37
	v_readlane_b32 s101, v33, 41
	v_fmac_f32_e32 v32, s10, v34
	v_readlane_b32 s10, v33, 42
	v_fmac_f32_e32 v38, s11, v35
	v_readlane_b32 s11, v33, 43
	v_fmac_f32_e32 v32, s100, v30
	v_readlane_b32 s100, v33, 44
	v_fmac_f32_e32 v38, s101, v31
	v_readlane_b32 s101, v33, 45
	v_fmac_f32_e32 v32, s10, v26
	v_readlane_b32 s10, v33, 46
	v_fmac_f32_e32 v38, s11, v27
	v_readlane_b32 s11, v33, 47
	v_fmac_f32_e32 v32, s100, v24
	v_readlane_b32 s100, v33, 48
	v_fmac_f32_e32 v38, s101, v25
	v_readlane_b32 s101, v33, 49
	v_fmac_f32_e32 v32, s10, v20
	v_readlane_b32 s10, v33, 50
	v_fmac_f32_e32 v38, s11, v21
	v_readlane_b32 s11, v33, 51
	v_fmac_f32_e32 v32, s100, v18
	v_readlane_b32 s100, v33, 52
	v_fmac_f32_e32 v38, s101, v19
	v_readlane_b32 s101, v33, 53
	v_fmac_f32_e32 v32, s10, v14
	v_readlane_b32 s10, v33, 54
	v_fmac_f32_e32 v38, s11, v15
	v_readlane_b32 s11, v33, 55
	v_fmac_f32_e32 v32, s100, v10
	v_readlane_b32 s100, v33, 56
	v_fmac_f32_e32 v38, s101, v11
	v_readlane_b32 s101, v33, 57
	v_fmac_f32_e32 v32, s10, v8
	v_readlane_b32 s10, v33, 58
	v_fmac_f32_e32 v38, s11, v9
	v_readlane_b32 s11, v33, 59
	v_fmac_f32_e32 v32, s100, v6
	v_fmac_f32_e32 v38, s101, v7
	v_fmac_f32_e32 v32, s10, v16
	v_fmac_f32_e32 v38, s11, v17
	v_add_f32_e32 v32, v32, v38
	s_waitcnt lgkmcnt(1)
	v_readlane_b32 s100, v28, 0
	v_readlane_b32 s101, v28, 1
	v_readlane_b32 s10, v28, 2
	v_readlane_b32 s11, v28, 3
	v_sub_f32_e32 v12, v12, v32
	v_fma_f32 v32, v5, s100, 0
	v_readlane_b32 s100, v28, 4
	v_fma_f32 v33, v4, s101, 0
	v_readlane_b32 s101, v28, 5
	v_fmac_f32_e32 v32, s10, v124
	v_readlane_b32 s10, v28, 6
	v_fmac_f32_e32 v33, s11, v71
	v_readlane_b32 s11, v28, 7
	v_fmac_f32_e32 v32, s100, v70
	v_readlane_b32 s100, v28, 8
	v_fmac_f32_e32 v33, s101, v74
	v_readlane_b32 s101, v28, 9
	v_fmac_f32_e32 v32, s10, v75
	v_readlane_b32 s10, v28, 10
	v_fmac_f32_e32 v33, s11, v80
	v_readlane_b32 s11, v28, 11
	v_fmac_f32_e32 v32, s100, v78
	v_readlane_b32 s100, v28, 12
	v_fmac_f32_e32 v33, s101, v79
	v_readlane_b32 s101, v28, 13
	v_fmac_f32_e32 v32, s10, v76
	v_readlane_b32 s10, v28, 14
	v_fmac_f32_e32 v33, s11, v77
	v_readlane_b32 s11, v28, 15
	v_fmac_f32_e32 v32, s100, v72
	v_readlane_b32 s100, v28, 16
	v_fmac_f32_e32 v33, s101, v73
	v_readlane_b32 s101, v28, 17
	v_fmac_f32_e32 v32, s10, v66
	v_readlane_b32 s10, v28, 18
	v_fmac_f32_e32 v33, s11, v67
	v_readlane_b32 s11, v28, 19
	v_fmac_f32_e32 v32, s100, v64
	v_readlane_b32 s100, v28, 20
	v_fmac_f32_e32 v33, s101, v65
	v_readlane_b32 s101, v28, 21
	v_fmac_f32_e32 v32, s10, v62
	v_readlane_b32 s10, v28, 22
	v_fmac_f32_e32 v33, s11, v63
	v_readlane_b32 s11, v28, 23
	v_fmac_f32_e32 v32, s100, v60
	v_readlane_b32 s100, v28, 24
	v_fmac_f32_e32 v33, s101, v61
	v_readlane_b32 s101, v28, 25
	v_fmac_f32_e32 v32, s10, v56
	v_readlane_b32 s10, v28, 26
	v_fmac_f32_e32 v33, s11, v57
	v_readlane_b32 s11, v28, 27
	v_fmac_f32_e32 v32, s100, v54
	v_readlane_b32 s100, v28, 28
	v_fmac_f32_e32 v33, s101, v55
	v_readlane_b32 s101, v28, 29
	v_fmac_f32_e32 v32, s10, v52
	v_readlane_b32 s10, v28, 30
	v_fmac_f32_e32 v33, s11, v53
	v_readlane_b32 s11, v28, 31
	v_fmac_f32_e32 v32, s100, v48
	v_readlane_b32 s100, v28, 32
	v_fmac_f32_e32 v33, s101, v49
	v_readlane_b32 s101, v28, 33
	v_fmac_f32_e32 v32, s10, v46
	v_readlane_b32 s10, v28, 34
	v_fmac_f32_e32 v33, s11, v47
	v_readlane_b32 s11, v28, 35
	v_fmac_f32_e32 v32, s100, v42
	v_readlane_b32 s100, v28, 36
	v_fmac_f32_e32 v33, s101, v43
	v_readlane_b32 s101, v28, 37
	v_fmac_f32_e32 v32, s10, v40
	v_readlane_b32 s10, v28, 38
	v_fmac_f32_e32 v33, s11, v41
	v_readlane_b32 s11, v28, 39
	v_fmac_f32_e32 v32, s100, v36
	v_readlane_b32 s100, v28, 40
	v_fmac_f32_e32 v33, s101, v37
	v_readlane_b32 s101, v28, 41
	v_fmac_f32_e32 v32, s10, v34
	v_readlane_b32 s10, v28, 42
	v_fmac_f32_e32 v33, s11, v35
	v_readlane_b32 s11, v28, 43
	v_fmac_f32_e32 v32, s100, v30
	v_readlane_b32 s100, v28, 44
	v_fmac_f32_e32 v33, s101, v31
	v_readlane_b32 s101, v28, 45
	v_fmac_f32_e32 v32, s10, v26
	v_readlane_b32 s10, v28, 46
	v_fmac_f32_e32 v33, s11, v27
	v_readlane_b32 s11, v28, 47
	v_fmac_f32_e32 v32, s100, v24
	v_readlane_b32 s100, v28, 48
	v_fmac_f32_e32 v33, s101, v25
	v_readlane_b32 s101, v28, 49
	v_fmac_f32_e32 v32, s10, v20
	v_readlane_b32 s10, v28, 50
	v_fmac_f32_e32 v33, s11, v21
	v_readlane_b32 s11, v28, 51
	v_fmac_f32_e32 v32, s100, v18
	v_readlane_b32 s100, v28, 52
	v_fmac_f32_e32 v33, s101, v19
	v_readlane_b32 s101, v28, 53
	v_fmac_f32_e32 v32, s10, v14
	v_readlane_b32 s10, v28, 54
	v_fmac_f32_e32 v33, s11, v15
	v_readlane_b32 s11, v28, 55
	v_fmac_f32_e32 v32, s100, v10
	v_readlane_b32 s100, v28, 56
	v_fmac_f32_e32 v33, s101, v11
	v_readlane_b32 s101, v28, 57
	v_fmac_f32_e32 v32, s10, v8
	v_readlane_b32 s10, v28, 58
	v_fmac_f32_e32 v33, s11, v9
	v_readlane_b32 s11, v28, 59
	v_fmac_f32_e32 v32, s100, v6
	v_readlane_b32 s100, v28, 60
	v_fmac_f32_e32 v33, s101, v7
	v_readlane_b32 s101, v29, 0
	v_fmac_f32_e32 v32, s10, v16
	v_readlane_b32 s10, v29, 1
	v_fmac_f32_e32 v33, s11, v17
	v_readlane_b32 s11, v29, 2
	v_fmac_f32_e32 v32, s100, v12
	v_readlane_b32 s100, v29, 3
	v_add_f32_e32 v28, v33, v32
	v_sub_f32_e32 v13, v13, v28
	v_fma_f32 v28, v5, s101, 0
	v_readlane_b32 s101, v29, 4
	v_fma_f32 v32, v4, s10, 0
	v_readlane_b32 s10, v29, 5
	v_fmac_f32_e32 v28, s11, v124
	v_readlane_b32 s11, v29, 6
	v_fmac_f32_e32 v32, s100, v71
; __device__ __forceinline__ void gd_prep_item(CArgs* a, LAS unsigned char* lds, int l, int item) {
;     ...
;         float nrow[64];
; #pragma unroll
;         for (int t = 1; t < 64; ++t) nrow[t] = NM[t * 64 + lane];
; #pragma unroll
;         for (int t = 1; t < 64; ++t) { float s0 = 0.f, s1 = 0.f;
; #pragma unroll
;             for (int sI = 0; sI < t; ++sI) { const float cf = __builtin_bit_cast(float, __builtin_amdgcn_readlane(__builtin_bit_cast(int, nrow[t]), sI)); if (sI & 1) s1 += cf * x[sI]; else s0 += cf * x[sI]; }
;             x[t] -= s0 + s1; }
	v_readlane_b32 s100, v29, 7
	v_fmac_f32_e32 v28, s101, v70
	v_readlane_b32 s101, v29, 8
	v_fmac_f32_e32 v32, s10, v74
	v_readlane_b32 s10, v29, 9
	v_fmac_f32_e32 v28, s11, v75
	v_readlane_b32 s11, v29, 10
	v_fmac_f32_e32 v32, s100, v80
	v_readlane_b32 s100, v29, 11
	v_fmac_f32_e32 v28, s101, v78
	v_readlane_b32 s101, v29, 12
	v_fmac_f32_e32 v32, s10, v79
	v_readlane_b32 s10, v29, 13
	v_fmac_f32_e32 v28, s11, v76
	v_readlane_b32 s11, v29, 14
	v_fmac_f32_e32 v32, s100, v77
	v_readlane_b32 s100, v29, 15
	v_fmac_f32_e32 v28, s101, v72
	v_readlane_b32 s101, v29, 16
	v_fmac_f32_e32 v32, s10, v73
	v_readlane_b32 s10, v29, 17
	v_fmac_f32_e32 v28, s11, v66
	v_readlane_b32 s11, v29, 18
	v_fmac_f32_e32 v32, s100, v67
	v_readlane_b32 s100, v29, 19
	v_fmac_f32_e32 v28, s101, v64
	v_readlane_b32 s101, v29, 20
	v_fmac_f32_e32 v32, s10, v65
	v_readlane_b32 s10, v29, 21
	v_fmac_f32_e32 v28, s11, v62
	v_readlane_b32 s11, v29, 22
	v_fmac_f32_e32 v32, s100, v63
	v_readlane_b32 s100, v29, 23
	v_fmac_f32_e32 v28, s101, v60
	v_readlane_b32 s101, v29, 24
	v_fmac_f32_e32 v32, s10, v61
	v_readlane_b32 s10, v29, 25
	v_fmac_f32_e32 v28, s11, v56
	v_readlane_b32 s11, v29, 26
	v_fmac_f32_e32 v32, s100, v57
	v_readlane_b32 s100, v29, 27
	v_fmac_f32_e32 v28, s101, v54
	v_readlane_b32 s101, v29, 28
	v_fmac_f32_e32 v32, s10, v55
	v_readlane_b32 s10, v29, 29
	v_fmac_f32_e32 v28, s11, v52
	v_readlane_b32 s11, v29, 30
	v_fmac_f32_e32 v32, s100, v53
	v_readlane_b32 s100, v29, 31
	v_fmac_f32_e32 v28, s101, v48
	v_readlane_b32 s101, v29, 32
	v_fmac_f32_e32 v32, s10, v49
	v_readlane_b32 s10, v29, 33
	v_fmac_f32_e32 v28, s11, v46
	v_readlane_b32 s11, v29, 34
	v_fmac_f32_e32 v32, s100, v47
	v_readlane_b32 s100, v29, 35
	v_fmac_f32_e32 v28, s101, v42
	v_readlane_b32 s101, v29, 36
	v_fmac_f32_e32 v32, s10, v43
	v_readlane_b32 s10, v29, 37
	v_fmac_f32_e32 v28, s11, v40
	v_readlane_b32 s11, v29, 38
	v_fmac_f32_e32 v32, s100, v41
	v_readlane_b32 s100, v29, 39
	v_fmac_f32_e32 v28, s101, v36
	v_readlane_b32 s101, v29, 40
	v_fmac_f32_e32 v32, s10, v37
	v_readlane_b32 s10, v29, 41
	v_fmac_f32_e32 v28, s11, v34
	v_readlane_b32 s11, v29, 42
	v_fmac_f32_e32 v32, s100, v35
	v_readlane_b32 s100, v29, 43
	v_fmac_f32_e32 v28, s101, v30
	v_readlane_b32 s101, v29, 44
	v_fmac_f32_e32 v32, s10, v31
	v_readlane_b32 s10, v29, 45
	v_fmac_f32_e32 v28, s11, v26
	v_readlane_b32 s11, v29, 46
	v_fmac_f32_e32 v32, s100, v27
	v_readlane_b32 s100, v29, 47
	v_fmac_f32_e32 v28, s101, v24
	v_readlane_b32 s101, v29, 48
	v_fmac_f32_e32 v32, s10, v25
	v_readlane_b32 s10, v29, 49
	v_fmac_f32_e32 v28, s11, v20
	v_readlane_b32 s11, v29, 50
	v_fmac_f32_e32 v32, s100, v21
	v_readlane_b32 s100, v29, 51
	v_fmac_f32_e32 v28, s101, v18
	v_readlane_b32 s101, v29, 52
	v_fmac_f32_e32 v32, s10, v19
	v_readlane_b32 s10, v29, 53
	v_fmac_f32_e32 v28, s11, v14
	v_readlane_b32 s11, v29, 54
	v_fmac_f32_e32 v32, s100, v15
	v_readlane_b32 s100, v29, 55
	v_fmac_f32_e32 v28, s101, v10
	v_readlane_b32 s101, v29, 56
	v_fmac_f32_e32 v32, s10, v11
	v_readlane_b32 s10, v29, 57
	v_fmac_f32_e32 v28, s11, v8
	v_readlane_b32 s11, v29, 58
	v_fmac_f32_e32 v32, s100, v9
	v_readlane_b32 s100, v29, 59
	v_fmac_f32_e32 v28, s101, v6
	v_readlane_b32 s101, v29, 60
	v_fmac_f32_e32 v32, s10, v7
	v_readlane_b32 s10, v29, 61
	v_fmac_f32_e32 v28, s11, v16
	v_fmac_f32_e32 v32, s100, v17
	v_fmac_f32_e32 v28, s101, v12
	v_fmac_f32_e32 v32, s10, v13
	v_add_f32_e32 v28, v28, v32
	s_waitcnt lgkmcnt(0)
	v_readlane_b32 s11, v125, 0
	v_readlane_b32 s100, v125, 1
	v_readlane_b32 s101, v125, 2
	v_readlane_b32 s10, v125, 3
	v_sub_f32_e32 v22, v22, v28
	v_fma_f32 v28, v5, s11, 0
	v_readlane_b32 s11, v125, 4
	v_fma_f32 v29, v4, s100, 0
	v_readlane_b32 s100, v125, 5
	v_fmac_f32_e32 v28, s101, v124
	v_readlane_b32 s101, v125, 6
	v_fmac_f32_e32 v29, s10, v71
	v_readlane_b32 s10, v125, 7
	v_fmac_f32_e32 v28, s11, v70
	v_readlane_b32 s11, v125, 8
	v_fmac_f32_e32 v29, s100, v74
	v_readlane_b32 s100, v125, 9
	v_fmac_f32_e32 v28, s101, v75
	v_readlane_b32 s101, v125, 10
	v_fmac_f32_e32 v29, s10, v80
	v_readlane_b32 s10, v125, 11
	v_fmac_f32_e32 v28, s11, v78
	v_readlane_b32 s11, v125, 12
	v_fmac_f32_e32 v29, s100, v79
	v_readlane_b32 s100, v125, 13
	v_fmac_f32_e32 v28, s101, v76
	v_readlane_b32 s101, v125, 14
	v_fmac_f32_e32 v29, s10, v77
	v_readlane_b32 s10, v125, 15
	v_fmac_f32_e32 v28, s11, v72
	v_readlane_b32 s11, v125, 16
	v_fmac_f32_e32 v29, s100, v73
	v_readlane_b32 s100, v125, 17
	v_fmac_f32_e32 v28, s101, v66
	v_readlane_b32 s101, v125, 18
	v_fmac_f32_e32 v29, s10, v67
	v_readlane_b32 s10, v125, 19
	v_fmac_f32_e32 v28, s11, v64
	v_readlane_b32 s11, v125, 20
	v_fmac_f32_e32 v29, s100, v65
	v_readlane_b32 s100, v125, 21
	v_fmac_f32_e32 v28, s101, v62
	v_readlane_b32 s101, v125, 22
	v_fmac_f32_e32 v29, s10, v63
	v_readlane_b32 s10, v125, 23
	v_fmac_f32_e32 v28, s11, v60
	v_readlane_b32 s11, v125, 24
	v_fmac_f32_e32 v29, s100, v61
	v_readlane_b32 s100, v125, 25
	v_fmac_f32_e32 v28, s101, v56
	v_readlane_b32 s101, v125, 26
	v_fmac_f32_e32 v29, s10, v57
	v_readlane_b32 s10, v125, 27
	v_fmac_f32_e32 v28, s11, v54
	v_readlane_b32 s11, v125, 28
	v_fmac_f32_e32 v29, s100, v55
	v_readlane_b32 s100, v125, 29
	v_fmac_f32_e32 v28, s101, v52
	v_readlane_b32 s101, v125, 30
	v_fmac_f32_e32 v29, s10, v53
	v_readlane_b32 s10, v125, 31
	v_fmac_f32_e32 v28, s11, v48
	v_readlane_b32 s11, v125, 32
	v_fmac_f32_e32 v29, s100, v49
	v_readlane_b32 s100, v125, 33
	v_fmac_f32_e32 v28, s101, v46
	v_readlane_b32 s101, v125, 34
	v_fmac_f32_e32 v29, s10, v47
	v_readlane_b32 s10, v125, 35
	v_fmac_f32_e32 v28, s11, v42
	v_readlane_b32 s11, v125, 36
	v_fmac_f32_e32 v29, s100, v43
	v_readlane_b32 s100, v125, 37
; __device__ __forceinline__ unsigned cvt_pk_bf16(float lo, float hi) { const f32x2 v = {lo, hi}; return __builtin_bit_cast(unsigned, __builtin_convertvector(v, bf16x2_t)); }
; __device__ __forceinline__ void gd_prep_item(CArgs* a, LAS unsigned char* lds, int l, int item) {
;     ...
;         float nrow[64];
; #pragma unroll
;         for (int t = 1; t < 64; ++t) nrow[t] = NM[t * 64 + lane];
; #pragma unroll
;         for (int t = 1; t < 64; ++t) { float s0 = 0.f, s1 = 0.f;
; #pragma unroll
;             for (int sI = 0; sI < t; ++sI) { const float cf = __builtin_bit_cast(float, __builtin_amdgcn_readlane(__builtin_bit_cast(int, nrow[t]), sI)); if (sI & 1) s1 += cf * x[sI]; else s0 += cf * x[sI]; }
;             x[t] -= s0 + s1; }
;         if (col < 128) { const int vb = col >> 4, r = col & 15;
; #pragma unroll
;             for (int pr = 0; pr < 2; ++pr)
; #pragma unroll
;                 for (int q = 0; q < 4; ++q) { const int t0 = 32 * pr + 4 * q; u32x4 w; w.x = cvt_pk_bf16(x[t0], x[t0 + 1]); w.y = cvt_pk_bf16(x[t0 + 2], x[t0 + 3]); w.z = cvt_pk_bf16(x[t0 + 16], x[t0 + 17]); w.w = cvt_pk_bf16(x[t0 + 18], x[t0 + 19]);
;                     *(u32x4*)(U + ((vb * 2 + pr) * 64 + q * 16 + r) * 16) = w; } }
;         else { const int d = col - 128, ks = d >> 5, dl = d & 31, q = (dl >> 2) & 3, j = (dl & 3) + 4 * (dl >> 4);
	v_fmac_f32_e32 v28, s101, v40
	v_readlane_b32 s101, v125, 38
	v_fmac_f32_e32 v29, s10, v41
	v_readlane_b32 s10, v125, 39
	v_fmac_f32_e32 v28, s11, v36
	v_readlane_b32 s11, v125, 40
	v_fmac_f32_e32 v29, s100, v37
	v_readlane_b32 s100, v125, 41
	v_fmac_f32_e32 v28, s101, v34
	v_readlane_b32 s101, v125, 42
	v_fmac_f32_e32 v29, s10, v35
	v_readlane_b32 s10, v125, 43
	v_fmac_f32_e32 v28, s11, v30
	v_readlane_b32 s11, v125, 44
	v_fmac_f32_e32 v29, s100, v31
	v_readlane_b32 s100, v125, 45
	v_fmac_f32_e32 v28, s101, v26
	v_readlane_b32 s101, v125, 46
	v_fmac_f32_e32 v29, s10, v27
	v_readlane_b32 s10, v125, 47
	v_fmac_f32_e32 v28, s11, v24
	v_readlane_b32 s11, v125, 48
	v_fmac_f32_e32 v29, s100, v25
	v_readlane_b32 s100, v125, 49
	v_fmac_f32_e32 v28, s101, v20
	v_readlane_b32 s101, v125, 50
	v_fmac_f32_e32 v29, s10, v21
	v_readlane_b32 s10, v125, 51
	v_fmac_f32_e32 v28, s11, v18
	v_readlane_b32 s11, v125, 52
	v_fmac_f32_e32 v29, s100, v19
	v_readlane_b32 s100, v125, 53
	v_fmac_f32_e32 v28, s101, v14
	v_readlane_b32 s101, v125, 54
	v_fmac_f32_e32 v29, s10, v15
	v_readlane_b32 s10, v125, 55
	v_fmac_f32_e32 v28, s11, v10
	v_readlane_b32 s11, v125, 56
	v_fmac_f32_e32 v29, s100, v11
	v_readlane_b32 s100, v125, 57
	v_fmac_f32_e32 v28, s101, v8
	v_readlane_b32 s101, v125, 58
	v_fmac_f32_e32 v29, s10, v9
	v_readlane_b32 s10, v125, 59
	v_fmac_f32_e32 v28, s11, v6
	v_readlane_b32 s11, v125, 60
	v_fmac_f32_e32 v29, s100, v7
	v_readlane_b32 s100, v125, 61
	v_fmac_f32_e32 v28, s101, v16
	v_readlane_b32 s101, v125, 62
	v_fmac_f32_e32 v29, s10, v17
	v_fmac_f32_e32 v28, s11, v12
	v_fmac_f32_e32 v29, s100, v13
	v_fmac_f32_e32 v28, s101, v22
	v_add_f32_e32 v28, v29, v28
	v_sub_f32_e32 v23, v23, v28
	s_and_saveexec_b64 s[10:11], vcc
	s_xor_b64 s[10:11], exec, s[10:11]
	s_cbranch_execz .LBB0_991
; __device__ __forceinline__ bf16_t f2bf(float f) { return (bf16_t)(cvt_pk_bf16(f, 0.f) & 0xffffu); }
; __device__ __forceinline__ void gd_prep_item(CArgs* a, LAS unsigned char* lds, int l, int item) {
;     ...
;         else { const int d = col - 128, ks = d >> 5, dl = d & 31, q = (dl >> 2) & 3, j = (dl & 3) + 4 * (dl >> 4);
; #pragma unroll
;             for (int t = 0; t < 64; ++t) *(bf16_t*)(ops + OG_WN + (((t >> 4) * 4 + ks) * 64 + q * 16 + (t & 15)) * 16 + j * 2) = f2bf(-x[t]); }
	v_lshrrev_b32_e32 v28, 2, v3
	v_and_or_b32 v28, v28, 4, v122
	v_lshlrev_b32_e32 v3, 2, v3
	v_lshlrev_b32_e32 v28, 1, v28
	v_mov_b32_e32 v29, v2
	v_and_b32_e32 v3, 48, v3
	v_lshl_add_u64 v[28:29], s[8:9], 0, v[28:29]
	s_mov_b32 s8, 0xfffffc0
	v_and_or_b32 v3, v123, s8, v3
	v_lshlrev_b32_e32 v32, 4, v3
	v_add_u32_e32 v38, 0xfffff000, v32
	v_mov_b32_e32 v39, v2
	v_lshl_add_u64 v[38:39], v[28:29], 0, v[38:39]
	v_cvt_pk_bf16_f32 v3, -v4, s0
	global_store_short v[38:39], v3, off offset:16
	v_cvt_pk_bf16_f32 v3, -v124, s0
	global_store_short v[38:39], v3, off offset:32
	v_cvt_pk_bf16_f32 v3, -v71, s0
	global_store_short v[38:39], v3, off offset:48
	v_cvt_pk_bf16_f32 v3, -v70, s0
	global_store_short v[38:39], v3, off offset:64
	v_cvt_pk_bf16_f32 v3, -v74, s0
	global_store_short v[38:39], v3, off offset:80
	v_cvt_pk_bf16_f32 v3, -v75, s0
	global_store_short v[38:39], v3, off offset:96
	v_cvt_pk_bf16_f32 v3, -v80, s0
	global_store_short v[38:39], v3, off offset:112
	v_cvt_pk_bf16_f32 v3, -v78, s0
	global_store_short v[38:39], v3, off offset:128
	v_cvt_pk_bf16_f32 v3, -v79, s0
	global_store_short v[38:39], v3, off offset:144
	v_cvt_pk_bf16_f32 v3, -v76, s0
	global_store_short v[38:39], v3, off offset:160
	v_cvt_pk_bf16_f32 v3, -v77, s0
	global_store_short v[38:39], v3, off offset:176
	v_cvt_pk_bf16_f32 v3, -v72, s0
	global_store_short v[38:39], v3, off offset:192
	v_cvt_pk_bf16_f32 v3, -v73, s0
	global_store_short v[38:39], v3, off offset:208
	v_cvt_pk_bf16_f32 v3, -v66, s0
	v_cvt_pk_bf16_f32 v5, -v5, s0
	global_store_short v[38:39], v3, off offset:224
	v_cvt_pk_bf16_f32 v3, -v67, s0
	v_mov_b32_e32 v33, v2
	global_store_short v[38:39], v5, off
	global_store_short v[38:39], v3, off offset:240
	v_cvt_pk_bf16_f32 v3, -v64, s0
	v_lshl_add_u64 v[4:5], v[28:29], 0, v[32:33]
	v_ashrrev_i32_e32 v33, 31, v32
	global_store_short v[4:5], v3, off
	v_cvt_pk_bf16_f32 v3, -v65, s0
	v_lshl_add_u64 v[4:5], v[28:29], 0, v[32:33]
	global_store_short v[4:5], v3, off offset:16
	v_cvt_pk_bf16_f32 v3, -v62, s0
	global_store_short v[4:5], v3, off offset:32
	v_cvt_pk_bf16_f32 v3, -v63, s0
	global_store_short v[4:5], v3, off offset:48
	v_cvt_pk_bf16_f32 v3, -v60, s0
	global_store_short v[4:5], v3, off offset:64
	v_cvt_pk_bf16_f32 v3, -v61, s0
	global_store_short v[4:5], v3, off offset:80
	v_cvt_pk_bf16_f32 v3, -v56, s0
	global_store_short v[4:5], v3, off offset:96
	v_cvt_pk_bf16_f32 v3, -v57, s0
	global_store_short v[4:5], v3, off offset:112
	v_cvt_pk_bf16_f32 v3, -v54, s0
	global_store_short v[4:5], v3, off offset:128
	v_cvt_pk_bf16_f32 v3, -v55, s0
	global_store_short v[4:5], v3, off offset:144
	v_cvt_pk_bf16_f32 v3, -v52, s0
	global_store_short v[4:5], v3, off offset:160
	v_cvt_pk_bf16_f32 v3, -v53, s0
	global_store_short v[4:5], v3, off offset:176
	v_cvt_pk_bf16_f32 v3, -v48, s0
	global_store_short v[4:5], v3, off offset:192
	v_cvt_pk_bf16_f32 v3, -v49, s0
	global_store_short v[4:5], v3, off offset:208
	v_cvt_pk_bf16_f32 v3, -v46, s0
	global_store_short v[4:5], v3, off offset:224
	v_cvt_pk_bf16_f32 v3, -v47, s0
	global_store_short v[4:5], v3, off offset:240
	v_add_u32_e32 v4, 0x1000, v32
	v_mov_b32_e32 v5, v2
	v_cvt_pk_bf16_f32 v3, -v42, s0
	v_lshl_add_u64 v[38:39], v[28:29], 0, v[4:5]
	v_ashrrev_i32_e32 v5, 31, v4
	global_store_short v[38:39], v3, off
	v_cvt_pk_bf16_f32 v3, -v43, s0
	v_lshl_add_u64 v[4:5], v[28:29], 0, v[4:5]
	global_store_short v[4:5], v3, off offset:16
	v_cvt_pk_bf16_f32 v3, -v40, s0
	global_store_short v[4:5], v3, off offset:32
	v_cvt_pk_bf16_f32 v3, -v41, s0
	global_store_short v[4:5], v3, off offset:48
	v_cvt_pk_bf16_f32 v3, -v36, s0
	global_store_short v[4:5], v3, off offset:64
	v_cvt_pk_bf16_f32 v3, -v37, s0
	global_store_short v[4:5], v3, off offset:80
	v_cvt_pk_bf16_f32 v3, -v34, s0
	global_store_short v[4:5], v3, off offset:96
	v_cvt_pk_bf16_f32 v3, -v35, s0
	global_store_short v[4:5], v3, off offset:112
	v_cvt_pk_bf16_f32 v3, -v30, s0
	global_store_short v[4:5], v3, off offset:128
	v_cvt_pk_bf16_f32 v3, -v31, s0
	global_store_short v[4:5], v3, off offset:144
	v_cvt_pk_bf16_f32 v3, -v26, s0
	global_store_short v[4:5], v3, off offset:160
	v_cvt_pk_bf16_f32 v3, -v27, s0
	global_store_short v[4:5], v3, off offset:176
	v_cvt_pk_bf16_f32 v3, -v24, s0
	global_store_short v[4:5], v3, off offset:192
	v_cvt_pk_bf16_f32 v3, -v25, s0
	global_store_short v[4:5], v3, off offset:208
	v_cvt_pk_bf16_f32 v3, -v20, s0
	global_store_short v[4:5], v3, off offset:224
	v_cvt_pk_bf16_f32 v3, -v21, s0
	global_store_short v[4:5], v3, off offset:240
	v_add_u32_e32 v4, 0x2000, v32
	v_mov_b32_e32 v5, v2
	v_cvt_pk_bf16_f32 v3, -v18, s0
	v_lshl_add_u64 v[20:21], v[28:29], 0, v[4:5]
	v_ashrrev_i32_e32 v5, 31, v4
	global_store_short v[20:21], v3, off
	v_cvt_pk_bf16_f32 v3, -v19, s0
	v_lshl_add_u64 v[4:5], v[28:29], 0, v[4:5]
	global_store_short v[4:5], v3, off offset:16
	v_cvt_pk_bf16_f32 v3, -v14, s0
	global_store_short v[4:5], v3, off offset:32
	v_cvt_pk_bf16_f32 v3, -v15, s0
	global_store_short v[4:5], v3, off offset:48
	v_cvt_pk_bf16_f32 v3, -v10, s0
	global_store_short v[4:5], v3, off offset:64
	v_cvt_pk_bf16_f32 v3, -v11, s0
	global_store_short v[4:5], v3, off offset:80
	v_cvt_pk_bf16_f32 v3, -v8, s0
	global_store_short v[4:5], v3, off offset:96
	v_cvt_pk_bf16_f32 v3, -v9, s0
	global_store_short v[4:5], v3, off offset:112
	v_cvt_pk_bf16_f32 v3, -v6, s0
	global_store_short v[4:5], v3, off offset:128
	v_cvt_pk_bf16_f32 v3, -v7, s0
	global_store_short v[4:5], v3, off offset:144
	v_cvt_pk_bf16_f32 v3, -v16, s0
	global_store_short v[4:5], v3, off offset:160
	v_cvt_pk_bf16_f32 v3, -v17, s0
	global_store_short v[4:5], v3, off offset:176
	v_cvt_pk_bf16_f32 v3, -v12, s0
	global_store_short v[4:5], v3, off offset:192
	v_cvt_pk_bf16_f32 v3, -v13, s0
	global_store_short v[4:5], v3, off offset:208
	v_cvt_pk_bf16_f32 v3, -v22, s0
	global_store_short v[4:5], v3, off offset:224
	v_cvt_pk_bf16_f32 v3, -v23, s0
	global_store_short v[4:5], v3, off offset:240

; __global__ void __launch_bounds__(512, 2) fwd_kernel(Args args_unused) {
	.amdhsa_kernel _Z10fwd_kernel4Args
		.amdhsa_group_segment_fixed_size 0
		.amdhsa_private_segment_fixed_size 0
		.amdhsa_kernarg_size 520
		.amdhsa_user_sgpr_count 2
		.amdhsa_user_sgpr_dispatch_ptr 0
		.amdhsa_user_sgpr_queue_ptr 0
		.amdhsa_user_sgpr_kernarg_segment_ptr 1
		.amdhsa_user_sgpr_dispatch_id 0
		.amdhsa_user_sgpr_kernarg_preload_length 0
		.amdhsa_user_sgpr_kernarg_preload_offset 0
		.amdhsa_user_sgpr_private_segment_size 0
		.amdhsa_uses_dynamic_stack 0
		.amdhsa_enable_private_segment 0
		.amdhsa_system_sgpr_workgroup_id_x 1
		.amdhsa_system_sgpr_workgroup_id_y 0
		.amdhsa_system_sgpr_workgroup_id_z 0
		.amdhsa_system_sgpr_workgroup_info 0
		.amdhsa_system_vgpr_workitem_id 0
		.amdhsa_next_free_vgpr 256
		.amdhsa_next_free_sgpr 102
		.amdhsa_accum_offset 256
		.amdhsa_reserve_vcc 1
		.amdhsa_float_round_mode_32 0
		.amdhsa_float_round_mode_16_64 0
		.amdhsa_float_denorm_mode_32 3
		.amdhsa_float_denorm_mode_16_64 3
		.amdhsa_dx10_clamp 1
		.amdhsa_ieee_mode 1
		.amdhsa_fp16_overflow 0
		.amdhsa_tg_split 0
		.amdhsa_exception_fp_ieee_invalid_op 0
		.amdhsa_exception_fp_denorm_src 0
		.amdhsa_exception_fp_ieee_div_zero 0
		.amdhsa_exception_fp_ieee_overflow 0
		.amdhsa_exception_fp_ieee_underflow 0
		.amdhsa_exception_fp_ieee_inexact 0
		.amdhsa_exception_int_div_zero 0
	.end_amdhsa_kernel

; __global__ void __launch_bounds__(512, 2) fwd_kernel(Args args_unused) {
amdhsa.kernels:
  - .agpr_count:     0
    .args:
      - .offset:         0
        .size:           264
        .value_kind:     by_value
      - .offset:         264
        .size:           4
        .value_kind:     hidden_block_count_x
      - .offset:         268
        .size:           4
        .value_kind:     hidden_block_count_y
      - .offset:         272
        .size:           4
        .value_kind:     hidden_block_count_z
      - .offset:         276
        .size:           2
        .value_kind:     hidden_group_size_x
      - .offset:         278
        .size:           2
        .value_kind:     hidden_group_size_y
      - .offset:         280
        .size:           2
        .value_kind:     hidden_group_size_z
      - .offset:         282
        .size:           2
        .value_kind:     hidden_remainder_x
      - .offset:         284
        .size:           2
        .value_kind:     hidden_remainder_y
      - .offset:         286
        .size:           2
        .value_kind:     hidden_remainder_z
      - .offset:         304
        .size:           8
        .value_kind:     hidden_global_offset_x
      - .offset:         312
        .size:           8
        .value_kind:     hidden_global_offset_y
      - .offset:         320
        .size:           8
        .value_kind:     hidden_global_offset_z
      - .offset:         328
        .size:           2
        .value_kind:     hidden_grid_dims
      - .offset:         384
        .size:           4
        .value_kind:     hidden_dynamic_lds_size
    .group_segment_fixed_size: 0
    .kernarg_segment_align: 8
    .kernarg_segment_size: 520
    .language:       OpenCL C
    .language_version:
      - 2
      - 0
    .max_flat_workgroup_size: 512
    .name:           _Z10fwd_kernel4Args
    .private_segment_fixed_size: 0
    .sgpr_count:     108
    .sgpr_spill_count: 173
    .symbol:         _Z10fwd_kernel4Args.kd
    .uniform_work_group_size: 1
    .uses_dynamic_stack: false
    .vgpr_count:     256
    .vgpr_spill_count: 0
    .wavefront_size: 64
